# move s_setprio 1 ahead of the pre-MFMA barrier and drop the redundant post-barrier lgkmcnt(0) in all 32 MFMA segment heads
# baseline (speedup 1.0000x reference)
; #define PG8_STAGE(bufoff, gbase, VO) do { _Pragma("unroll") for (int _i = 0; _i < 2; ++_i) \
;         __builtin_amdgcn_global_load_lds((const unsigned*)((const char*)(gbase) + VO[_i]), (LAS unsigned*)(lds + (bufoff) + ldsw + _i * 8192), 16, 0, 0); } while (0)
; #define PG8_LDA(dst, b, h) do { _Pragma("unroll") for (int m = 0; m < 4; ++m) _Pragma("unroll") for (int k = 0; k < 2; ++k) dst[m][k] = *(const LAS bf16x8*)(lds + PG8_SA(b, h) + aoff + m * 2048 + k * 1024); } while (0)
; #define PG8_LDB(dst, b, h) do { _Pragma("unroll") for (int n = 0; n < 2; ++n) _Pragma("unroll") for (int k = 0; k < 2; ++k) dst[n][k] = *(const LAS bf16x8*)(lds + PG8_SB(b, h) + boff + n * 2048 + k * 1024); } while (0)
; #define PG8_MMA(ai, bj, At, Bt) do { __builtin_amdgcn_s_setprio(1); _Pragma("unroll") for (int m = 0; m < 4; ++m) _Pragma("unroll") for (int n = 0; n < 2; ++n) _Pragma("unroll") for (int k = 0; k < 2; ++k) \
;         acc[ai][bj][m][n] = __builtin_amdgcn_mfma_f32_16x16x32_bf16(Bt[n][k], At[m][k], acc[ai][bj][m][n], 0, 0, 0); __builtin_amdgcn_s_setprio(0); } while (0)
; #define PG8_WAIT_V(n) asm volatile("s_waitcnt vmcnt(" #n ")" ::: "memory")
; #define PG8_WAIT_L(n) asm volatile("s_waitcnt lgkmcnt(" #n ")" ::: "memory")
; template <int NSEG, class Epi, bool ALIGN_EPI = PG8_ALIGN, bool SP2 = PG8_SP2>
; DI void gemm_phase(LAS unsigned char* lds, const Gemm g, const StaticOrder& S, const Epi& E) {
;     ...
;         for (int t = 0; t < nt; t += 2) {
;             const bool last = (t == nt - 2);
;             const char* a1 = cA + (size_t)(t + 1) * kstep;
;             const char* a2 = last ? nA : cA + (size_t)(t + 2) * kstep; const char* b2 = last ? nB : cB + (size_t)(t + 2) * kstep;
;             const char* a3 = a2 + kstep; const char* b3 = b2 + kstep;
;             unsigned v2[2]; v2[0] = (NSEG > 1 && last) ? voffN[0] : voffC[0]; v2[1] = (NSEG > 1 && last) ? voffN[1] : voffC[1];
;             const size_t h2 = (NSEG > 1 && last) ? hstepN : hstepC;
;             if constexpr (SP2) {
;             PG8_LDB(B0, 0, 0); PG8_LDB(B1, 0, 1); PG8_SCHED; PG8_LDA(At, 0, 0); PG8_STAGE(PG8_SA(1, 1), a1 + hstepC, voffC);
;             PG8_WAIT_V(8); PG8_WAIT_L(0); PG8_BAR; PG8_MMA(0, 0, At, B0); PG8_MMA(0, 1, At, B1); PG8_BAR; PG8_SCHED;
;             PG8_LDA(At, 0, 1); PG8_STAGE(PG8_SB(0, 0), b2, v2); PG8_STAGE(PG8_SB(0, 1), b2 + h2, v2); PG8_STAGE(PG8_SA(0, 0), a2, v2);
.LBB0_139:
	v_add_u32_e32 v134, s62, v157
	ds_read_b128 v[144:147], v178
	ds_read_b128 v[148:151], v178 offset:1024
	ds_read_b128 v[152:155], v178 offset:2048
	ds_read_b128 v[182:185], v178 offset:3072
	ds_read_b128 v[186:189], v134
	ds_read_b128 v[190:193], v134 offset:1024
	ds_read_b128 v[194:197], v134 offset:2048
	ds_read_b128 v[198:201], v134 offset:3072
	s_add_u32 s36, s34, 0xfff80080
	s_addc_u32 s37, s35, -1
	s_cmp_eq_u32 s72, 28
	s_cselect_b32 s41, s3, s37
	s_cselect_b32 s40, s25, s36
	s_cselect_b32 s37, s27, s71
	s_cselect_b32 s36, s69, s70
	v_lshl_add_u64 v[234:235], s[34:35], 0, v[136:137]
	s_add_i32 m0, s45, 0xc000
	ds_read_b128 v[202:205], v179
	ds_read_b128 v[206:209], v179 offset:1024
	ds_read_b128 v[210:213], v179 offset:2048
	ds_read_b128 v[214:217], v179 offset:3072
	ds_read_b128 v[218:221], v179 offset:4096
	ds_read_b128 v[222:225], v179 offset:5120
	ds_read_b128 v[226:229], v179 offset:6144
	ds_read_b128 v[230:233], v179 offset:7168
	global_load_lds_dwordx4 v[234:235], off
	v_lshl_add_u64 v[234:235], s[34:35], 0, v[138:139]
	s_add_i32 m0, s45, 0xe000
	s_nop 0
	global_load_lds_dwordx4 v[234:235], off
	s_waitcnt vmcnt(8)
	s_waitcnt lgkmcnt(0)
	s_setprio 1
	s_barrier
	v_mfma_f32_16x16x32_bf16 v[126:129], v[144:147], v[202:205], v[126:129]
	v_mfma_f32_16x16x32_bf16 v[122:125], v[152:155], v[202:205], v[122:125]
	v_mfma_f32_16x16x32_bf16 v[110:113], v[144:147], v[210:213], v[110:113]
	v_mfma_f32_16x16x32_bf16 v[106:109], v[152:155], v[210:213], v[106:109]
	v_mfma_f32_16x16x32_bf16 v[94:97], v[144:147], v[218:221], v[94:97]
	v_mfma_f32_16x16x32_bf16 v[90:93], v[152:155], v[218:221], v[90:93]
	v_mfma_f32_16x16x32_bf16 v[78:81], v[144:147], v[226:229], v[78:81]
	v_mfma_f32_16x16x32_bf16 v[74:77], v[152:155], v[226:229], v[74:77]
	v_mfma_f32_16x16x32_bf16 v[126:129], v[148:151], v[206:209], v[126:129]
	v_mfma_f32_16x16x32_bf16 v[122:125], v[182:185], v[206:209], v[122:125]
	v_mfma_f32_16x16x32_bf16 v[110:113], v[148:151], v[214:217], v[110:113]
	v_mfma_f32_16x16x32_bf16 v[106:109], v[182:185], v[214:217], v[106:109]
	v_mfma_f32_16x16x32_bf16 v[94:97], v[148:151], v[222:225], v[94:97]
	v_mfma_f32_16x16x32_bf16 v[90:93], v[182:185], v[222:225], v[90:93]
	v_mfma_f32_16x16x32_bf16 v[78:81], v[148:151], v[230:233], v[78:81]
	v_mfma_f32_16x16x32_bf16 v[74:77], v[182:185], v[230:233], v[74:77]
	s_setprio 0
	s_setprio 1
	v_mfma_f32_16x16x32_bf16 v[118:121], v[186:189], v[202:205], v[118:121]
	v_mfma_f32_16x16x32_bf16 v[114:117], v[194:197], v[202:205], v[114:117]
	v_mfma_f32_16x16x32_bf16 v[102:105], v[186:189], v[210:213], v[102:105]
	v_mfma_f32_16x16x32_bf16 v[98:101], v[194:197], v[210:213], v[98:101]
	v_mfma_f32_16x16x32_bf16 v[86:89], v[186:189], v[218:221], v[86:89]
	v_mfma_f32_16x16x32_bf16 v[82:85], v[194:197], v[218:221], v[82:85]
	v_mfma_f32_16x16x32_bf16 v[70:73], v[186:189], v[226:229], v[70:73]
	v_mfma_f32_16x16x32_bf16 v[66:69], v[194:197], v[226:229], v[66:69]
	v_mfma_f32_16x16x32_bf16 v[118:121], v[190:193], v[206:209], v[118:121]
	v_mfma_f32_16x16x32_bf16 v[114:117], v[198:201], v[206:209], v[114:117]
	v_mfma_f32_16x16x32_bf16 v[102:105], v[190:193], v[214:217], v[102:105]
	v_mfma_f32_16x16x32_bf16 v[98:101], v[198:201], v[214:217], v[98:101]
	v_mfma_f32_16x16x32_bf16 v[86:89], v[190:193], v[222:225], v[86:89]
	v_mfma_f32_16x16x32_bf16 v[82:85], v[198:201], v[222:225], v[82:85]
	v_mfma_f32_16x16x32_bf16 v[70:73], v[190:193], v[230:233], v[70:73]
	v_mfma_f32_16x16x32_bf16 v[66:69], v[198:201], v[230:233], v[66:69]
	s_setprio 0
	s_barrier
	s_add_i32 s73, s61, s51
	v_lshl_add_u64 v[234:235], s[36:37], 0, v[130:131]
	s_mov_b32 m0, s73
	ds_read_b128 v[202:205], v179 offset:16384
	ds_read_b128 v[206:209], v179 offset:17408
	ds_read_b128 v[210:213], v179 offset:18432
	ds_read_b128 v[214:217], v179 offset:19456
	ds_read_b128 v[218:221], v179 offset:20480
	ds_read_b128 v[222:225], v179 offset:21504
	ds_read_b128 v[226:229], v179 offset:22528
	ds_read_b128 v[230:233], v179 offset:23552
	global_load_lds_dwordx4 v[234:235], off
	s_add_i32 m0, s73, 0x2000
	s_add_u32 s74, s36, 0x80000
	v_lshl_add_u64 v[236:237], s[36:37], 0, v[132:133]
	s_addc_u32 s75, s37, 0
	s_add_i32 s73, s62, s51
	global_load_lds_dwordx4 v[236:237], off
	v_lshl_add_u64 v[238:239], s[74:75], 0, v[130:131]
	s_mov_b32 m0, s73
	v_lshl_add_u64 v[240:241], s[40:41], 0, v[132:133]
	global_load_lds_dwordx4 v[238:239], off
	v_lshl_add_u64 v[238:239], s[74:75], 0, v[132:133]
	s_add_i32 m0, s73, 0x2000
	s_nop 0
	global_load_lds_dwordx4 v[238:239], off
	v_lshl_add_u64 v[238:239], s[40:41], 0, v[130:131]
	s_mov_b32 m0, s45
	s_nop 0
	global_load_lds_dwordx4 v[238:239], off
	s_mov_b32 m0, s54
	s_nop 0
	global_load_lds_dwordx4 v[240:241], off
	s_waitcnt vmcnt(8)
	s_waitcnt lgkmcnt(0)
	s_setprio 1
	s_barrier
; #define PG8_STAGE(bufoff, gbase, VO) do { _Pragma("unroll") for (int _i = 0; _i < 2; ++_i) \
;         __builtin_amdgcn_global_load_lds((const unsigned*)((const char*)(gbase) + VO[_i]), (LAS unsigned*)(lds + (bufoff) + ldsw + _i * 8192), 16, 0, 0); } while (0)
; #define PG8_LDA(dst, b, h) do { _Pragma("unroll") for (int m = 0; m < 4; ++m) _Pragma("unroll") for (int k = 0; k < 2; ++k) dst[m][k] = *(const LAS bf16x8*)(lds + PG8_SA(b, h) + aoff + m * 2048 + k * 1024); } while (0)
; #define PG8_LDB(dst, b, h) do { _Pragma("unroll") for (int n = 0; n < 2; ++n) _Pragma("unroll") for (int k = 0; k < 2; ++k) dst[n][k] = *(const LAS bf16x8*)(lds + PG8_SB(b, h) + boff + n * 2048 + k * 1024); } while (0)
; #define PG8_MMA(ai, bj, At, Bt) do { __builtin_amdgcn_s_setprio(1); _Pragma("unroll") for (int m = 0; m < 4; ++m) _Pragma("unroll") for (int n = 0; n < 2; ++n) _Pragma("unroll") for (int k = 0; k < 2; ++k) \
;         acc[ai][bj][m][n] = __builtin_amdgcn_mfma_f32_16x16x32_bf16(Bt[n][k], At[m][k], acc[ai][bj][m][n], 0, 0, 0); __builtin_amdgcn_s_setprio(0); } while (0)
; #define PG8_WAIT_V(n) asm volatile("s_waitcnt vmcnt(" #n ")" ::: "memory")
; #define PG8_WAIT_L(n) asm volatile("s_waitcnt lgkmcnt(" #n ")" ::: "memory")
; #define PG8_BAR __builtin_amdgcn_s_barrier()
; #define PG8_SCHED __builtin_amdgcn_sched_barrier(0)
; template <int NSEG, class Epi, bool ALIGN_EPI = PG8_ALIGN, bool SP2 = PG8_SP2>
; DI void gemm_phase(LAS unsigned char* lds, const Gemm g, const StaticOrder& S, const Epi& E) {
;     ...
;             PG8_LDA(At, 0, 1); PG8_STAGE(PG8_SB(0, 0), b2, v2); PG8_STAGE(PG8_SB(0, 1), b2 + h2, v2); PG8_STAGE(PG8_SA(0, 0), a2, v2);
;             PG8_WAIT_V(8); PG8_WAIT_L(0); PG8_BAR; PG8_MMA(1, 0, At, B0); PG8_MMA(1, 1, At, B1); PG8_BAR; PG8_SCHED;
;             PG8_LDB(B0, 1, 0); PG8_LDB(B1, 1, 1); PG8_SCHED; PG8_LDA(At, 1, 0); PG8_STAGE(PG8_SA(0, 1), a2 + h2, v2);
;             PG8_WAIT_V(8); PG8_WAIT_L(0); PG8_BAR; PG8_MMA(0, 0, At, B0); PG8_MMA(0, 1, At, B1); PG8_BAR; PG8_SCHED;
	v_mfma_f32_16x16x32_bf16 v[62:65], v[144:147], v[202:205], v[62:65]
	v_mfma_f32_16x16x32_bf16 v[58:61], v[152:155], v[202:205], v[58:61]
	v_mfma_f32_16x16x32_bf16 v[46:49], v[144:147], v[210:213], v[46:49]
	v_mfma_f32_16x16x32_bf16 v[42:45], v[152:155], v[210:213], v[42:45]
	v_mfma_f32_16x16x32_bf16 v[22:25], v[144:147], v[218:221], v[22:25]
	v_mfma_f32_16x16x32_bf16 v[18:21], v[152:155], v[218:221], v[18:21]
	v_mfma_f32_16x16x32_bf16 v[6:9], v[144:147], v[226:229], v[6:9]
	v_mfma_f32_16x16x32_bf16 v[2:5], v[152:155], v[226:229], v[2:5]
	v_mfma_f32_16x16x32_bf16 v[62:65], v[148:151], v[206:209], v[62:65]
	v_mfma_f32_16x16x32_bf16 v[58:61], v[182:185], v[206:209], v[58:61]
	v_mfma_f32_16x16x32_bf16 v[46:49], v[148:151], v[214:217], v[46:49]
	v_mfma_f32_16x16x32_bf16 v[42:45], v[182:185], v[214:217], v[42:45]
	v_mfma_f32_16x16x32_bf16 v[22:25], v[148:151], v[222:225], v[22:25]
	v_mfma_f32_16x16x32_bf16 v[18:21], v[182:185], v[222:225], v[18:21]
	v_mfma_f32_16x16x32_bf16 v[6:9], v[148:151], v[230:233], v[6:9]
	v_mfma_f32_16x16x32_bf16 v[2:5], v[182:185], v[230:233], v[2:5]
	s_setprio 0
	s_setprio 1
	v_mfma_f32_16x16x32_bf16 v[54:57], v[186:189], v[202:205], v[54:57]
	v_mfma_f32_16x16x32_bf16 v[50:53], v[194:197], v[202:205], v[50:53]
	v_mfma_f32_16x16x32_bf16 v[38:41], v[186:189], v[210:213], v[38:41]
	v_mfma_f32_16x16x32_bf16 v[26:29], v[194:197], v[210:213], v[26:29]
	v_mfma_f32_16x16x32_bf16 v[34:37], v[186:189], v[218:221], v[34:37]
	v_mfma_f32_16x16x32_bf16 v[30:33], v[194:197], v[218:221], v[30:33]
	v_mfma_f32_16x16x32_bf16 v[14:17], v[186:189], v[226:229], v[14:17]
	v_mfma_f32_16x16x32_bf16 v[10:13], v[194:197], v[226:229], v[10:13]
	v_mfma_f32_16x16x32_bf16 v[54:57], v[190:193], v[206:209], v[54:57]
	v_mfma_f32_16x16x32_bf16 v[50:53], v[198:201], v[206:209], v[50:53]
	v_mfma_f32_16x16x32_bf16 v[38:41], v[190:193], v[214:217], v[38:41]
	v_mfma_f32_16x16x32_bf16 v[26:29], v[198:201], v[214:217], v[26:29]
	v_mfma_f32_16x16x32_bf16 v[34:37], v[190:193], v[222:225], v[34:37]
	v_mfma_f32_16x16x32_bf16 v[30:33], v[198:201], v[222:225], v[30:33]
	v_mfma_f32_16x16x32_bf16 v[14:17], v[190:193], v[230:233], v[14:17]
	v_mfma_f32_16x16x32_bf16 v[10:13], v[198:201], v[230:233], v[10:13]
	s_setprio 0
	s_barrier
	s_add_i32 s73, 0, 0x18000
	v_add_u32_e32 v134, s73, v157
	s_add_i32 s74, 0, 0x1c000
	ds_read_b128 v[144:147], v134
	ds_read_b128 v[148:151], v134 offset:1024
	ds_read_b128 v[152:155], v134 offset:2048
	ds_read_b128 v[182:185], v134 offset:3072
	v_add_u32_e32 v134, s74, v157
	ds_read_b128 v[186:189], v134
	ds_read_b128 v[190:193], v134 offset:1024
	ds_read_b128 v[194:197], v134 offset:2048
	ds_read_b128 v[198:201], v134 offset:3072
	s_add_u32 s40, s40, 0x80000
	s_addc_u32 s41, s41, 0
	s_mov_b32 m0, s55
	v_lshl_add_u64 v[242:243], s[40:41], 0, v[130:131]
	ds_read_b128 v[202:205], v179 offset:32768
	ds_read_b128 v[206:209], v179 offset:33792
	ds_read_b128 v[210:213], v179 offset:34816
	ds_read_b128 v[214:217], v179 offset:35840
	ds_read_b128 v[218:221], v179 offset:36864
	ds_read_b128 v[222:225], v179 offset:37888
	ds_read_b128 v[226:229], v179 offset:38912
	ds_read_b128 v[230:233], v179 offset:39936
	global_load_lds_dwordx4 v[242:243], off
	v_lshl_add_u64 v[242:243], s[40:41], 0, v[132:133]
	s_mov_b32 m0, s56
	s_nop 0
	global_load_lds_dwordx4 v[242:243], off
	s_waitcnt vmcnt(8)
	s_waitcnt lgkmcnt(0)
	s_setprio 1
	s_barrier
	v_mfma_f32_16x16x32_bf16 v[126:129], v[144:147], v[202:205], v[126:129]
	v_mfma_f32_16x16x32_bf16 v[122:125], v[152:155], v[202:205], v[122:125]
	v_mfma_f32_16x16x32_bf16 v[110:113], v[144:147], v[210:213], v[110:113]
	v_mfma_f32_16x16x32_bf16 v[106:109], v[152:155], v[210:213], v[106:109]
	v_mfma_f32_16x16x32_bf16 v[94:97], v[144:147], v[218:221], v[94:97]
	v_mfma_f32_16x16x32_bf16 v[90:93], v[152:155], v[218:221], v[90:93]
	v_mfma_f32_16x16x32_bf16 v[78:81], v[144:147], v[226:229], v[78:81]
	v_mfma_f32_16x16x32_bf16 v[74:77], v[152:155], v[226:229], v[74:77]
	v_mfma_f32_16x16x32_bf16 v[126:129], v[148:151], v[206:209], v[126:129]
	v_mfma_f32_16x16x32_bf16 v[122:125], v[182:185], v[206:209], v[122:125]
	v_mfma_f32_16x16x32_bf16 v[110:113], v[148:151], v[214:217], v[110:113]
	v_mfma_f32_16x16x32_bf16 v[106:109], v[182:185], v[214:217], v[106:109]
	v_mfma_f32_16x16x32_bf16 v[94:97], v[148:151], v[222:225], v[94:97]
	v_mfma_f32_16x16x32_bf16 v[90:93], v[182:185], v[222:225], v[90:93]
	v_mfma_f32_16x16x32_bf16 v[78:81], v[148:151], v[230:233], v[78:81]
	v_mfma_f32_16x16x32_bf16 v[74:77], v[182:185], v[230:233], v[74:77]
	s_setprio 0
	s_setprio 1
	v_mfma_f32_16x16x32_bf16 v[118:121], v[186:189], v[202:205], v[118:121]
	v_mfma_f32_16x16x32_bf16 v[114:117], v[194:197], v[202:205], v[114:117]
	v_mfma_f32_16x16x32_bf16 v[102:105], v[186:189], v[210:213], v[102:105]
	v_mfma_f32_16x16x32_bf16 v[98:101], v[194:197], v[210:213], v[98:101]
	v_mfma_f32_16x16x32_bf16 v[86:89], v[186:189], v[218:221], v[86:89]
	v_mfma_f32_16x16x32_bf16 v[82:85], v[194:197], v[218:221], v[82:85]
	v_mfma_f32_16x16x32_bf16 v[70:73], v[186:189], v[226:229], v[70:73]
	v_mfma_f32_16x16x32_bf16 v[66:69], v[194:197], v[226:229], v[66:69]
	v_mfma_f32_16x16x32_bf16 v[118:121], v[190:193], v[206:209], v[118:121]
	v_mfma_f32_16x16x32_bf16 v[114:117], v[198:201], v[206:209], v[114:117]
	v_mfma_f32_16x16x32_bf16 v[102:105], v[190:193], v[214:217], v[102:105]
	v_mfma_f32_16x16x32_bf16 v[98:101], v[198:201], v[214:217], v[98:101]
	v_mfma_f32_16x16x32_bf16 v[86:89], v[190:193], v[222:225], v[86:89]
	v_mfma_f32_16x16x32_bf16 v[82:85], v[198:201], v[222:225], v[82:85]
	v_mfma_f32_16x16x32_bf16 v[70:73], v[190:193], v[230:233], v[70:73]
	v_mfma_f32_16x16x32_bf16 v[66:69], v[198:201], v[230:233], v[66:69]
	s_setprio 0
	s_barrier
; #define PG8_STAGE(bufoff, gbase, VO) do { _Pragma("unroll") for (int _i = 0; _i < 2; ++_i) \
;         __builtin_amdgcn_global_load_lds((const unsigned*)((const char*)(gbase) + VO[_i]), (LAS unsigned*)(lds + (bufoff) + ldsw + _i * 8192), 16, 0, 0); } while (0)
; #define PG8_LDA(dst, b, h) do { _Pragma("unroll") for (int m = 0; m < 4; ++m) _Pragma("unroll") for (int k = 0; k < 2; ++k) dst[m][k] = *(const LAS bf16x8*)(lds + PG8_SA(b, h) + aoff + m * 2048 + k * 1024); } while (0)
; #define PG8_MMA(ai, bj, At, Bt) do { __builtin_amdgcn_s_setprio(1); _Pragma("unroll") for (int m = 0; m < 4; ++m) _Pragma("unroll") for (int n = 0; n < 2; ++n) _Pragma("unroll") for (int k = 0; k < 2; ++k) \
;         acc[ai][bj][m][n] = __builtin_amdgcn_mfma_f32_16x16x32_bf16(Bt[n][k], At[m][k], acc[ai][bj][m][n], 0, 0, 0); __builtin_amdgcn_s_setprio(0); } while (0)
; #define PG8_WAIT_V(n) asm volatile("s_waitcnt vmcnt(" #n ")" ::: "memory")
; #define PG8_WAIT_L(n) asm volatile("s_waitcnt lgkmcnt(" #n ")" ::: "memory")
; #define PG8_BAR __builtin_amdgcn_s_barrier()
; #define PG8_SCHED __builtin_amdgcn_sched_barrier(0)
; template <int NSEG, class Epi, bool ALIGN_EPI = PG8_ALIGN, bool SP2 = PG8_SP2>
; DI void gemm_phase(LAS unsigned char* lds, const Gemm g, const StaticOrder& S, const Epi& E) {
;     ...
;             PG8_LDA(At, 1, 1); PG8_STAGE(PG8_SB(1, 0), b3, v2); PG8_STAGE(PG8_SB(1, 1), b3 + h2, v2); PG8_STAGE(PG8_SA(1, 0), a3, v2);
;             PG8_WAIT_V(8); PG8_WAIT_L(0); PG8_BAR; PG8_MMA(1, 0, At, B0); PG8_MMA(1, 1, At, B1); PG8_BAR; PG8_SCHED;
	s_add_i32 s40, s73, s51
	v_lshl_add_u64 v[234:235], v[234:235], 0, s[12:13]
	s_mov_b32 m0, s40
	ds_read_b128 v[202:205], v179 offset:49152
	ds_read_b128 v[206:209], v179 offset:50176
	ds_read_b128 v[210:213], v179 offset:51200
	ds_read_b128 v[214:217], v179 offset:52224
	ds_read_b128 v[218:221], v179 offset:53248
	ds_read_b128 v[222:225], v179 offset:54272
	ds_read_b128 v[226:229], v179 offset:55296
	ds_read_b128 v[230:233], v179 offset:56320
	global_load_lds_dwordx4 v[234:235], off
	s_add_i32 m0, s40, 0x2000
	s_add_u32 s36, s36, 0x80080
	v_lshl_add_u64 v[234:235], v[236:237], 0, s[12:13]
	s_addc_u32 s37, s37, 0
	s_add_i32 s40, s74, s51
	global_load_lds_dwordx4 v[234:235], off
	v_lshl_add_u64 v[234:235], s[36:37], 0, v[130:131]
	s_mov_b32 m0, s40
	s_nop 0
	global_load_lds_dwordx4 v[234:235], off
	v_lshl_add_u64 v[234:235], s[36:37], 0, v[132:133]
	s_add_i32 m0, s40, 0x2000
	s_nop 0
	global_load_lds_dwordx4 v[234:235], off
	v_lshl_add_u64 v[234:235], v[238:239], 0, s[12:13]
	s_mov_b32 m0, s57
	s_nop 0
	global_load_lds_dwordx4 v[234:235], off
	v_lshl_add_u64 v[234:235], v[240:241], 0, s[12:13]
	s_mov_b32 m0, s58
	s_nop 0
	global_load_lds_dwordx4 v[234:235], off
	s_waitcnt vmcnt(8)
	s_waitcnt lgkmcnt(0)
	s_setprio 1
	s_barrier
	v_mfma_f32_16x16x32_bf16 v[62:65], v[144:147], v[202:205], v[62:65]
	v_mfma_f32_16x16x32_bf16 v[58:61], v[152:155], v[202:205], v[58:61]
	v_mfma_f32_16x16x32_bf16 v[46:49], v[144:147], v[210:213], v[46:49]
	v_mfma_f32_16x16x32_bf16 v[42:45], v[152:155], v[210:213], v[42:45]
	v_mfma_f32_16x16x32_bf16 v[22:25], v[144:147], v[218:221], v[22:25]
	v_mfma_f32_16x16x32_bf16 v[18:21], v[152:155], v[218:221], v[18:21]
	v_mfma_f32_16x16x32_bf16 v[6:9], v[144:147], v[226:229], v[6:9]
	v_mfma_f32_16x16x32_bf16 v[2:5], v[152:155], v[226:229], v[2:5]
	v_mfma_f32_16x16x32_bf16 v[62:65], v[148:151], v[206:209], v[62:65]
	v_mfma_f32_16x16x32_bf16 v[58:61], v[182:185], v[206:209], v[58:61]
	v_mfma_f32_16x16x32_bf16 v[46:49], v[148:151], v[214:217], v[46:49]
	v_mfma_f32_16x16x32_bf16 v[42:45], v[182:185], v[214:217], v[42:45]
	v_mfma_f32_16x16x32_bf16 v[22:25], v[148:151], v[222:225], v[22:25]
	v_mfma_f32_16x16x32_bf16 v[18:21], v[182:185], v[222:225], v[18:21]
	v_mfma_f32_16x16x32_bf16 v[6:9], v[148:151], v[230:233], v[6:9]
	v_mfma_f32_16x16x32_bf16 v[2:5], v[182:185], v[230:233], v[2:5]
	s_setprio 0
	s_setprio 1
	v_mfma_f32_16x16x32_bf16 v[54:57], v[186:189], v[202:205], v[54:57]
	v_mfma_f32_16x16x32_bf16 v[50:53], v[194:197], v[202:205], v[50:53]
	v_mfma_f32_16x16x32_bf16 v[38:41], v[186:189], v[210:213], v[38:41]
	v_mfma_f32_16x16x32_bf16 v[26:29], v[194:197], v[210:213], v[26:29]
	v_mfma_f32_16x16x32_bf16 v[34:37], v[186:189], v[218:221], v[34:37]
	v_mfma_f32_16x16x32_bf16 v[30:33], v[194:197], v[218:221], v[30:33]
	v_mfma_f32_16x16x32_bf16 v[14:17], v[186:189], v[226:229], v[14:17]
	v_mfma_f32_16x16x32_bf16 v[10:13], v[194:197], v[226:229], v[10:13]
	v_mfma_f32_16x16x32_bf16 v[54:57], v[190:193], v[206:209], v[54:57]
	v_mfma_f32_16x16x32_bf16 v[50:53], v[198:201], v[206:209], v[50:53]
	v_mfma_f32_16x16x32_bf16 v[38:41], v[190:193], v[214:217], v[38:41]
	v_mfma_f32_16x16x32_bf16 v[26:29], v[198:201], v[214:217], v[26:29]
	v_mfma_f32_16x16x32_bf16 v[34:37], v[190:193], v[222:225], v[34:37]
	v_mfma_f32_16x16x32_bf16 v[30:33], v[198:201], v[222:225], v[30:33]
	v_mfma_f32_16x16x32_bf16 v[14:17], v[190:193], v[230:233], v[14:17]
	v_mfma_f32_16x16x32_bf16 v[10:13], v[198:201], v[230:233], v[10:13]
	s_setprio 0
	s_barrier
	s_add_i32 s72, s72, 2
	s_add_u32 s34, s34, 0x100
	s_addc_u32 s35, s35, 0
	s_add_u32 s70, s70, 0x100
	s_addc_u32 s71, s71, 0
	s_cmp_gt_u32 s72, 29
	s_cbranch_scc0 .LBB0_139
	s_and_b64 vcc, exec, s[14:15]
	s_cbranch_vccnz .LBB0_144
	v_lshl_add_u32 v144, s2, 8, v1
	s_cmp_gt_i32 s44, 15
	s_mov_b64 s[2:3], -1
	s_cbranch_scc1 .LBB0_145

; #define PG8_STAGE(bufoff, gbase, VO) do { _Pragma("unroll") for (int _i = 0; _i < 2; ++_i) \
;         __builtin_amdgcn_global_load_lds((const unsigned*)((const char*)(gbase) + VO[_i]), (LAS unsigned*)(lds + (bufoff) + ldsw + _i * 8192), 16, 0, 0); } while (0)
; #define PG8_LDA(dst, b, h) do { _Pragma("unroll") for (int m = 0; m < 4; ++m) _Pragma("unroll") for (int k = 0; k < 2; ++k) dst[m][k] = *(const LAS bf16x8*)(lds + PG8_SA(b, h) + aoff + m * 2048 + k * 1024); } while (0)
; #define PG8_LDB(dst, b, h) do { _Pragma("unroll") for (int n = 0; n < 2; ++n) _Pragma("unroll") for (int k = 0; k < 2; ++k) dst[n][k] = *(const LAS bf16x8*)(lds + PG8_SB(b, h) + boff + n * 2048 + k * 1024); } while (0)
; #define PG8_MMA(ai, bj, At, Bt) do { __builtin_amdgcn_s_setprio(1); _Pragma("unroll") for (int m = 0; m < 4; ++m) _Pragma("unroll") for (int n = 0; n < 2; ++n) _Pragma("unroll") for (int k = 0; k < 2; ++k) \
;         acc[ai][bj][m][n] = __builtin_amdgcn_mfma_f32_16x16x32_bf16(Bt[n][k], At[m][k], acc[ai][bj][m][n], 0, 0, 0); __builtin_amdgcn_s_setprio(0); } while (0)
; #define PG8_WAIT_V(n) asm volatile("s_waitcnt vmcnt(" #n ")" ::: "memory")
; #define PG8_WAIT_L(n) asm volatile("s_waitcnt lgkmcnt(" #n ")" ::: "memory")
; template <int NSEG, class Epi, bool ALIGN_EPI = PG8_ALIGN, bool SP2 = PG8_SP2>
; DI void gemm_phase(LAS unsigned char* lds, const Gemm g, const StaticOrder& S, const Epi& E) {
;     ...
;         for (int t = 0; t < nt; t += 2) {
;             const bool last = (t == nt - 2);
;             const char* a1 = cA + (size_t)(t + 1) * kstep;
;             const char* a2 = last ? nA : cA + (size_t)(t + 2) * kstep; const char* b2 = last ? nB : cB + (size_t)(t + 2) * kstep;
;             const char* a3 = a2 + kstep; const char* b3 = b2 + kstep;
;             unsigned v2[2]; v2[0] = (NSEG > 1 && last) ? voffN[0] : voffC[0]; v2[1] = (NSEG > 1 && last) ? voffN[1] : voffC[1];
;             const size_t h2 = (NSEG > 1 && last) ? hstepN : hstepC;
;             if constexpr (SP2) {
;             PG8_LDB(B0, 0, 0); PG8_LDB(B1, 0, 1); PG8_SCHED; PG8_LDA(At, 0, 0); PG8_STAGE(PG8_SA(1, 1), a1 + hstepC, voffC);
;             PG8_WAIT_V(8); PG8_WAIT_L(0); PG8_BAR; PG8_MMA(0, 0, At, B0); PG8_MMA(0, 1, At, B1); PG8_BAR; PG8_SCHED;
;             PG8_LDA(At, 0, 1); PG8_STAGE(PG8_SB(0, 0), b2, v2); PG8_STAGE(PG8_SB(0, 1), b2 + h2, v2); PG8_STAGE(PG8_SA(0, 0), a2, v2);
.LBB0_281:
	ds_read_b128 v[42:45], v250
	ds_read_b128 v[46:49], v250 offset:1024
	ds_read_b128 v[58:61], v250 offset:2048
	ds_read_b128 v[62:65], v250 offset:3072
	ds_read_b128 v[122:125], v251
	ds_read_b128 v[134:137], v251 offset:1024
	ds_read_b128 v[146:149], v251 offset:2048
	ds_read_b128 v[150:153], v251 offset:3072
	s_add_u32 s24, s22, 0xfff80080
	s_addc_u32 s25, s23, -1
	s_cmp_eq_u32 s56, 28
	s_cselect_b32 s27, s15, s25
	s_cselect_b32 s26, s17, s24
	s_cselect_b32 s25, s52, s55
	s_cselect_b32 s24, s53, s54
	v_lshl_add_u64 v[194:195], s[22:23], 0, v[206:207]
	s_add_i32 m0, s37, 0xc000
	ds_read_b128 v[154:157], v252
	ds_read_b128 v[166:169], v252 offset:1024
	ds_read_b128 v[170:173], v252 offset:2048
	ds_read_b128 v[174:177], v252 offset:3072
	ds_read_b128 v[178:181], v252 offset:4096
	ds_read_b128 v[182:185], v252 offset:5120
	ds_read_b128 v[186:189], v252 offset:6144
	ds_read_b128 v[190:193], v252 offset:7168
	global_load_lds_dwordx4 v[194:195], off
	v_lshl_add_u64 v[194:195], s[22:23], 0, v[208:209]
	s_add_i32 m0, s37, 0xe000
	s_nop 0
	global_load_lds_dwordx4 v[194:195], off
	s_waitcnt vmcnt(8)
	s_waitcnt lgkmcnt(0)
	s_setprio 1
	s_barrier
	v_mfma_f32_16x16x32_bf16 v[162:165], v[42:45], v[154:157], v[162:165]
	v_mfma_f32_16x16x32_bf16 v[158:161], v[58:61], v[154:157], v[158:161]
	v_mfma_f32_16x16x32_bf16 v[130:133], v[42:45], v[170:173], v[130:133]
	v_mfma_f32_16x16x32_bf16 v[126:129], v[58:61], v[170:173], v[126:129]
	v_mfma_f32_16x16x32_bf16 v[110:113], v[42:45], v[178:181], v[110:113]
	v_mfma_f32_16x16x32_bf16 v[106:109], v[58:61], v[178:181], v[106:109]
	v_mfma_f32_16x16x32_bf16 v[94:97], v[42:45], v[186:189], v[94:97]
	v_mfma_f32_16x16x32_bf16 v[90:93], v[58:61], v[186:189], v[90:93]
	v_mfma_f32_16x16x32_bf16 v[162:165], v[46:49], v[166:169], v[162:165]
	v_mfma_f32_16x16x32_bf16 v[158:161], v[62:65], v[166:169], v[158:161]
	v_mfma_f32_16x16x32_bf16 v[130:133], v[46:49], v[174:177], v[130:133]
	v_mfma_f32_16x16x32_bf16 v[126:129], v[62:65], v[174:177], v[126:129]
	v_mfma_f32_16x16x32_bf16 v[110:113], v[46:49], v[182:185], v[110:113]
	v_mfma_f32_16x16x32_bf16 v[106:109], v[62:65], v[182:185], v[106:109]
	v_mfma_f32_16x16x32_bf16 v[94:97], v[46:49], v[190:193], v[94:97]
	v_mfma_f32_16x16x32_bf16 v[90:93], v[62:65], v[190:193], v[90:93]
	s_setprio 0
	s_setprio 1
	v_mfma_f32_16x16x32_bf16 v[142:145], v[122:125], v[154:157], v[142:145]
	v_mfma_f32_16x16x32_bf16 v[138:141], v[146:149], v[154:157], v[138:141]
	v_mfma_f32_16x16x32_bf16 v[118:121], v[122:125], v[170:173], v[118:121]
	v_mfma_f32_16x16x32_bf16 v[114:117], v[146:149], v[170:173], v[114:117]
	v_mfma_f32_16x16x32_bf16 v[102:105], v[122:125], v[178:181], v[102:105]
	v_mfma_f32_16x16x32_bf16 v[98:101], v[146:149], v[178:181], v[98:101]
	v_mfma_f32_16x16x32_bf16 v[86:89], v[122:125], v[186:189], v[86:89]
	v_mfma_f32_16x16x32_bf16 v[82:85], v[146:149], v[186:189], v[82:85]
	v_mfma_f32_16x16x32_bf16 v[142:145], v[134:137], v[166:169], v[142:145]
	v_mfma_f32_16x16x32_bf16 v[138:141], v[150:153], v[166:169], v[138:141]
	v_mfma_f32_16x16x32_bf16 v[118:121], v[134:137], v[174:177], v[118:121]
	v_mfma_f32_16x16x32_bf16 v[114:117], v[150:153], v[174:177], v[114:117]
	v_mfma_f32_16x16x32_bf16 v[102:105], v[134:137], v[182:185], v[102:105]
	v_mfma_f32_16x16x32_bf16 v[98:101], v[150:153], v[182:185], v[98:101]
	v_mfma_f32_16x16x32_bf16 v[86:89], v[134:137], v[190:193], v[86:89]
	v_mfma_f32_16x16x32_bf16 v[82:85], v[150:153], v[190:193], v[82:85]
	s_setprio 0
	s_barrier
	s_add_i32 s57, s50, s36
	v_lshl_add_u64 v[194:195], s[24:25], 0, v[202:203]
	s_mov_b32 m0, s57
	ds_read_b128 v[154:157], v252 offset:16384
	ds_read_b128 v[166:169], v252 offset:17408
	ds_read_b128 v[170:173], v252 offset:18432
	ds_read_b128 v[174:177], v252 offset:19456
	ds_read_b128 v[178:181], v252 offset:20480
	ds_read_b128 v[182:185], v252 offset:21504
	ds_read_b128 v[186:189], v252 offset:22528
	ds_read_b128 v[190:193], v252 offset:23552
	global_load_lds_dwordx4 v[194:195], off
	s_add_i32 m0, s57, 0x2000
	s_add_u32 s58, s24, 0x80000
	v_lshl_add_u64 v[196:197], s[24:25], 0, v[204:205]
	s_addc_u32 s59, s25, 0
	s_add_i32 s57, s51, s36
	global_load_lds_dwordx4 v[196:197], off
	v_lshl_add_u64 v[198:199], s[58:59], 0, v[202:203]
	s_mov_b32 m0, s57
	v_lshl_add_u64 v[200:201], s[26:27], 0, v[204:205]
	global_load_lds_dwordx4 v[198:199], off
	v_lshl_add_u64 v[198:199], s[58:59], 0, v[204:205]
	s_add_i32 m0, s57, 0x2000
	s_nop 0
	global_load_lds_dwordx4 v[198:199], off
	v_lshl_add_u64 v[198:199], s[26:27], 0, v[202:203]
	s_mov_b32 m0, s37
	s_nop 0
	global_load_lds_dwordx4 v[198:199], off
	s_mov_b32 m0, s38
	s_nop 0
	global_load_lds_dwordx4 v[200:201], off
	s_waitcnt vmcnt(8)
	s_waitcnt lgkmcnt(0)
	s_setprio 1
	s_barrier
; #define PG8_STAGE(bufoff, gbase, VO) do { _Pragma("unroll") for (int _i = 0; _i < 2; ++_i) \
;         __builtin_amdgcn_global_load_lds((const unsigned*)((const char*)(gbase) + VO[_i]), (LAS unsigned*)(lds + (bufoff) + ldsw + _i * 8192), 16, 0, 0); } while (0)
; #define PG8_LDA(dst, b, h) do { _Pragma("unroll") for (int m = 0; m < 4; ++m) _Pragma("unroll") for (int k = 0; k < 2; ++k) dst[m][k] = *(const LAS bf16x8*)(lds + PG8_SA(b, h) + aoff + m * 2048 + k * 1024); } while (0)
; #define PG8_LDB(dst, b, h) do { _Pragma("unroll") for (int n = 0; n < 2; ++n) _Pragma("unroll") for (int k = 0; k < 2; ++k) dst[n][k] = *(const LAS bf16x8*)(lds + PG8_SB(b, h) + boff + n * 2048 + k * 1024); } while (0)
; #define PG8_MMA(ai, bj, At, Bt) do { __builtin_amdgcn_s_setprio(1); _Pragma("unroll") for (int m = 0; m < 4; ++m) _Pragma("unroll") for (int n = 0; n < 2; ++n) _Pragma("unroll") for (int k = 0; k < 2; ++k) \
;         acc[ai][bj][m][n] = __builtin_amdgcn_mfma_f32_16x16x32_bf16(Bt[n][k], At[m][k], acc[ai][bj][m][n], 0, 0, 0); __builtin_amdgcn_s_setprio(0); } while (0)
; #define PG8_WAIT_V(n) asm volatile("s_waitcnt vmcnt(" #n ")" ::: "memory")
; #define PG8_WAIT_L(n) asm volatile("s_waitcnt lgkmcnt(" #n ")" ::: "memory")
; #define PG8_BAR __builtin_amdgcn_s_barrier()
; #define PG8_SCHED __builtin_amdgcn_sched_barrier(0)
; template <int NSEG, class Epi, bool ALIGN_EPI = PG8_ALIGN, bool SP2 = PG8_SP2>
; DI void gemm_phase(LAS unsigned char* lds, const Gemm g, const StaticOrder& S, const Epi& E) {
;     ...
;             PG8_LDA(At, 0, 1); PG8_STAGE(PG8_SB(0, 0), b2, v2); PG8_STAGE(PG8_SB(0, 1), b2 + h2, v2); PG8_STAGE(PG8_SA(0, 0), a2, v2);
;             PG8_WAIT_V(8); PG8_WAIT_L(0); PG8_BAR; PG8_MMA(1, 0, At, B0); PG8_MMA(1, 1, At, B1); PG8_BAR; PG8_SCHED;
;             PG8_LDB(B0, 1, 0); PG8_LDB(B1, 1, 1); PG8_SCHED; PG8_LDA(At, 1, 0); PG8_STAGE(PG8_SA(0, 1), a2 + h2, v2);
;             PG8_WAIT_V(8); PG8_WAIT_L(0); PG8_BAR; PG8_MMA(0, 0, At, B0); PG8_MMA(0, 1, At, B1); PG8_BAR; PG8_SCHED;
	v_mfma_f32_16x16x32_bf16 v[78:81], v[42:45], v[154:157], v[78:81]
	v_mfma_f32_16x16x32_bf16 v[74:77], v[58:61], v[154:157], v[74:77]
	v_mfma_f32_16x16x32_bf16 v[54:57], v[42:45], v[170:173], v[54:57]
	v_mfma_f32_16x16x32_bf16 v[50:53], v[58:61], v[170:173], v[50:53]
	v_mfma_f32_16x16x32_bf16 v[30:33], v[42:45], v[178:181], v[30:33]
	v_mfma_f32_16x16x32_bf16 v[26:29], v[58:61], v[178:181], v[26:29]
	v_mfma_f32_16x16x32_bf16 v[14:17], v[42:45], v[186:189], v[14:17]
	v_mfma_f32_16x16x32_bf16 v[10:13], v[58:61], v[186:189], v[10:13]
	v_mfma_f32_16x16x32_bf16 v[78:81], v[46:49], v[166:169], v[78:81]
	v_mfma_f32_16x16x32_bf16 v[74:77], v[62:65], v[166:169], v[74:77]
	v_mfma_f32_16x16x32_bf16 v[54:57], v[46:49], v[174:177], v[54:57]
	v_mfma_f32_16x16x32_bf16 v[50:53], v[62:65], v[174:177], v[50:53]
	v_mfma_f32_16x16x32_bf16 v[30:33], v[46:49], v[182:185], v[30:33]
	v_mfma_f32_16x16x32_bf16 v[26:29], v[62:65], v[182:185], v[26:29]
	v_mfma_f32_16x16x32_bf16 v[14:17], v[46:49], v[190:193], v[14:17]
	v_mfma_f32_16x16x32_bf16 v[10:13], v[62:65], v[190:193], v[10:13]
	s_setprio 0
	s_setprio 1
	v_mfma_f32_16x16x32_bf16 v[38:41], v[122:125], v[170:173], v[38:41]
	v_mfma_f32_16x16x32_bf16 v[34:37], v[146:149], v[170:173], v[34:37]
	v_mfma_f32_16x16x32_bf16 v[22:25], v[122:125], v[178:181], v[22:25]
	v_mfma_f32_16x16x32_bf16 v[18:21], v[146:149], v[178:181], v[18:21]
	v_mfma_f32_16x16x32_bf16 v[6:9], v[122:125], v[186:189], v[6:9]
	v_mfma_f32_16x16x32_bf16 v[2:5], v[146:149], v[186:189], v[2:5]
	v_mfma_f32_16x16x32_bf16 v[42:45], v[122:125], v[154:157], v[70:73]
	v_mfma_f32_16x16x32_bf16 v[46:49], v[146:149], v[154:157], v[66:69]
	v_mfma_f32_16x16x32_bf16 v[38:41], v[134:137], v[174:177], v[38:41]
	v_mfma_f32_16x16x32_bf16 v[34:37], v[150:153], v[174:177], v[34:37]
	v_mfma_f32_16x16x32_bf16 v[22:25], v[134:137], v[182:185], v[22:25]
	v_mfma_f32_16x16x32_bf16 v[18:21], v[150:153], v[182:185], v[18:21]
	v_mfma_f32_16x16x32_bf16 v[6:9], v[134:137], v[190:193], v[6:9]
	v_mfma_f32_16x16x32_bf16 v[2:5], v[150:153], v[190:193], v[2:5]
	v_mfma_f32_16x16x32_bf16 v[42:45], v[134:137], v[166:169], v[42:45]
	v_mfma_f32_16x16x32_bf16 v[46:49], v[150:153], v[166:169], v[46:49]
	s_setprio 0
	s_barrier
	s_add_i32 s57, 0, 0x18000
	s_add_i32 s58, 0, 0x1c000
	v_add_u32_e32 v70, s57, v248
	v_add_u32_e32 v150, s58, v248
	ds_read_b128 v[58:61], v70
	ds_read_b128 v[62:65], v70 offset:1024
	ds_read_b128 v[66:69], v70 offset:2048
	ds_read_b128 v[70:73], v70 offset:3072
	ds_read_b128 v[122:125], v150
	ds_read_b128 v[134:137], v150 offset:1024
	ds_read_b128 v[146:149], v150 offset:2048
	ds_read_b128 v[150:153], v150 offset:3072
	s_add_u32 s26, s26, 0x80000
	s_addc_u32 s27, s27, 0
	s_mov_b32 m0, s39
	v_lshl_add_u64 v[212:213], s[26:27], 0, v[202:203]
	ds_read_b128 v[154:157], v252 offset:32768
	ds_read_b128 v[166:169], v252 offset:33792
	ds_read_b128 v[170:173], v252 offset:34816
	ds_read_b128 v[174:177], v252 offset:35840
	ds_read_b128 v[178:181], v252 offset:36864
	ds_read_b128 v[182:185], v252 offset:37888
	ds_read_b128 v[186:189], v252 offset:38912
	ds_read_b128 v[190:193], v252 offset:39936
	global_load_lds_dwordx4 v[212:213], off
	v_lshl_add_u64 v[212:213], s[26:27], 0, v[204:205]
	s_mov_b32 m0, s40
	s_nop 0
	global_load_lds_dwordx4 v[212:213], off
	s_waitcnt vmcnt(8)
	s_waitcnt lgkmcnt(0)
	s_setprio 1
	s_barrier
	v_mfma_f32_16x16x32_bf16 v[162:165], v[58:61], v[154:157], v[162:165]
	v_mfma_f32_16x16x32_bf16 v[158:161], v[66:69], v[154:157], v[158:161]
	v_mfma_f32_16x16x32_bf16 v[130:133], v[58:61], v[170:173], v[130:133]
	v_mfma_f32_16x16x32_bf16 v[126:129], v[66:69], v[170:173], v[126:129]
	v_mfma_f32_16x16x32_bf16 v[110:113], v[58:61], v[178:181], v[110:113]
	v_mfma_f32_16x16x32_bf16 v[106:109], v[66:69], v[178:181], v[106:109]
	v_mfma_f32_16x16x32_bf16 v[94:97], v[58:61], v[186:189], v[94:97]
	v_mfma_f32_16x16x32_bf16 v[90:93], v[66:69], v[186:189], v[90:93]
	v_mfma_f32_16x16x32_bf16 v[162:165], v[62:65], v[166:169], v[162:165]
	v_mfma_f32_16x16x32_bf16 v[158:161], v[70:73], v[166:169], v[158:161]
	v_mfma_f32_16x16x32_bf16 v[130:133], v[62:65], v[174:177], v[130:133]
	v_mfma_f32_16x16x32_bf16 v[126:129], v[70:73], v[174:177], v[126:129]
	v_mfma_f32_16x16x32_bf16 v[110:113], v[62:65], v[182:185], v[110:113]
	v_mfma_f32_16x16x32_bf16 v[106:109], v[70:73], v[182:185], v[106:109]
	v_mfma_f32_16x16x32_bf16 v[94:97], v[62:65], v[190:193], v[94:97]
	v_mfma_f32_16x16x32_bf16 v[90:93], v[70:73], v[190:193], v[90:93]
	s_setprio 0
	s_setprio 1
	v_mfma_f32_16x16x32_bf16 v[142:145], v[122:125], v[154:157], v[142:145]
	v_mfma_f32_16x16x32_bf16 v[138:141], v[146:149], v[154:157], v[138:141]
	v_mfma_f32_16x16x32_bf16 v[118:121], v[122:125], v[170:173], v[118:121]
	v_mfma_f32_16x16x32_bf16 v[114:117], v[146:149], v[170:173], v[114:117]
	v_mfma_f32_16x16x32_bf16 v[102:105], v[122:125], v[178:181], v[102:105]
	v_mfma_f32_16x16x32_bf16 v[98:101], v[146:149], v[178:181], v[98:101]
	v_mfma_f32_16x16x32_bf16 v[86:89], v[122:125], v[186:189], v[86:89]
	v_mfma_f32_16x16x32_bf16 v[82:85], v[146:149], v[186:189], v[82:85]
	v_mfma_f32_16x16x32_bf16 v[142:145], v[134:137], v[166:169], v[142:145]
	v_mfma_f32_16x16x32_bf16 v[138:141], v[150:153], v[166:169], v[138:141]
	v_mfma_f32_16x16x32_bf16 v[118:121], v[134:137], v[174:177], v[118:121]
	v_mfma_f32_16x16x32_bf16 v[114:117], v[150:153], v[174:177], v[114:117]
	v_mfma_f32_16x16x32_bf16 v[102:105], v[134:137], v[182:185], v[102:105]
	v_mfma_f32_16x16x32_bf16 v[98:101], v[150:153], v[182:185], v[98:101]
	v_mfma_f32_16x16x32_bf16 v[86:89], v[134:137], v[190:193], v[86:89]
	v_mfma_f32_16x16x32_bf16 v[82:85], v[150:153], v[190:193], v[82:85]
	s_setprio 0
	s_barrier
; #define PG8_STAGE(bufoff, gbase, VO) do { _Pragma("unroll") for (int _i = 0; _i < 2; ++_i) \
;         __builtin_amdgcn_global_load_lds((const unsigned*)((const char*)(gbase) + VO[_i]), (LAS unsigned*)(lds + (bufoff) + ldsw + _i * 8192), 16, 0, 0); } while (0)
; #define PG8_LDA(dst, b, h) do { _Pragma("unroll") for (int m = 0; m < 4; ++m) _Pragma("unroll") for (int k = 0; k < 2; ++k) dst[m][k] = *(const LAS bf16x8*)(lds + PG8_SA(b, h) + aoff + m * 2048 + k * 1024); } while (0)
; #define PG8_MMA(ai, bj, At, Bt) do { __builtin_amdgcn_s_setprio(1); _Pragma("unroll") for (int m = 0; m < 4; ++m) _Pragma("unroll") for (int n = 0; n < 2; ++n) _Pragma("unroll") for (int k = 0; k < 2; ++k) \
;         acc[ai][bj][m][n] = __builtin_amdgcn_mfma_f32_16x16x32_bf16(Bt[n][k], At[m][k], acc[ai][bj][m][n], 0, 0, 0); __builtin_amdgcn_s_setprio(0); } while (0)
; #define PG8_WAIT_V(n) asm volatile("s_waitcnt vmcnt(" #n ")" ::: "memory")
; #define PG8_WAIT_L(n) asm volatile("s_waitcnt lgkmcnt(" #n ")" ::: "memory")
; #define PG8_BAR __builtin_amdgcn_s_barrier()
; #define PG8_SCHED __builtin_amdgcn_sched_barrier(0)
; template <int NSEG, class Epi, bool ALIGN_EPI = PG8_ALIGN, bool SP2 = PG8_SP2>
; DI void gemm_phase(LAS unsigned char* lds, const Gemm g, const StaticOrder& S, const Epi& E) {
;     ...
;             PG8_LDA(At, 1, 1); PG8_STAGE(PG8_SB(1, 0), b3, v2); PG8_STAGE(PG8_SB(1, 1), b3 + h2, v2); PG8_STAGE(PG8_SA(1, 0), a3, v2);
;             PG8_WAIT_V(8); PG8_WAIT_L(0); PG8_BAR; PG8_MMA(1, 0, At, B0); PG8_MMA(1, 1, At, B1); PG8_BAR; PG8_SCHED;
	s_add_i32 s26, s57, s36
	v_lshl_add_u64 v[194:195], v[194:195], 0, s[10:11]
	s_mov_b32 m0, s26
	ds_read_b128 v[154:157], v252 offset:49152
	ds_read_b128 v[166:169], v252 offset:50176
	ds_read_b128 v[170:173], v252 offset:51200
	ds_read_b128 v[174:177], v252 offset:52224
	ds_read_b128 v[178:181], v252 offset:53248
	ds_read_b128 v[182:185], v252 offset:54272
	ds_read_b128 v[186:189], v252 offset:55296
	ds_read_b128 v[190:193], v252 offset:56320
	global_load_lds_dwordx4 v[194:195], off
	s_add_i32 m0, s26, 0x2000
	s_add_u32 s24, s24, 0x80080
	v_lshl_add_u64 v[194:195], v[196:197], 0, s[10:11]
	s_addc_u32 s25, s25, 0
	s_add_i32 s26, s58, s36
	global_load_lds_dwordx4 v[194:195], off
	v_lshl_add_u64 v[194:195], s[24:25], 0, v[202:203]
	s_mov_b32 m0, s26
	s_nop 0
	global_load_lds_dwordx4 v[194:195], off
	v_lshl_add_u64 v[194:195], s[24:25], 0, v[204:205]
	s_add_i32 m0, s26, 0x2000
	s_nop 0
	global_load_lds_dwordx4 v[194:195], off
	v_lshl_add_u64 v[194:195], v[198:199], 0, s[10:11]
	s_mov_b32 m0, s48
	s_nop 0
	global_load_lds_dwordx4 v[194:195], off
	v_lshl_add_u64 v[194:195], v[200:201], 0, s[10:11]
	s_mov_b32 m0, s49
	s_nop 0
	global_load_lds_dwordx4 v[194:195], off
	s_waitcnt vmcnt(8)
	s_waitcnt lgkmcnt(0)
	s_setprio 1
	s_barrier
	v_mfma_f32_16x16x32_bf16 v[78:81], v[58:61], v[154:157], v[78:81]
	v_mfma_f32_16x16x32_bf16 v[74:77], v[66:69], v[154:157], v[74:77]
	v_mfma_f32_16x16x32_bf16 v[54:57], v[58:61], v[170:173], v[54:57]
	v_mfma_f32_16x16x32_bf16 v[50:53], v[66:69], v[170:173], v[50:53]
	v_mfma_f32_16x16x32_bf16 v[30:33], v[58:61], v[178:181], v[30:33]
	v_mfma_f32_16x16x32_bf16 v[26:29], v[66:69], v[178:181], v[26:29]
	v_mfma_f32_16x16x32_bf16 v[14:17], v[58:61], v[186:189], v[14:17]
	v_mfma_f32_16x16x32_bf16 v[10:13], v[66:69], v[186:189], v[10:13]
	v_mfma_f32_16x16x32_bf16 v[78:81], v[62:65], v[166:169], v[78:81]
	v_mfma_f32_16x16x32_bf16 v[74:77], v[70:73], v[166:169], v[74:77]
	v_mfma_f32_16x16x32_bf16 v[54:57], v[62:65], v[174:177], v[54:57]
	v_mfma_f32_16x16x32_bf16 v[50:53], v[70:73], v[174:177], v[50:53]
	v_mfma_f32_16x16x32_bf16 v[30:33], v[62:65], v[182:185], v[30:33]
	v_mfma_f32_16x16x32_bf16 v[26:29], v[70:73], v[182:185], v[26:29]
	v_mfma_f32_16x16x32_bf16 v[14:17], v[62:65], v[190:193], v[14:17]
	v_mfma_f32_16x16x32_bf16 v[10:13], v[70:73], v[190:193], v[10:13]
	s_setprio 0
	s_setprio 1
	v_mfma_f32_16x16x32_bf16 v[42:45], v[122:125], v[154:157], v[42:45]
	v_mfma_f32_16x16x32_bf16 v[70:73], v[134:137], v[166:169], v[42:45]
	v_mfma_f32_16x16x32_bf16 v[42:45], v[146:149], v[154:157], v[46:49]
	v_mfma_f32_16x16x32_bf16 v[38:41], v[122:125], v[170:173], v[38:41]
	v_mfma_f32_16x16x32_bf16 v[34:37], v[146:149], v[170:173], v[34:37]
	v_mfma_f32_16x16x32_bf16 v[22:25], v[122:125], v[178:181], v[22:25]
	v_mfma_f32_16x16x32_bf16 v[18:21], v[146:149], v[178:181], v[18:21]
	v_mfma_f32_16x16x32_bf16 v[6:9], v[122:125], v[186:189], v[6:9]
	v_mfma_f32_16x16x32_bf16 v[2:5], v[146:149], v[186:189], v[2:5]
	v_mfma_f32_16x16x32_bf16 v[66:69], v[150:153], v[166:169], v[42:45]
	v_mfma_f32_16x16x32_bf16 v[38:41], v[134:137], v[174:177], v[38:41]
	v_mfma_f32_16x16x32_bf16 v[34:37], v[150:153], v[174:177], v[34:37]
	v_mfma_f32_16x16x32_bf16 v[22:25], v[134:137], v[182:185], v[22:25]
	v_mfma_f32_16x16x32_bf16 v[18:21], v[150:153], v[182:185], v[18:21]
	v_mfma_f32_16x16x32_bf16 v[6:9], v[134:137], v[190:193], v[6:9]
	v_mfma_f32_16x16x32_bf16 v[2:5], v[150:153], v[190:193], v[2:5]
	s_setprio 0
	s_barrier
	s_add_i32 s56, s56, 2
	s_add_u32 s22, s22, 0x100
	s_addc_u32 s23, s23, 0
	s_add_u32 s54, s54, 0x100
	s_addc_u32 s55, s55, 0
	s_cmp_gt_u32 s56, 29
	s_cbranch_scc0 .LBB0_281
	s_and_b64 vcc, exec, s[12:13]
	s_cbranch_vccz .LBB0_284
	s_barrier

; #define PG8_STAGE(bufoff, gbase, VO) do { _Pragma("unroll") for (int _i = 0; _i < 2; ++_i) \
;         __builtin_amdgcn_global_load_lds((const unsigned*)((const char*)(gbase) + VO[_i]), (LAS unsigned*)(lds + (bufoff) + ldsw + _i * 8192), 16, 0, 0); } while (0)
; #define PG8_LDA(dst, b, h) do { _Pragma("unroll") for (int m = 0; m < 4; ++m) _Pragma("unroll") for (int k = 0; k < 2; ++k) dst[m][k] = *(const LAS bf16x8*)(lds + PG8_SA(b, h) + aoff + m * 2048 + k * 1024); } while (0)
; #define PG8_LDB(dst, b, h) do { _Pragma("unroll") for (int n = 0; n < 2; ++n) _Pragma("unroll") for (int k = 0; k < 2; ++k) dst[n][k] = *(const LAS bf16x8*)(lds + PG8_SB(b, h) + boff + n * 2048 + k * 1024); } while (0)
; #define PG8_MMA(ai, bj, At, Bt) do { __builtin_amdgcn_s_setprio(1); _Pragma("unroll") for (int m = 0; m < 4; ++m) _Pragma("unroll") for (int n = 0; n < 2; ++n) _Pragma("unroll") for (int k = 0; k < 2; ++k) \
;         acc[ai][bj][m][n] = __builtin_amdgcn_mfma_f32_16x16x32_bf16(Bt[n][k], At[m][k], acc[ai][bj][m][n], 0, 0, 0); __builtin_amdgcn_s_setprio(0); } while (0)
; #define PG8_WAIT_V(n) asm volatile("s_waitcnt vmcnt(" #n ")" ::: "memory")
; #define PG8_WAIT_L(n) asm volatile("s_waitcnt lgkmcnt(" #n ")" ::: "memory")
; template <int NSEG, class Epi, bool ALIGN_EPI = PG8_ALIGN, bool SP2 = PG8_SP2>
; DI void gemm_phase(LAS unsigned char* lds, const Gemm g, const StaticOrder& S, const Epi& E) {
;     ...
;         for (int t = 0; t < nt; t += 2) {
;             const bool last = (t == nt - 2);
;             const char* a1 = cA + (size_t)(t + 1) * kstep;
;             const char* a2 = last ? nA : cA + (size_t)(t + 2) * kstep; const char* b2 = last ? nB : cB + (size_t)(t + 2) * kstep;
;             const char* a3 = a2 + kstep; const char* b3 = b2 + kstep;
;             unsigned v2[2]; v2[0] = (NSEG > 1 && last) ? voffN[0] : voffC[0]; v2[1] = (NSEG > 1 && last) ? voffN[1] : voffC[1];
;             const size_t h2 = (NSEG > 1 && last) ? hstepN : hstepC;
;             if constexpr (SP2) {
;             PG8_LDB(B0, 0, 0); PG8_LDB(B1, 0, 1); PG8_SCHED; PG8_LDA(At, 0, 0); PG8_STAGE(PG8_SA(1, 1), a1 + hstepC, voffC);
;             PG8_WAIT_V(8); PG8_WAIT_L(0); PG8_BAR; PG8_MMA(0, 0, At, B0); PG8_MMA(0, 1, At, B1); PG8_BAR; PG8_SCHED;
;             PG8_LDA(At, 0, 1); PG8_STAGE(PG8_SB(0, 0), b2, v2); PG8_STAGE(PG8_SB(0, 1), b2 + h2, v2); PG8_STAGE(PG8_SA(0, 0), a2, v2);
.LBB0_305:
	ds_read_b128 v[130:133], v161
	ds_read_b128 v[134:137], v161 offset:1024
	ds_read_b128 v[150:153], v161 offset:2048
	ds_read_b128 v[154:157], v161 offset:3072
	ds_read_b128 v[164:167], v162
	ds_read_b128 v[168:171], v162 offset:1024
	ds_read_b128 v[172:175], v162 offset:2048
	ds_read_b128 v[176:179], v162 offset:3072
	s_add_u32 s38, s36, 0xfff80080
	s_addc_u32 s39, s37, -1
	s_cmp_eq_u32 s66, 28
	s_cselect_b32 s41, s21, s39
	s_cselect_b32 s40, s23, s38
	s_cselect_b32 s39, s62, s65
	s_cselect_b32 s38, s63, s64
	v_lshl_add_u64 v[212:213], s[36:37], 0, v[142:143]
	s_add_i32 m0, s35, 0xc000
	ds_read_b128 v[180:183], v163
	ds_read_b128 v[184:187], v163 offset:1024
	ds_read_b128 v[188:191], v163 offset:2048
	ds_read_b128 v[192:195], v163 offset:3072
	ds_read_b128 v[196:199], v163 offset:4096
	ds_read_b128 v[200:203], v163 offset:5120
	ds_read_b128 v[204:207], v163 offset:6144
	ds_read_b128 v[208:211], v163 offset:7168
	global_load_lds_dwordx4 v[212:213], off
	v_lshl_add_u64 v[212:213], s[36:37], 0, v[144:145]
	s_add_i32 m0, s35, 0xe000
	s_nop 0
	global_load_lds_dwordx4 v[212:213], off
	s_waitcnt vmcnt(8)
	s_waitcnt lgkmcnt(0)
	s_setprio 1
	s_barrier
	v_mfma_f32_16x16x32_bf16 v[126:129], v[130:133], v[180:183], v[126:129]
	v_mfma_f32_16x16x32_bf16 v[122:125], v[150:153], v[180:183], v[122:125]
	v_mfma_f32_16x16x32_bf16 v[118:121], v[130:133], v[188:191], v[118:121]
	v_mfma_f32_16x16x32_bf16 v[114:117], v[150:153], v[188:191], v[114:117]
	v_mfma_f32_16x16x32_bf16 v[110:113], v[130:133], v[196:199], v[110:113]
	v_mfma_f32_16x16x32_bf16 v[106:109], v[150:153], v[196:199], v[106:109]
	v_mfma_f32_16x16x32_bf16 v[102:105], v[130:133], v[204:207], v[102:105]
	v_mfma_f32_16x16x32_bf16 v[98:101], v[150:153], v[204:207], v[98:101]
	v_mfma_f32_16x16x32_bf16 v[126:129], v[134:137], v[184:187], v[126:129]
	v_mfma_f32_16x16x32_bf16 v[122:125], v[154:157], v[184:187], v[122:125]
	v_mfma_f32_16x16x32_bf16 v[118:121], v[134:137], v[192:195], v[118:121]
	v_mfma_f32_16x16x32_bf16 v[114:117], v[154:157], v[192:195], v[114:117]
	v_mfma_f32_16x16x32_bf16 v[110:113], v[134:137], v[200:203], v[110:113]
	v_mfma_f32_16x16x32_bf16 v[106:109], v[154:157], v[200:203], v[106:109]
	v_mfma_f32_16x16x32_bf16 v[102:105], v[134:137], v[208:211], v[102:105]
	v_mfma_f32_16x16x32_bf16 v[98:101], v[154:157], v[208:211], v[98:101]
	s_setprio 0
	s_setprio 1
	v_mfma_f32_16x16x32_bf16 v[62:65], v[164:167], v[180:183], v[62:65]
	v_mfma_f32_16x16x32_bf16 v[58:61], v[172:175], v[180:183], v[58:61]
	v_mfma_f32_16x16x32_bf16 v[54:57], v[164:167], v[188:191], v[54:57]
	v_mfma_f32_16x16x32_bf16 v[50:53], v[172:175], v[188:191], v[50:53]
	v_mfma_f32_16x16x32_bf16 v[46:49], v[164:167], v[196:199], v[46:49]
	v_mfma_f32_16x16x32_bf16 v[42:45], v[172:175], v[196:199], v[42:45]
	v_mfma_f32_16x16x32_bf16 v[38:41], v[164:167], v[204:207], v[38:41]
	v_mfma_f32_16x16x32_bf16 v[34:37], v[172:175], v[204:207], v[34:37]
	v_mfma_f32_16x16x32_bf16 v[62:65], v[168:171], v[184:187], v[62:65]
	v_mfma_f32_16x16x32_bf16 v[58:61], v[176:179], v[184:187], v[58:61]
	v_mfma_f32_16x16x32_bf16 v[54:57], v[168:171], v[192:195], v[54:57]
	v_mfma_f32_16x16x32_bf16 v[50:53], v[176:179], v[192:195], v[50:53]
	v_mfma_f32_16x16x32_bf16 v[46:49], v[168:171], v[200:203], v[46:49]
	v_mfma_f32_16x16x32_bf16 v[42:45], v[176:179], v[200:203], v[42:45]
	v_mfma_f32_16x16x32_bf16 v[38:41], v[168:171], v[208:211], v[38:41]
	v_mfma_f32_16x16x32_bf16 v[34:37], v[176:179], v[208:211], v[34:37]
	s_setprio 0
	s_barrier
	s_add_i32 s67, s55, s48
	v_lshl_add_u64 v[212:213], s[38:39], 0, v[138:139]
	s_mov_b32 m0, s67
	ds_read_b128 v[180:183], v163 offset:16384
	ds_read_b128 v[184:187], v163 offset:17408
	ds_read_b128 v[188:191], v163 offset:18432
	ds_read_b128 v[192:195], v163 offset:19456
	ds_read_b128 v[196:199], v163 offset:20480
	ds_read_b128 v[200:203], v163 offset:21504
	ds_read_b128 v[204:207], v163 offset:22528
	ds_read_b128 v[208:211], v163 offset:23552
	global_load_lds_dwordx4 v[212:213], off
	s_add_i32 m0, s67, 0x2000
	s_add_u32 s68, s38, 0x80000
	v_lshl_add_u64 v[214:215], s[38:39], 0, v[140:141]
	s_addc_u32 s69, s39, 0
	s_add_i32 s67, s56, s48
	global_load_lds_dwordx4 v[214:215], off
	v_lshl_add_u64 v[216:217], s[68:69], 0, v[138:139]
	s_mov_b32 m0, s67
	v_lshl_add_u64 v[218:219], s[40:41], 0, v[140:141]
	global_load_lds_dwordx4 v[216:217], off
	v_lshl_add_u64 v[216:217], s[68:69], 0, v[140:141]
	s_add_i32 m0, s67, 0x2000
	s_nop 0
	global_load_lds_dwordx4 v[216:217], off
	v_lshl_add_u64 v[216:217], s[40:41], 0, v[138:139]
	s_mov_b32 m0, s35
	s_nop 0
	global_load_lds_dwordx4 v[216:217], off
	s_mov_b32 m0, s49
	s_nop 0
	global_load_lds_dwordx4 v[218:219], off
	s_waitcnt vmcnt(8)
	s_waitcnt lgkmcnt(0)
	s_setprio 1
	s_barrier
; #define PG8_STAGE(bufoff, gbase, VO) do { _Pragma("unroll") for (int _i = 0; _i < 2; ++_i) \
;         __builtin_amdgcn_global_load_lds((const unsigned*)((const char*)(gbase) + VO[_i]), (LAS unsigned*)(lds + (bufoff) + ldsw + _i * 8192), 16, 0, 0); } while (0)
; #define PG8_LDA(dst, b, h) do { _Pragma("unroll") for (int m = 0; m < 4; ++m) _Pragma("unroll") for (int k = 0; k < 2; ++k) dst[m][k] = *(const LAS bf16x8*)(lds + PG8_SA(b, h) + aoff + m * 2048 + k * 1024); } while (0)
; #define PG8_LDB(dst, b, h) do { _Pragma("unroll") for (int n = 0; n < 2; ++n) _Pragma("unroll") for (int k = 0; k < 2; ++k) dst[n][k] = *(const LAS bf16x8*)(lds + PG8_SB(b, h) + boff + n * 2048 + k * 1024); } while (0)
; #define PG8_MMA(ai, bj, At, Bt) do { __builtin_amdgcn_s_setprio(1); _Pragma("unroll") for (int m = 0; m < 4; ++m) _Pragma("unroll") for (int n = 0; n < 2; ++n) _Pragma("unroll") for (int k = 0; k < 2; ++k) \
;         acc[ai][bj][m][n] = __builtin_amdgcn_mfma_f32_16x16x32_bf16(Bt[n][k], At[m][k], acc[ai][bj][m][n], 0, 0, 0); __builtin_amdgcn_s_setprio(0); } while (0)
; #define PG8_WAIT_V(n) asm volatile("s_waitcnt vmcnt(" #n ")" ::: "memory")
; #define PG8_WAIT_L(n) asm volatile("s_waitcnt lgkmcnt(" #n ")" ::: "memory")
; #define PG8_BAR __builtin_amdgcn_s_barrier()
; #define PG8_SCHED __builtin_amdgcn_sched_barrier(0)
; template <int NSEG, class Epi, bool ALIGN_EPI = PG8_ALIGN, bool SP2 = PG8_SP2>
; DI void gemm_phase(LAS unsigned char* lds, const Gemm g, const StaticOrder& S, const Epi& E) {
;     ...
;             PG8_LDA(At, 0, 1); PG8_STAGE(PG8_SB(0, 0), b2, v2); PG8_STAGE(PG8_SB(0, 1), b2 + h2, v2); PG8_STAGE(PG8_SA(0, 0), a2, v2);
;             PG8_WAIT_V(8); PG8_WAIT_L(0); PG8_BAR; PG8_MMA(1, 0, At, B0); PG8_MMA(1, 1, At, B1); PG8_BAR; PG8_SCHED;
;             PG8_LDB(B0, 1, 0); PG8_LDB(B1, 1, 1); PG8_SCHED; PG8_LDA(At, 1, 0); PG8_STAGE(PG8_SA(0, 1), a2 + h2, v2);
;             PG8_WAIT_V(8); PG8_WAIT_L(0); PG8_BAR; PG8_MMA(0, 0, At, B0); PG8_MMA(0, 1, At, B1); PG8_BAR; PG8_SCHED;
	v_mfma_f32_16x16x32_bf16 v[94:97], v[130:133], v[180:183], v[94:97]
	v_mfma_f32_16x16x32_bf16 v[90:93], v[150:153], v[180:183], v[90:93]
	v_mfma_f32_16x16x32_bf16 v[86:89], v[130:133], v[188:191], v[86:89]
	v_mfma_f32_16x16x32_bf16 v[82:85], v[150:153], v[188:191], v[82:85]
	v_mfma_f32_16x16x32_bf16 v[78:81], v[130:133], v[196:199], v[78:81]
	v_mfma_f32_16x16x32_bf16 v[74:77], v[150:153], v[196:199], v[74:77]
	v_mfma_f32_16x16x32_bf16 v[70:73], v[130:133], v[204:207], v[70:73]
	v_mfma_f32_16x16x32_bf16 v[66:69], v[150:153], v[204:207], v[66:69]
	v_mfma_f32_16x16x32_bf16 v[94:97], v[134:137], v[184:187], v[94:97]
	v_mfma_f32_16x16x32_bf16 v[90:93], v[154:157], v[184:187], v[90:93]
	v_mfma_f32_16x16x32_bf16 v[86:89], v[134:137], v[192:195], v[86:89]
	v_mfma_f32_16x16x32_bf16 v[82:85], v[154:157], v[192:195], v[82:85]
	v_mfma_f32_16x16x32_bf16 v[78:81], v[134:137], v[200:203], v[78:81]
	v_mfma_f32_16x16x32_bf16 v[74:77], v[154:157], v[200:203], v[74:77]
	v_mfma_f32_16x16x32_bf16 v[70:73], v[134:137], v[208:211], v[70:73]
	v_mfma_f32_16x16x32_bf16 v[66:69], v[154:157], v[208:211], v[66:69]
	s_setprio 0
	s_setprio 1
	v_mfma_f32_16x16x32_bf16 v[30:33], v[164:167], v[180:183], v[30:33]
	v_mfma_f32_16x16x32_bf16 v[26:29], v[172:175], v[180:183], v[26:29]
	v_mfma_f32_16x16x32_bf16 v[14:17], v[164:167], v[188:191], v[14:17]
	v_mfma_f32_16x16x32_bf16 v[2:5], v[172:175], v[188:191], v[2:5]
	v_mfma_f32_16x16x32_bf16 v[22:25], v[164:167], v[196:199], v[22:25]
	v_mfma_f32_16x16x32_bf16 v[18:21], v[172:175], v[196:199], v[18:21]
	v_mfma_f32_16x16x32_bf16 v[10:13], v[164:167], v[204:207], v[10:13]
	v_mfma_f32_16x16x32_bf16 v[6:9], v[172:175], v[204:207], v[6:9]
	v_mfma_f32_16x16x32_bf16 v[30:33], v[168:171], v[184:187], v[30:33]
	v_mfma_f32_16x16x32_bf16 v[26:29], v[176:179], v[184:187], v[26:29]
	v_mfma_f32_16x16x32_bf16 v[14:17], v[168:171], v[192:195], v[14:17]
	v_mfma_f32_16x16x32_bf16 v[2:5], v[176:179], v[192:195], v[2:5]
	v_mfma_f32_16x16x32_bf16 v[22:25], v[168:171], v[200:203], v[22:25]
	v_mfma_f32_16x16x32_bf16 v[18:21], v[176:179], v[200:203], v[18:21]
	v_mfma_f32_16x16x32_bf16 v[10:13], v[168:171], v[208:211], v[10:13]
	v_mfma_f32_16x16x32_bf16 v[6:9], v[176:179], v[208:211], v[6:9]
	s_setprio 0
	s_barrier
	s_add_i32 s67, 0, 0x18000
	s_add_i32 s68, 0, 0x1c000
	v_add_u32_e32 v154, s67, v159
	v_add_u32_e32 v176, s68, v159
	ds_read_b128 v[130:133], v154
	ds_read_b128 v[134:137], v154 offset:1024
	ds_read_b128 v[150:153], v154 offset:2048
	ds_read_b128 v[154:157], v154 offset:3072
	ds_read_b128 v[164:167], v176
	ds_read_b128 v[168:171], v176 offset:1024
	ds_read_b128 v[172:175], v176 offset:2048
	ds_read_b128 v[176:179], v176 offset:3072
	s_add_u32 s40, s40, 0x80000
	s_addc_u32 s41, s41, 0
	s_mov_b32 m0, s50
	v_lshl_add_u64 v[220:221], s[40:41], 0, v[138:139]
	ds_read_b128 v[180:183], v163 offset:32768
	ds_read_b128 v[184:187], v163 offset:33792
	ds_read_b128 v[188:191], v163 offset:34816
	ds_read_b128 v[192:195], v163 offset:35840
	ds_read_b128 v[196:199], v163 offset:36864
	ds_read_b128 v[200:203], v163 offset:37888
	ds_read_b128 v[204:207], v163 offset:38912
	ds_read_b128 v[208:211], v163 offset:39936
	global_load_lds_dwordx4 v[220:221], off
	v_lshl_add_u64 v[220:221], s[40:41], 0, v[140:141]
	s_mov_b32 m0, s51
	s_nop 0
	global_load_lds_dwordx4 v[220:221], off
	s_waitcnt vmcnt(8)
	s_waitcnt lgkmcnt(0)
	s_setprio 1
	s_barrier
	v_mfma_f32_16x16x32_bf16 v[126:129], v[130:133], v[180:183], v[126:129]
	v_mfma_f32_16x16x32_bf16 v[122:125], v[150:153], v[180:183], v[122:125]
	v_mfma_f32_16x16x32_bf16 v[118:121], v[130:133], v[188:191], v[118:121]
	v_mfma_f32_16x16x32_bf16 v[114:117], v[150:153], v[188:191], v[114:117]
	v_mfma_f32_16x16x32_bf16 v[110:113], v[130:133], v[196:199], v[110:113]
	v_mfma_f32_16x16x32_bf16 v[106:109], v[150:153], v[196:199], v[106:109]
	v_mfma_f32_16x16x32_bf16 v[102:105], v[130:133], v[204:207], v[102:105]
	v_mfma_f32_16x16x32_bf16 v[98:101], v[150:153], v[204:207], v[98:101]
	v_mfma_f32_16x16x32_bf16 v[126:129], v[134:137], v[184:187], v[126:129]
	v_mfma_f32_16x16x32_bf16 v[122:125], v[154:157], v[184:187], v[122:125]
	v_mfma_f32_16x16x32_bf16 v[118:121], v[134:137], v[192:195], v[118:121]
	v_mfma_f32_16x16x32_bf16 v[114:117], v[154:157], v[192:195], v[114:117]
	v_mfma_f32_16x16x32_bf16 v[110:113], v[134:137], v[200:203], v[110:113]
	v_mfma_f32_16x16x32_bf16 v[106:109], v[154:157], v[200:203], v[106:109]
	v_mfma_f32_16x16x32_bf16 v[102:105], v[134:137], v[208:211], v[102:105]
	v_mfma_f32_16x16x32_bf16 v[98:101], v[154:157], v[208:211], v[98:101]
	s_setprio 0
	s_setprio 1
	v_mfma_f32_16x16x32_bf16 v[62:65], v[164:167], v[180:183], v[62:65]
	v_mfma_f32_16x16x32_bf16 v[58:61], v[172:175], v[180:183], v[58:61]
	v_mfma_f32_16x16x32_bf16 v[54:57], v[164:167], v[188:191], v[54:57]
	v_mfma_f32_16x16x32_bf16 v[50:53], v[172:175], v[188:191], v[50:53]
	v_mfma_f32_16x16x32_bf16 v[46:49], v[164:167], v[196:199], v[46:49]
	v_mfma_f32_16x16x32_bf16 v[42:45], v[172:175], v[196:199], v[42:45]
	v_mfma_f32_16x16x32_bf16 v[38:41], v[164:167], v[204:207], v[38:41]
	v_mfma_f32_16x16x32_bf16 v[34:37], v[172:175], v[204:207], v[34:37]
	v_mfma_f32_16x16x32_bf16 v[62:65], v[168:171], v[184:187], v[62:65]
	v_mfma_f32_16x16x32_bf16 v[58:61], v[176:179], v[184:187], v[58:61]
	v_mfma_f32_16x16x32_bf16 v[54:57], v[168:171], v[192:195], v[54:57]
	v_mfma_f32_16x16x32_bf16 v[50:53], v[176:179], v[192:195], v[50:53]
	v_mfma_f32_16x16x32_bf16 v[46:49], v[168:171], v[200:203], v[46:49]
	v_mfma_f32_16x16x32_bf16 v[42:45], v[176:179], v[200:203], v[42:45]
	v_mfma_f32_16x16x32_bf16 v[38:41], v[168:171], v[208:211], v[38:41]
	v_mfma_f32_16x16x32_bf16 v[34:37], v[176:179], v[208:211], v[34:37]
	s_setprio 0
	s_barrier
; #define PG8_STAGE(bufoff, gbase, VO) do { _Pragma("unroll") for (int _i = 0; _i < 2; ++_i) \
;         __builtin_amdgcn_global_load_lds((const unsigned*)((const char*)(gbase) + VO[_i]), (LAS unsigned*)(lds + (bufoff) + ldsw + _i * 8192), 16, 0, 0); } while (0)
; #define PG8_LDA(dst, b, h) do { _Pragma("unroll") for (int m = 0; m < 4; ++m) _Pragma("unroll") for (int k = 0; k < 2; ++k) dst[m][k] = *(const LAS bf16x8*)(lds + PG8_SA(b, h) + aoff + m * 2048 + k * 1024); } while (0)
; #define PG8_MMA(ai, bj, At, Bt) do { __builtin_amdgcn_s_setprio(1); _Pragma("unroll") for (int m = 0; m < 4; ++m) _Pragma("unroll") for (int n = 0; n < 2; ++n) _Pragma("unroll") for (int k = 0; k < 2; ++k) \
;         acc[ai][bj][m][n] = __builtin_amdgcn_mfma_f32_16x16x32_bf16(Bt[n][k], At[m][k], acc[ai][bj][m][n], 0, 0, 0); __builtin_amdgcn_s_setprio(0); } while (0)
; #define PG8_WAIT_V(n) asm volatile("s_waitcnt vmcnt(" #n ")" ::: "memory")
; #define PG8_WAIT_L(n) asm volatile("s_waitcnt lgkmcnt(" #n ")" ::: "memory")
; #define PG8_BAR __builtin_amdgcn_s_barrier()
; #define PG8_SCHED __builtin_amdgcn_sched_barrier(0)
; template <int NSEG, class Epi, bool ALIGN_EPI = PG8_ALIGN, bool SP2 = PG8_SP2>
; DI void gemm_phase(LAS unsigned char* lds, const Gemm g, const StaticOrder& S, const Epi& E) {
;     ...
;             PG8_LDA(At, 1, 1); PG8_STAGE(PG8_SB(1, 0), b3, v2); PG8_STAGE(PG8_SB(1, 1), b3 + h2, v2); PG8_STAGE(PG8_SA(1, 0), a3, v2);
;             PG8_WAIT_V(8); PG8_WAIT_L(0); PG8_BAR; PG8_MMA(1, 0, At, B0); PG8_MMA(1, 1, At, B1); PG8_BAR; PG8_SCHED;
	s_add_i32 s40, s67, s48
	v_lshl_add_u64 v[212:213], v[212:213], 0, s[8:9]
	s_mov_b32 m0, s40
	ds_read_b128 v[180:183], v163 offset:49152
	ds_read_b128 v[184:187], v163 offset:50176
	ds_read_b128 v[188:191], v163 offset:51200
	ds_read_b128 v[192:195], v163 offset:52224
	ds_read_b128 v[196:199], v163 offset:53248
	ds_read_b128 v[200:203], v163 offset:54272
	ds_read_b128 v[204:207], v163 offset:55296
	ds_read_b128 v[208:211], v163 offset:56320
	global_load_lds_dwordx4 v[212:213], off
	s_add_i32 m0, s40, 0x2000
	s_add_u32 s38, s38, 0x80080
	v_lshl_add_u64 v[212:213], v[214:215], 0, s[8:9]
	s_addc_u32 s39, s39, 0
	s_add_i32 s40, s68, s48
	global_load_lds_dwordx4 v[212:213], off
	v_lshl_add_u64 v[212:213], s[38:39], 0, v[138:139]
	s_mov_b32 m0, s40
	s_nop 0
	global_load_lds_dwordx4 v[212:213], off
	v_lshl_add_u64 v[212:213], s[38:39], 0, v[140:141]
	s_add_i32 m0, s40, 0x2000
	s_nop 0
	global_load_lds_dwordx4 v[212:213], off
	v_lshl_add_u64 v[212:213], v[216:217], 0, s[8:9]
	s_mov_b32 m0, s53
	s_nop 0
	global_load_lds_dwordx4 v[212:213], off
	v_lshl_add_u64 v[212:213], v[218:219], 0, s[8:9]
	s_mov_b32 m0, s54
	s_nop 0
	global_load_lds_dwordx4 v[212:213], off
	s_waitcnt vmcnt(8)
	s_waitcnt lgkmcnt(0)
	s_setprio 1
	s_barrier
	v_mfma_f32_16x16x32_bf16 v[94:97], v[130:133], v[180:183], v[94:97]
	v_mfma_f32_16x16x32_bf16 v[90:93], v[150:153], v[180:183], v[90:93]
	v_mfma_f32_16x16x32_bf16 v[86:89], v[130:133], v[188:191], v[86:89]
	v_mfma_f32_16x16x32_bf16 v[82:85], v[150:153], v[188:191], v[82:85]
	v_mfma_f32_16x16x32_bf16 v[78:81], v[130:133], v[196:199], v[78:81]
	v_mfma_f32_16x16x32_bf16 v[74:77], v[150:153], v[196:199], v[74:77]
	v_mfma_f32_16x16x32_bf16 v[70:73], v[130:133], v[204:207], v[70:73]
	v_mfma_f32_16x16x32_bf16 v[66:69], v[150:153], v[204:207], v[66:69]
	v_mfma_f32_16x16x32_bf16 v[94:97], v[134:137], v[184:187], v[94:97]
	v_mfma_f32_16x16x32_bf16 v[90:93], v[154:157], v[184:187], v[90:93]
	v_mfma_f32_16x16x32_bf16 v[86:89], v[134:137], v[192:195], v[86:89]
	v_mfma_f32_16x16x32_bf16 v[82:85], v[154:157], v[192:195], v[82:85]
	v_mfma_f32_16x16x32_bf16 v[78:81], v[134:137], v[200:203], v[78:81]
	v_mfma_f32_16x16x32_bf16 v[74:77], v[154:157], v[200:203], v[74:77]
	v_mfma_f32_16x16x32_bf16 v[70:73], v[134:137], v[208:211], v[70:73]
	v_mfma_f32_16x16x32_bf16 v[66:69], v[154:157], v[208:211], v[66:69]
	s_setprio 0
	s_setprio 1
	v_mfma_f32_16x16x32_bf16 v[30:33], v[164:167], v[180:183], v[30:33]
	v_mfma_f32_16x16x32_bf16 v[26:29], v[172:175], v[180:183], v[26:29]
	v_mfma_f32_16x16x32_bf16 v[14:17], v[164:167], v[188:191], v[14:17]
	v_mfma_f32_16x16x32_bf16 v[2:5], v[172:175], v[188:191], v[2:5]
	v_mfma_f32_16x16x32_bf16 v[22:25], v[164:167], v[196:199], v[22:25]
	v_mfma_f32_16x16x32_bf16 v[18:21], v[172:175], v[196:199], v[18:21]
	v_mfma_f32_16x16x32_bf16 v[10:13], v[164:167], v[204:207], v[10:13]
	v_mfma_f32_16x16x32_bf16 v[6:9], v[172:175], v[204:207], v[6:9]
	v_mfma_f32_16x16x32_bf16 v[30:33], v[168:171], v[184:187], v[30:33]
	v_mfma_f32_16x16x32_bf16 v[26:29], v[176:179], v[184:187], v[26:29]
	v_mfma_f32_16x16x32_bf16 v[14:17], v[168:171], v[192:195], v[14:17]
	v_mfma_f32_16x16x32_bf16 v[2:5], v[176:179], v[192:195], v[2:5]
	v_mfma_f32_16x16x32_bf16 v[22:25], v[168:171], v[200:203], v[22:25]
	v_mfma_f32_16x16x32_bf16 v[18:21], v[176:179], v[200:203], v[18:21]
	v_mfma_f32_16x16x32_bf16 v[10:13], v[168:171], v[208:211], v[10:13]
	v_mfma_f32_16x16x32_bf16 v[6:9], v[176:179], v[208:211], v[6:9]
	s_setprio 0
	s_barrier
	s_add_i32 s66, s66, 2
	s_add_u32 s36, s36, 0x100
	s_addc_u32 s37, s37, 0
	s_add_u32 s64, s64, 0x100
	s_addc_u32 s65, s65, 0
	s_cmp_gt_u32 s66, 29
	s_cbranch_scc0 .LBB0_305
	s_and_b64 vcc, exec, s[10:11]
	s_cbranch_vccz .LBB0_308
	s_barrier

; #define PG8_STAGE(bufoff, gbase, VO) do { _Pragma("unroll") for (int _i = 0; _i < 2; ++_i) \
;         __builtin_amdgcn_global_load_lds((const unsigned*)((const char*)(gbase) + VO[_i]), (LAS unsigned*)(lds + (bufoff) + ldsw + _i * 8192), 16, 0, 0); } while (0)
; #define PG8_LDA(dst, b, h) do { _Pragma("unroll") for (int m = 0; m < 4; ++m) _Pragma("unroll") for (int k = 0; k < 2; ++k) dst[m][k] = *(const LAS bf16x8*)(lds + PG8_SA(b, h) + aoff + m * 2048 + k * 1024); } while (0)
; #define PG8_LDB(dst, b, h) do { _Pragma("unroll") for (int n = 0; n < 2; ++n) _Pragma("unroll") for (int k = 0; k < 2; ++k) dst[n][k] = *(const LAS bf16x8*)(lds + PG8_SB(b, h) + boff + n * 2048 + k * 1024); } while (0)
; #define PG8_MMA(ai, bj, At, Bt) do { __builtin_amdgcn_s_setprio(1); _Pragma("unroll") for (int m = 0; m < 4; ++m) _Pragma("unroll") for (int n = 0; n < 2; ++n) _Pragma("unroll") for (int k = 0; k < 2; ++k) \
;         acc[ai][bj][m][n] = __builtin_amdgcn_mfma_f32_16x16x32_bf16(Bt[n][k], At[m][k], acc[ai][bj][m][n], 0, 0, 0); __builtin_amdgcn_s_setprio(0); } while (0)
; #define PG8_WAIT_V(n) asm volatile("s_waitcnt vmcnt(" #n ")" ::: "memory")
; #define PG8_WAIT_L(n) asm volatile("s_waitcnt lgkmcnt(" #n ")" ::: "memory")
; #define PG8_BAR __builtin_amdgcn_s_barrier()
; template <int NSEG, class Epi, bool ALIGN_EPI = PG8_ALIGN, bool SP2 = PG8_SP2>
; DI void gemm_phase(LAS unsigned char* lds, const Gemm g, const StaticOrder& S, const Epi& E) {
;     ...
;             const bool last = (t == nt - 2);
;             const char* a1 = cA + (size_t)(t + 1) * kstep;
;             const char* a2 = last ? nA : cA + (size_t)(t + 2) * kstep; const char* b2 = last ? nB : cB + (size_t)(t + 2) * kstep;
;             const char* a3 = a2 + kstep; const char* b3 = b2 + kstep;
;             unsigned v2[2]; v2[0] = (NSEG > 1 && last) ? voffN[0] : voffC[0]; v2[1] = (NSEG > 1 && last) ? voffN[1] : voffC[1];
;             const size_t h2 = (NSEG > 1 && last) ? hstepN : hstepC;
;             if constexpr (SP2) {
;             PG8_LDB(B0, 0, 0); PG8_LDB(B1, 0, 1); PG8_SCHED; PG8_LDA(At, 0, 0); PG8_STAGE(PG8_SA(1, 1), a1 + hstepC, voffC);
;             PG8_WAIT_V(8); PG8_WAIT_L(0); PG8_BAR; PG8_MMA(0, 0, At, B0); PG8_MMA(0, 1, At, B1); PG8_BAR; PG8_SCHED;
;             PG8_LDA(At, 0, 1); PG8_STAGE(PG8_SB(0, 0), b2, v2); PG8_STAGE(PG8_SB(0, 1), b2 + h2, v2); PG8_STAGE(PG8_SA(0, 0), a2, v2);
.LBB0_369:
	v_add_u32_e32 v131, s59, v194
	v_add_u32_e32 v133, s60, v194
	ds_read_b128 v[138:141], v131
	ds_read_b128 v[142:145], v131 offset:1024
	ds_read_b128 v[146:149], v131 offset:2048
	ds_read_b128 v[150:153], v131 offset:3072
	ds_read_b128 v[154:157], v133
	ds_read_b128 v[158:161], v133 offset:1024
	ds_read_b128 v[162:165], v133 offset:2048
	ds_read_b128 v[166:169], v133 offset:3072
	s_cmp_eq_u32 s69, s72
	s_cselect_b64 vcc, -1, 0
	s_add_i32 s72, s72, 2
	s_add_u32 s42, s34, s38
	s_addc_u32 s43, s35, s39
	s_add_u32 s73, s42, 0x100
	s_addc_u32 s74, s43, 0
	s_and_b64 s[42:43], vcc, exec
	s_cselect_b32 s43, s21, s74
	s_cselect_b32 s42, s20, s73
	s_cselect_b32 s73, s25, s37
	s_cselect_b32 s74, s24, s36
	s_add_u32 s75, s70, s38
	s_addc_u32 s78, s71, s39
	s_and_b64 s[76:77], vcc, exec
	v_cndmask_b32_e32 v174, v132, v197, vcc
	v_cndmask_b32_e32 v216, v130, v198, vcc
	s_cselect_b32 s77, s23, s78
	s_cselect_b32 s76, s22, s75
	v_lshl_add_u64 v[218:219], v[134:135], 0, s[38:39]
	s_add_i32 m0, s48, 0xc000
	ds_read_b128 v[170:173], v196
	ds_read_b128 v[178:181], v196 offset:1024
	ds_read_b128 v[182:185], v196 offset:2048
	ds_read_b128 v[186:189], v196 offset:3072
	ds_read_b128 v[200:203], v196 offset:4096
	ds_read_b128 v[204:207], v196 offset:5120
	ds_read_b128 v[208:211], v196 offset:6144
	ds_read_b128 v[212:215], v196 offset:7168
	global_load_lds_dwordx4 v[218:219], off
	v_lshl_add_u64 v[218:219], v[136:137], 0, s[38:39]
	s_add_i32 m0, s48, 0xe000
	s_nop 0
	global_load_lds_dwordx4 v[218:219], off
	s_waitcnt vmcnt(8)
	s_waitcnt lgkmcnt(0)
	s_setprio 1
	s_barrier
	v_mfma_f32_16x16x32_bf16 v[126:129], v[138:141], v[170:173], v[126:129]
	v_mfma_f32_16x16x32_bf16 v[122:125], v[146:149], v[170:173], v[122:125]
	v_mfma_f32_16x16x32_bf16 v[118:121], v[138:141], v[182:185], v[118:121]
	v_mfma_f32_16x16x32_bf16 v[114:117], v[146:149], v[182:185], v[114:117]
	v_mfma_f32_16x16x32_bf16 v[106:109], v[138:141], v[200:203], v[106:109]
	v_mfma_f32_16x16x32_bf16 v[98:101], v[146:149], v[200:203], v[98:101]
	v_mfma_f32_16x16x32_bf16 v[90:93], v[138:141], v[208:211], v[90:93]
	v_mfma_f32_16x16x32_bf16 v[82:85], v[146:149], v[208:211], v[82:85]
	v_mfma_f32_16x16x32_bf16 v[126:129], v[142:145], v[178:181], v[126:129]
	v_mfma_f32_16x16x32_bf16 v[122:125], v[150:153], v[178:181], v[122:125]
	v_mfma_f32_16x16x32_bf16 v[118:121], v[142:145], v[186:189], v[118:121]
	v_mfma_f32_16x16x32_bf16 v[114:117], v[150:153], v[186:189], v[114:117]
	v_mfma_f32_16x16x32_bf16 v[106:109], v[142:145], v[204:207], v[106:109]
	v_mfma_f32_16x16x32_bf16 v[98:101], v[150:153], v[204:207], v[98:101]
	v_mfma_f32_16x16x32_bf16 v[90:93], v[142:145], v[212:215], v[90:93]
	v_mfma_f32_16x16x32_bf16 v[82:85], v[150:153], v[212:215], v[82:85]
	s_setprio 0
	s_setprio 1
	v_mfma_f32_16x16x32_bf16 v[78:81], v[154:157], v[170:173], v[78:81]
	v_mfma_f32_16x16x32_bf16 v[74:77], v[162:165], v[170:173], v[74:77]
	v_mfma_f32_16x16x32_bf16 v[70:73], v[154:157], v[182:185], v[70:73]
	v_mfma_f32_16x16x32_bf16 v[66:69], v[162:165], v[182:185], v[66:69]
	v_mfma_f32_16x16x32_bf16 v[62:65], v[154:157], v[200:203], v[62:65]
	v_mfma_f32_16x16x32_bf16 v[58:61], v[162:165], v[200:203], v[58:61]
	v_mfma_f32_16x16x32_bf16 v[54:57], v[154:157], v[208:211], v[54:57]
	v_mfma_f32_16x16x32_bf16 v[50:53], v[162:165], v[208:211], v[50:53]
	v_mfma_f32_16x16x32_bf16 v[78:81], v[158:161], v[178:181], v[78:81]
	v_mfma_f32_16x16x32_bf16 v[74:77], v[166:169], v[178:181], v[74:77]
	v_mfma_f32_16x16x32_bf16 v[70:73], v[158:161], v[186:189], v[70:73]
	v_mfma_f32_16x16x32_bf16 v[66:69], v[166:169], v[186:189], v[66:69]
	v_mfma_f32_16x16x32_bf16 v[62:65], v[158:161], v[204:207], v[62:65]
	v_mfma_f32_16x16x32_bf16 v[58:61], v[166:169], v[204:207], v[58:61]
	v_mfma_f32_16x16x32_bf16 v[54:57], v[158:161], v[212:215], v[54:57]
	v_mfma_f32_16x16x32_bf16 v[50:53], v[166:169], v[212:215], v[50:53]
	s_setprio 0
	s_barrier
	s_add_i32 s75, s59, s47
	s_mov_b32 m0, s75
	ds_read_b128 v[170:173], v196 offset:16384
	ds_read_b128 v[178:181], v196 offset:17408
	ds_read_b128 v[182:185], v196 offset:18432
	ds_read_b128 v[186:189], v196 offset:19456
	ds_read_b128 v[200:203], v196 offset:20480
	ds_read_b128 v[204:207], v196 offset:21504
	ds_read_b128 v[208:211], v196 offset:22528
	ds_read_b128 v[212:215], v196 offset:23552
	global_load_lds_dwordx4 v174, s[76:77]
	v_mov_b32_e32 v217, v175
	s_add_i32 m0, s75, 0x2000
	v_lshl_add_u64 v[218:219], s[76:77], 0, v[174:175]
	v_lshl_add_u64 v[220:221], s[76:77], 0, v[216:217]
	global_load_lds_dwordx4 v216, s[76:77]
	s_add_u32 s76, s76, s74
	s_addc_u32 s77, s77, s73
	s_add_i32 s75, s60, s47
	s_mov_b32 m0, s75
	v_lshl_add_u64 v[222:223], s[76:77], 0, v[174:175]
	global_load_lds_dwordx4 v174, s[76:77]
	s_add_i32 m0, s75, 0x2000
	v_lshl_add_u64 v[224:225], s[76:77], 0, v[216:217]
	global_load_lds_dwordx4 v216, s[76:77]
	s_mov_b32 m0, s48
	v_lshl_add_u64 v[226:227], s[42:43], 0, v[174:175]
	global_load_lds_dwordx4 v174, s[42:43]
	s_mov_b32 m0, s49
	v_lshl_add_u64 v[228:229], s[42:43], 0, v[216:217]
	global_load_lds_dwordx4 v216, s[42:43]
	s_waitcnt vmcnt(8)
	s_waitcnt lgkmcnt(0)
	s_setprio 1
	s_barrier
; #define PG8_STAGE(bufoff, gbase, VO) do { _Pragma("unroll") for (int _i = 0; _i < 2; ++_i) \
;         __builtin_amdgcn_global_load_lds((const unsigned*)((const char*)(gbase) + VO[_i]), (LAS unsigned*)(lds + (bufoff) + ldsw + _i * 8192), 16, 0, 0); } while (0)
; #define PG8_LDA(dst, b, h) do { _Pragma("unroll") for (int m = 0; m < 4; ++m) _Pragma("unroll") for (int k = 0; k < 2; ++k) dst[m][k] = *(const LAS bf16x8*)(lds + PG8_SA(b, h) + aoff + m * 2048 + k * 1024); } while (0)
; #define PG8_LDB(dst, b, h) do { _Pragma("unroll") for (int n = 0; n < 2; ++n) _Pragma("unroll") for (int k = 0; k < 2; ++k) dst[n][k] = *(const LAS bf16x8*)(lds + PG8_SB(b, h) + boff + n * 2048 + k * 1024); } while (0)
; #define PG8_MMA(ai, bj, At, Bt) do { __builtin_amdgcn_s_setprio(1); _Pragma("unroll") for (int m = 0; m < 4; ++m) _Pragma("unroll") for (int n = 0; n < 2; ++n) _Pragma("unroll") for (int k = 0; k < 2; ++k) \
;         acc[ai][bj][m][n] = __builtin_amdgcn_mfma_f32_16x16x32_bf16(Bt[n][k], At[m][k], acc[ai][bj][m][n], 0, 0, 0); __builtin_amdgcn_s_setprio(0); } while (0)
; #define PG8_WAIT_V(n) asm volatile("s_waitcnt vmcnt(" #n ")" ::: "memory")
; #define PG8_WAIT_L(n) asm volatile("s_waitcnt lgkmcnt(" #n ")" ::: "memory")
; #define PG8_BAR __builtin_amdgcn_s_barrier()
; #define PG8_SCHED __builtin_amdgcn_sched_barrier(0)
; template <int NSEG, class Epi, bool ALIGN_EPI = PG8_ALIGN, bool SP2 = PG8_SP2>
; DI void gemm_phase(LAS unsigned char* lds, const Gemm g, const StaticOrder& S, const Epi& E) {
;     ...
;             PG8_LDA(At, 0, 1); PG8_STAGE(PG8_SB(0, 0), b2, v2); PG8_STAGE(PG8_SB(0, 1), b2 + h2, v2); PG8_STAGE(PG8_SA(0, 0), a2, v2);
;             PG8_WAIT_V(8); PG8_WAIT_L(0); PG8_BAR; PG8_MMA(1, 0, At, B0); PG8_MMA(1, 1, At, B1); PG8_BAR; PG8_SCHED;
;             PG8_LDB(B0, 1, 0); PG8_LDB(B1, 1, 1); PG8_SCHED; PG8_LDA(At, 1, 0); PG8_STAGE(PG8_SA(0, 1), a2 + h2, v2);
;             PG8_WAIT_V(8); PG8_WAIT_L(0); PG8_BAR; PG8_MMA(0, 0, At, B0); PG8_MMA(0, 1, At, B1); PG8_BAR; PG8_SCHED;
	v_mfma_f32_16x16x32_bf16 v[46:49], v[138:141], v[170:173], v[46:49]
	v_mfma_f32_16x16x32_bf16 v[42:45], v[146:149], v[170:173], v[42:45]
	v_mfma_f32_16x16x32_bf16 v[38:41], v[138:141], v[182:185], v[38:41]
	v_mfma_f32_16x16x32_bf16 v[34:37], v[146:149], v[182:185], v[34:37]
	v_mfma_f32_16x16x32_bf16 v[30:33], v[138:141], v[200:203], v[30:33]
	v_mfma_f32_16x16x32_bf16 v[26:29], v[146:149], v[200:203], v[26:29]
	v_mfma_f32_16x16x32_bf16 v[22:25], v[138:141], v[208:211], v[22:25]
	v_mfma_f32_16x16x32_bf16 v[18:21], v[146:149], v[208:211], v[18:21]
	v_mfma_f32_16x16x32_bf16 v[46:49], v[142:145], v[178:181], v[46:49]
	v_mfma_f32_16x16x32_bf16 v[42:45], v[150:153], v[178:181], v[42:45]
	v_mfma_f32_16x16x32_bf16 v[38:41], v[142:145], v[186:189], v[38:41]
	v_mfma_f32_16x16x32_bf16 v[34:37], v[150:153], v[186:189], v[34:37]
	v_mfma_f32_16x16x32_bf16 v[30:33], v[142:145], v[204:207], v[30:33]
	v_mfma_f32_16x16x32_bf16 v[26:29], v[150:153], v[204:207], v[26:29]
	v_mfma_f32_16x16x32_bf16 v[22:25], v[142:145], v[212:215], v[22:25]
	v_mfma_f32_16x16x32_bf16 v[18:21], v[150:153], v[212:215], v[18:21]
	s_setprio 0
	s_setprio 1
	v_mfma_f32_16x16x32_bf16 v[14:17], v[154:157], v[170:173], v[14:17]
	v_mfma_f32_16x16x32_bf16 v[10:13], v[162:165], v[170:173], v[10:13]
	v_mfma_f32_16x16x32_bf16 v[6:9], v[154:157], v[182:185], v[6:9]
	v_mfma_f32_16x16x32_bf16 v[2:5], v[162:165], v[182:185], v[2:5]
	v_mfma_f32_16x16x32_bf16 v[86:89], v[154:157], v[200:203], v[86:89]
	v_mfma_f32_16x16x32_bf16 v[94:97], v[162:165], v[200:203], v[94:97]
	v_mfma_f32_16x16x32_bf16 v[102:105], v[154:157], v[208:211], v[102:105]
	v_mfma_f32_16x16x32_bf16 v[110:113], v[162:165], v[208:211], v[110:113]
	v_mfma_f32_16x16x32_bf16 v[14:17], v[158:161], v[178:181], v[14:17]
	v_mfma_f32_16x16x32_bf16 v[10:13], v[166:169], v[178:181], v[10:13]
	v_mfma_f32_16x16x32_bf16 v[6:9], v[158:161], v[186:189], v[6:9]
	v_mfma_f32_16x16x32_bf16 v[2:5], v[166:169], v[186:189], v[2:5]
	v_mfma_f32_16x16x32_bf16 v[86:89], v[158:161], v[204:207], v[86:89]
	v_mfma_f32_16x16x32_bf16 v[94:97], v[166:169], v[204:207], v[94:97]
	v_mfma_f32_16x16x32_bf16 v[102:105], v[158:161], v[212:215], v[102:105]
	v_mfma_f32_16x16x32_bf16 v[110:113], v[166:169], v[212:215], v[110:113]
	s_setprio 0
	s_barrier
	s_add_i32 s75, 0, 0x18000
	v_add_u32_e32 v131, s75, v194
	s_add_i32 s76, 0, 0x1c000
	ds_read_b128 v[138:141], v131
	ds_read_b128 v[142:145], v131 offset:1024
	ds_read_b128 v[146:149], v131 offset:2048
	ds_read_b128 v[150:153], v131 offset:3072
	v_add_u32_e32 v131, s76, v194
	ds_read_b128 v[154:157], v131
	ds_read_b128 v[158:161], v131 offset:1024
	ds_read_b128 v[162:165], v131 offset:2048
	ds_read_b128 v[166:169], v131 offset:3072
	s_add_u32 s42, s42, s74
	s_addc_u32 s43, s43, s73
	s_mov_b32 m0, s50
	ds_read_b128 v[170:173], v196 offset:32768
	ds_read_b128 v[178:181], v196 offset:33792
	ds_read_b128 v[182:185], v196 offset:34816
	ds_read_b128 v[186:189], v196 offset:35840
	ds_read_b128 v[200:203], v196 offset:36864
	ds_read_b128 v[204:207], v196 offset:37888
	ds_read_b128 v[208:211], v196 offset:38912
	ds_read_b128 v[212:215], v196 offset:39936
	global_load_lds_dwordx4 v174, s[42:43]
	s_mov_b32 m0, s51
	s_nop 0
	global_load_lds_dwordx4 v216, s[42:43]
	s_waitcnt vmcnt(8)
	s_waitcnt lgkmcnt(0)
	s_setprio 1
	s_barrier
	v_mfma_f32_16x16x32_bf16 v[126:129], v[138:141], v[170:173], v[126:129]
	v_mfma_f32_16x16x32_bf16 v[122:125], v[146:149], v[170:173], v[122:125]
	v_mfma_f32_16x16x32_bf16 v[118:121], v[138:141], v[182:185], v[118:121]
	v_mfma_f32_16x16x32_bf16 v[114:117], v[146:149], v[182:185], v[114:117]
	v_mfma_f32_16x16x32_bf16 v[106:109], v[138:141], v[200:203], v[106:109]
	v_mfma_f32_16x16x32_bf16 v[98:101], v[146:149], v[200:203], v[98:101]
	v_mfma_f32_16x16x32_bf16 v[90:93], v[138:141], v[208:211], v[90:93]
	v_mfma_f32_16x16x32_bf16 v[82:85], v[146:149], v[208:211], v[82:85]
	v_mfma_f32_16x16x32_bf16 v[126:129], v[142:145], v[178:181], v[126:129]
	v_mfma_f32_16x16x32_bf16 v[122:125], v[150:153], v[178:181], v[122:125]
	v_mfma_f32_16x16x32_bf16 v[118:121], v[142:145], v[186:189], v[118:121]
	v_mfma_f32_16x16x32_bf16 v[114:117], v[150:153], v[186:189], v[114:117]
	v_mfma_f32_16x16x32_bf16 v[106:109], v[142:145], v[204:207], v[106:109]
	v_mfma_f32_16x16x32_bf16 v[98:101], v[150:153], v[204:207], v[98:101]
	v_mfma_f32_16x16x32_bf16 v[90:93], v[142:145], v[212:215], v[90:93]
	v_mfma_f32_16x16x32_bf16 v[82:85], v[150:153], v[212:215], v[82:85]
	s_setprio 0
	s_setprio 1
	v_mfma_f32_16x16x32_bf16 v[78:81], v[154:157], v[170:173], v[78:81]
	v_mfma_f32_16x16x32_bf16 v[74:77], v[162:165], v[170:173], v[74:77]
	v_mfma_f32_16x16x32_bf16 v[70:73], v[154:157], v[182:185], v[70:73]
	v_mfma_f32_16x16x32_bf16 v[66:69], v[162:165], v[182:185], v[66:69]
	v_mfma_f32_16x16x32_bf16 v[62:65], v[154:157], v[200:203], v[62:65]
	v_mfma_f32_16x16x32_bf16 v[58:61], v[162:165], v[200:203], v[58:61]
	v_mfma_f32_16x16x32_bf16 v[54:57], v[154:157], v[208:211], v[54:57]
	v_mfma_f32_16x16x32_bf16 v[50:53], v[162:165], v[208:211], v[50:53]
	v_mfma_f32_16x16x32_bf16 v[78:81], v[158:161], v[178:181], v[78:81]
	v_mfma_f32_16x16x32_bf16 v[74:77], v[166:169], v[178:181], v[74:77]
	v_mfma_f32_16x16x32_bf16 v[70:73], v[158:161], v[186:189], v[70:73]
	v_mfma_f32_16x16x32_bf16 v[66:69], v[166:169], v[186:189], v[66:69]
	v_mfma_f32_16x16x32_bf16 v[62:65], v[158:161], v[204:207], v[62:65]
	v_mfma_f32_16x16x32_bf16 v[58:61], v[166:169], v[204:207], v[58:61]
	v_mfma_f32_16x16x32_bf16 v[54:57], v[158:161], v[212:215], v[54:57]
	v_mfma_f32_16x16x32_bf16 v[50:53], v[166:169], v[212:215], v[50:53]
	s_setprio 0
	s_barrier
; #define PG8_STAGE(bufoff, gbase, VO) do { _Pragma("unroll") for (int _i = 0; _i < 2; ++_i) \
;         __builtin_amdgcn_global_load_lds((const unsigned*)((const char*)(gbase) + VO[_i]), (LAS unsigned*)(lds + (bufoff) + ldsw + _i * 8192), 16, 0, 0); } while (0)
; #define PG8_LDA(dst, b, h) do { _Pragma("unroll") for (int m = 0; m < 4; ++m) _Pragma("unroll") for (int k = 0; k < 2; ++k) dst[m][k] = *(const LAS bf16x8*)(lds + PG8_SA(b, h) + aoff + m * 2048 + k * 1024); } while (0)
; #define PG8_MMA(ai, bj, At, Bt) do { __builtin_amdgcn_s_setprio(1); _Pragma("unroll") for (int m = 0; m < 4; ++m) _Pragma("unroll") for (int n = 0; n < 2; ++n) _Pragma("unroll") for (int k = 0; k < 2; ++k) \
;         acc[ai][bj][m][n] = __builtin_amdgcn_mfma_f32_16x16x32_bf16(Bt[n][k], At[m][k], acc[ai][bj][m][n], 0, 0, 0); __builtin_amdgcn_s_setprio(0); } while (0)
; #define PG8_WAIT_V(n) asm volatile("s_waitcnt vmcnt(" #n ")" ::: "memory")
; #define PG8_WAIT_L(n) asm volatile("s_waitcnt lgkmcnt(" #n ")" ::: "memory")
; #define PG8_BAR __builtin_amdgcn_s_barrier()
; #define PG8_SCHED __builtin_amdgcn_sched_barrier(0)
; template <int NSEG, class Epi, bool ALIGN_EPI = PG8_ALIGN, bool SP2 = PG8_SP2>
; DI void gemm_phase(LAS unsigned char* lds, const Gemm g, const StaticOrder& S, const Epi& E) {
;     ...
;             PG8_LDA(At, 1, 1); PG8_STAGE(PG8_SB(1, 0), b3, v2); PG8_STAGE(PG8_SB(1, 1), b3 + h2, v2); PG8_STAGE(PG8_SA(1, 0), a3, v2);
;             PG8_WAIT_V(8); PG8_WAIT_L(0); PG8_BAR; PG8_MMA(1, 0, At, B0); PG8_MMA(1, 1, At, B1); PG8_BAR; PG8_SCHED;
	s_add_i32 s42, s75, s47
	v_lshl_add_u64 v[216:217], v[218:219], 0, s[10:11]
	s_mov_b32 m0, s42
	ds_read_b128 v[170:173], v196 offset:49152
	ds_read_b128 v[178:181], v196 offset:50176
	ds_read_b128 v[182:185], v196 offset:51200
	ds_read_b128 v[186:189], v196 offset:52224
	ds_read_b128 v[200:203], v196 offset:53248
	ds_read_b128 v[204:207], v196 offset:54272
	ds_read_b128 v[208:211], v196 offset:55296
	ds_read_b128 v[212:215], v196 offset:56320
	global_load_lds_dwordx4 v[216:217], off
	v_lshl_add_u64 v[216:217], v[220:221], 0, s[10:11]
	s_add_i32 m0, s42, 0x2000
	s_add_i32 s42, s76, s47
	global_load_lds_dwordx4 v[216:217], off
	v_lshl_add_u64 v[216:217], v[222:223], 0, s[10:11]
	s_mov_b32 m0, s42
	s_nop 0
	global_load_lds_dwordx4 v[216:217], off
	v_lshl_add_u64 v[216:217], v[224:225], 0, s[10:11]
	s_add_i32 m0, s42, 0x2000
	s_nop 0
	global_load_lds_dwordx4 v[216:217], off
	v_lshl_add_u64 v[216:217], v[226:227], 0, s[10:11]
	s_mov_b32 m0, s56
	s_nop 0
	global_load_lds_dwordx4 v[216:217], off
	v_lshl_add_u64 v[216:217], v[228:229], 0, s[10:11]
	s_mov_b32 m0, s57
	s_nop 0
	global_load_lds_dwordx4 v[216:217], off
	s_waitcnt vmcnt(8)
	s_waitcnt lgkmcnt(0)
	s_setprio 1
	s_barrier
	v_mfma_f32_16x16x32_bf16 v[46:49], v[138:141], v[170:173], v[46:49]
	v_mfma_f32_16x16x32_bf16 v[42:45], v[146:149], v[170:173], v[42:45]
	v_mfma_f32_16x16x32_bf16 v[38:41], v[138:141], v[182:185], v[38:41]
	v_mfma_f32_16x16x32_bf16 v[34:37], v[146:149], v[182:185], v[34:37]
	v_mfma_f32_16x16x32_bf16 v[30:33], v[138:141], v[200:203], v[30:33]
	v_mfma_f32_16x16x32_bf16 v[26:29], v[146:149], v[200:203], v[26:29]
	v_mfma_f32_16x16x32_bf16 v[22:25], v[138:141], v[208:211], v[22:25]
	v_mfma_f32_16x16x32_bf16 v[18:21], v[146:149], v[208:211], v[18:21]
	v_mfma_f32_16x16x32_bf16 v[46:49], v[142:145], v[178:181], v[46:49]
	v_mfma_f32_16x16x32_bf16 v[42:45], v[150:153], v[178:181], v[42:45]
	v_mfma_f32_16x16x32_bf16 v[38:41], v[142:145], v[186:189], v[38:41]
	v_mfma_f32_16x16x32_bf16 v[34:37], v[150:153], v[186:189], v[34:37]
	v_mfma_f32_16x16x32_bf16 v[30:33], v[142:145], v[204:207], v[30:33]
	v_mfma_f32_16x16x32_bf16 v[26:29], v[150:153], v[204:207], v[26:29]
	v_mfma_f32_16x16x32_bf16 v[22:25], v[142:145], v[212:215], v[22:25]
	v_mfma_f32_16x16x32_bf16 v[18:21], v[150:153], v[212:215], v[18:21]
	s_setprio 0
	s_setprio 1
	v_mfma_f32_16x16x32_bf16 v[14:17], v[154:157], v[170:173], v[14:17]
	v_mfma_f32_16x16x32_bf16 v[10:13], v[162:165], v[170:173], v[10:13]
	v_mfma_f32_16x16x32_bf16 v[6:9], v[154:157], v[182:185], v[6:9]
	v_mfma_f32_16x16x32_bf16 v[2:5], v[162:165], v[182:185], v[2:5]
	v_mfma_f32_16x16x32_bf16 v[86:89], v[154:157], v[200:203], v[86:89]
	v_mfma_f32_16x16x32_bf16 v[94:97], v[162:165], v[200:203], v[94:97]
	v_mfma_f32_16x16x32_bf16 v[102:105], v[154:157], v[208:211], v[102:105]
	v_mfma_f32_16x16x32_bf16 v[110:113], v[162:165], v[208:211], v[110:113]
	v_mfma_f32_16x16x32_bf16 v[14:17], v[158:161], v[178:181], v[14:17]
	v_mfma_f32_16x16x32_bf16 v[10:13], v[166:169], v[178:181], v[10:13]
	v_mfma_f32_16x16x32_bf16 v[6:9], v[158:161], v[186:189], v[6:9]
	v_mfma_f32_16x16x32_bf16 v[2:5], v[166:169], v[186:189], v[2:5]
	v_mfma_f32_16x16x32_bf16 v[86:89], v[158:161], v[204:207], v[86:89]
	v_mfma_f32_16x16x32_bf16 v[94:97], v[166:169], v[204:207], v[94:97]
	v_mfma_f32_16x16x32_bf16 v[102:105], v[158:161], v[212:215], v[102:105]
	v_mfma_f32_16x16x32_bf16 v[110:113], v[166:169], v[212:215], v[110:113]
	s_setprio 0
	s_barrier
	s_add_u32 s38, s38, 0x100
	s_addc_u32 s39, s39, 0
	s_cmp_ge_u32 s72, s0
	s_cbranch_scc0 .LBB0_369
	s_and_b64 vcc, exec, s[12:13]
	s_cbranch_vccz .LBB0_372
	s_barrier

; #define PG8_STAGE(bufoff, gbase, VO) do { _Pragma("unroll") for (int _i = 0; _i < 2; ++_i) \
;         __builtin_amdgcn_global_load_lds((const unsigned*)((const char*)(gbase) + VO[_i]), (LAS unsigned*)(lds + (bufoff) + ldsw + _i * 8192), 16, 0, 0); } while (0)
; #define PG8_LDA(dst, b, h) do { _Pragma("unroll") for (int m = 0; m < 4; ++m) _Pragma("unroll") for (int k = 0; k < 2; ++k) dst[m][k] = *(const LAS bf16x8*)(lds + PG8_SA(b, h) + aoff + m * 2048 + k * 1024); } while (0)
; #define PG8_LDB(dst, b, h) do { _Pragma("unroll") for (int n = 0; n < 2; ++n) _Pragma("unroll") for (int k = 0; k < 2; ++k) dst[n][k] = *(const LAS bf16x8*)(lds + PG8_SB(b, h) + boff + n * 2048 + k * 1024); } while (0)
; #define PG8_MMA(ai, bj, At, Bt) do { __builtin_amdgcn_s_setprio(1); _Pragma("unroll") for (int m = 0; m < 4; ++m) _Pragma("unroll") for (int n = 0; n < 2; ++n) _Pragma("unroll") for (int k = 0; k < 2; ++k) \
;         acc[ai][bj][m][n] = __builtin_amdgcn_mfma_f32_16x16x32_bf16(Bt[n][k], At[m][k], acc[ai][bj][m][n], 0, 0, 0); __builtin_amdgcn_s_setprio(0); } while (0)
; #define PG8_WAIT_V(n) asm volatile("s_waitcnt vmcnt(" #n ")" ::: "memory")
; #define PG8_WAIT_L(n) asm volatile("s_waitcnt lgkmcnt(" #n ")" ::: "memory")
; template <int NSEG, class Epi, bool ALIGN_EPI = PG8_ALIGN, bool SP2 = PG8_SP2>
; DI void gemm_phase(LAS unsigned char* lds, const Gemm g, const StaticOrder& S, const Epi& E) {
;     ...
;         for (int t = 0; t < nt; t += 2) {
;             const bool last = (t == nt - 2);
;             const char* a1 = cA + (size_t)(t + 1) * kstep;
;             const char* a2 = last ? nA : cA + (size_t)(t + 2) * kstep; const char* b2 = last ? nB : cB + (size_t)(t + 2) * kstep;
;             const char* a3 = a2 + kstep; const char* b3 = b2 + kstep;
;             unsigned v2[2]; v2[0] = (NSEG > 1 && last) ? voffN[0] : voffC[0]; v2[1] = (NSEG > 1 && last) ? voffN[1] : voffC[1];
;             const size_t h2 = (NSEG > 1 && last) ? hstepN : hstepC;
;             if constexpr (SP2) {
;             PG8_LDB(B0, 0, 0); PG8_LDB(B1, 0, 1); PG8_SCHED; PG8_LDA(At, 0, 0); PG8_STAGE(PG8_SA(1, 1), a1 + hstepC, voffC);
;             PG8_WAIT_V(8); PG8_WAIT_L(0); PG8_BAR; PG8_MMA(0, 0, At, B0); PG8_MMA(0, 1, At, B1); PG8_BAR; PG8_SCHED;
;             PG8_LDA(At, 0, 1); PG8_STAGE(PG8_SB(0, 0), b2, v2); PG8_STAGE(PG8_SB(0, 1), b2 + h2, v2); PG8_STAGE(PG8_SA(0, 0), a2, v2);
.LBB0_427:
	ds_read_b128 v[148:151], v145
	ds_read_b128 v[152:155], v145 offset:1024
	ds_read_b128 v[156:159], v145 offset:2048
	ds_read_b128 v[160:163], v145 offset:3072
	ds_read_b128 v[164:167], v146
	ds_read_b128 v[168:171], v146 offset:1024
	ds_read_b128 v[172:175], v146 offset:2048
	ds_read_b128 v[176:179], v146 offset:3072
	s_add_u32 s38, s36, 0xfff80080
	s_addc_u32 s39, s37, -1
	s_cmp_eq_u32 s61, 28
	s_cselect_b32 s41, s5, s39
	s_cselect_b32 s40, s4, s38
	s_cselect_b32 s39, s35, s27
	s_cselect_b32 s38, s34, s25
	v_lshl_add_u64 v[212:213], s[36:37], 0, v[134:135]
	s_add_i32 m0, s23, 0xc000
	ds_read_b128 v[180:183], v147
	ds_read_b128 v[184:187], v147 offset:1024
	ds_read_b128 v[188:191], v147 offset:2048
	ds_read_b128 v[192:195], v147 offset:3072
	ds_read_b128 v[196:199], v147 offset:4096
	ds_read_b128 v[200:203], v147 offset:5120
	ds_read_b128 v[204:207], v147 offset:6144
	ds_read_b128 v[208:211], v147 offset:7168
	global_load_lds_dwordx4 v[212:213], off
	v_lshl_add_u64 v[212:213], s[36:37], 0, v[136:137]
	s_add_i32 m0, s23, 0xe000
	s_nop 0
	global_load_lds_dwordx4 v[212:213], off
	s_waitcnt vmcnt(8)
	s_waitcnt lgkmcnt(0)
	s_setprio 1
	s_barrier
	v_mfma_f32_16x16x32_bf16 v[126:129], v[148:151], v[180:183], v[126:129]
	v_mfma_f32_16x16x32_bf16 v[122:125], v[156:159], v[180:183], v[122:125]
	v_mfma_f32_16x16x32_bf16 v[118:121], v[148:151], v[188:191], v[118:121]
	v_mfma_f32_16x16x32_bf16 v[114:117], v[156:159], v[188:191], v[114:117]
	v_mfma_f32_16x16x32_bf16 v[102:105], v[148:151], v[196:199], v[102:105]
	v_mfma_f32_16x16x32_bf16 v[98:101], v[156:159], v[196:199], v[98:101]
	v_mfma_f32_16x16x32_bf16 v[86:89], v[148:151], v[204:207], v[86:89]
	v_mfma_f32_16x16x32_bf16 v[82:85], v[156:159], v[204:207], v[82:85]
	v_mfma_f32_16x16x32_bf16 v[126:129], v[152:155], v[184:187], v[126:129]
	v_mfma_f32_16x16x32_bf16 v[122:125], v[160:163], v[184:187], v[122:125]
	v_mfma_f32_16x16x32_bf16 v[118:121], v[152:155], v[192:195], v[118:121]
	v_mfma_f32_16x16x32_bf16 v[114:117], v[160:163], v[192:195], v[114:117]
	v_mfma_f32_16x16x32_bf16 v[102:105], v[152:155], v[200:203], v[102:105]
	v_mfma_f32_16x16x32_bf16 v[98:101], v[160:163], v[200:203], v[98:101]
	v_mfma_f32_16x16x32_bf16 v[86:89], v[152:155], v[208:211], v[86:89]
	v_mfma_f32_16x16x32_bf16 v[82:85], v[160:163], v[208:211], v[82:85]
	s_setprio 0
	s_setprio 1
	v_mfma_f32_16x16x32_bf16 v[110:113], v[164:167], v[180:183], v[110:113]
	v_mfma_f32_16x16x32_bf16 v[106:109], v[172:175], v[180:183], v[106:109]
	v_mfma_f32_16x16x32_bf16 v[94:97], v[164:167], v[188:191], v[94:97]
	v_mfma_f32_16x16x32_bf16 v[90:93], v[172:175], v[188:191], v[90:93]
	v_mfma_f32_16x16x32_bf16 v[78:81], v[164:167], v[196:199], v[78:81]
	v_mfma_f32_16x16x32_bf16 v[74:77], v[172:175], v[196:199], v[74:77]
	v_mfma_f32_16x16x32_bf16 v[70:73], v[164:167], v[204:207], v[70:73]
	v_mfma_f32_16x16x32_bf16 v[66:69], v[172:175], v[204:207], v[66:69]
	v_mfma_f32_16x16x32_bf16 v[110:113], v[168:171], v[184:187], v[110:113]
	v_mfma_f32_16x16x32_bf16 v[106:109], v[176:179], v[184:187], v[106:109]
	v_mfma_f32_16x16x32_bf16 v[94:97], v[168:171], v[192:195], v[94:97]
	v_mfma_f32_16x16x32_bf16 v[90:93], v[176:179], v[192:195], v[90:93]
	v_mfma_f32_16x16x32_bf16 v[78:81], v[168:171], v[200:203], v[78:81]
	v_mfma_f32_16x16x32_bf16 v[74:77], v[176:179], v[200:203], v[74:77]
	v_mfma_f32_16x16x32_bf16 v[70:73], v[168:171], v[208:211], v[70:73]
	v_mfma_f32_16x16x32_bf16 v[66:69], v[176:179], v[208:211], v[66:69]
	s_setprio 0
	s_barrier
	s_add_i32 s62, s55, s47
	v_lshl_add_u64 v[212:213], s[38:39], 0, v[130:131]
	s_mov_b32 m0, s62
	ds_read_b128 v[180:183], v147 offset:16384
	ds_read_b128 v[184:187], v147 offset:17408
	ds_read_b128 v[188:191], v147 offset:18432
	ds_read_b128 v[192:195], v147 offset:19456
	ds_read_b128 v[196:199], v147 offset:20480
	ds_read_b128 v[200:203], v147 offset:21504
	ds_read_b128 v[204:207], v147 offset:22528
	ds_read_b128 v[208:211], v147 offset:23552
	global_load_lds_dwordx4 v[212:213], off
	s_add_i32 m0, s62, 0x2000
	s_add_u32 s62, s38, 0x80000
	v_lshl_add_u64 v[214:215], s[38:39], 0, v[132:133]
	s_addc_u32 s63, s39, 0
	s_add_i32 s64, s56, s47
	global_load_lds_dwordx4 v[214:215], off
	v_lshl_add_u64 v[216:217], s[62:63], 0, v[130:131]
	s_mov_b32 m0, s64
	v_lshl_add_u64 v[218:219], s[40:41], 0, v[132:133]
	global_load_lds_dwordx4 v[216:217], off
	v_lshl_add_u64 v[216:217], s[62:63], 0, v[132:133]
	s_add_i32 m0, s64, 0x2000
	s_nop 0
	global_load_lds_dwordx4 v[216:217], off
	v_lshl_add_u64 v[216:217], s[40:41], 0, v[130:131]
	s_mov_b32 m0, s23
	s_nop 0
	global_load_lds_dwordx4 v[216:217], off
	s_mov_b32 m0, s48
	s_nop 0
	global_load_lds_dwordx4 v[218:219], off
	s_waitcnt vmcnt(8)
	s_waitcnt lgkmcnt(0)
	s_setprio 1
	s_barrier
; #define PG8_STAGE(bufoff, gbase, VO) do { _Pragma("unroll") for (int _i = 0; _i < 2; ++_i) \
;         __builtin_amdgcn_global_load_lds((const unsigned*)((const char*)(gbase) + VO[_i]), (LAS unsigned*)(lds + (bufoff) + ldsw + _i * 8192), 16, 0, 0); } while (0)
; #define PG8_LDA(dst, b, h) do { _Pragma("unroll") for (int m = 0; m < 4; ++m) _Pragma("unroll") for (int k = 0; k < 2; ++k) dst[m][k] = *(const LAS bf16x8*)(lds + PG8_SA(b, h) + aoff + m * 2048 + k * 1024); } while (0)
; #define PG8_LDB(dst, b, h) do { _Pragma("unroll") for (int n = 0; n < 2; ++n) _Pragma("unroll") for (int k = 0; k < 2; ++k) dst[n][k] = *(const LAS bf16x8*)(lds + PG8_SB(b, h) + boff + n * 2048 + k * 1024); } while (0)
; #define PG8_MMA(ai, bj, At, Bt) do { __builtin_amdgcn_s_setprio(1); _Pragma("unroll") for (int m = 0; m < 4; ++m) _Pragma("unroll") for (int n = 0; n < 2; ++n) _Pragma("unroll") for (int k = 0; k < 2; ++k) \
;         acc[ai][bj][m][n] = __builtin_amdgcn_mfma_f32_16x16x32_bf16(Bt[n][k], At[m][k], acc[ai][bj][m][n], 0, 0, 0); __builtin_amdgcn_s_setprio(0); } while (0)
; #define PG8_WAIT_V(n) asm volatile("s_waitcnt vmcnt(" #n ")" ::: "memory")
; #define PG8_WAIT_L(n) asm volatile("s_waitcnt lgkmcnt(" #n ")" ::: "memory")
; #define PG8_BAR __builtin_amdgcn_s_barrier()
; #define PG8_SCHED __builtin_amdgcn_sched_barrier(0)
; template <int NSEG, class Epi, bool ALIGN_EPI = PG8_ALIGN, bool SP2 = PG8_SP2>
; DI void gemm_phase(LAS unsigned char* lds, const Gemm g, const StaticOrder& S, const Epi& E) {
;     ...
;             PG8_LDA(At, 0, 1); PG8_STAGE(PG8_SB(0, 0), b2, v2); PG8_STAGE(PG8_SB(0, 1), b2 + h2, v2); PG8_STAGE(PG8_SA(0, 0), a2, v2);
;             PG8_WAIT_V(8); PG8_WAIT_L(0); PG8_BAR; PG8_MMA(1, 0, At, B0); PG8_MMA(1, 1, At, B1); PG8_BAR; PG8_SCHED;
;             PG8_LDB(B0, 1, 0); PG8_LDB(B1, 1, 1); PG8_SCHED; PG8_LDA(At, 1, 0); PG8_STAGE(PG8_SA(0, 1), a2 + h2, v2);
;             PG8_WAIT_V(8); PG8_WAIT_L(0); PG8_BAR; PG8_MMA(0, 0, At, B0); PG8_MMA(0, 1, At, B1); PG8_BAR; PG8_SCHED;
	v_mfma_f32_16x16x32_bf16 v[54:57], v[148:151], v[180:183], v[54:57]
	v_mfma_f32_16x16x32_bf16 v[46:49], v[156:159], v[180:183], v[46:49]
	v_mfma_f32_16x16x32_bf16 v[38:41], v[148:151], v[188:191], v[38:41]
	v_mfma_f32_16x16x32_bf16 v[34:37], v[156:159], v[188:191], v[34:37]
	v_mfma_f32_16x16x32_bf16 v[22:25], v[148:151], v[196:199], v[22:25]
	v_mfma_f32_16x16x32_bf16 v[18:21], v[156:159], v[196:199], v[18:21]
	v_mfma_f32_16x16x32_bf16 v[6:9], v[148:151], v[204:207], v[6:9]
	v_mfma_f32_16x16x32_bf16 v[2:5], v[156:159], v[204:207], v[2:5]
	v_mfma_f32_16x16x32_bf16 v[54:57], v[152:155], v[184:187], v[54:57]
	v_mfma_f32_16x16x32_bf16 v[46:49], v[160:163], v[184:187], v[46:49]
	v_mfma_f32_16x16x32_bf16 v[38:41], v[152:155], v[192:195], v[38:41]
	v_mfma_f32_16x16x32_bf16 v[34:37], v[160:163], v[192:195], v[34:37]
	v_mfma_f32_16x16x32_bf16 v[22:25], v[152:155], v[200:203], v[22:25]
	v_mfma_f32_16x16x32_bf16 v[18:21], v[160:163], v[200:203], v[18:21]
	v_mfma_f32_16x16x32_bf16 v[6:9], v[152:155], v[208:211], v[6:9]
	v_mfma_f32_16x16x32_bf16 v[2:5], v[160:163], v[208:211], v[2:5]
	s_setprio 0
	s_setprio 1
	v_mfma_f32_16x16x32_bf16 v[30:33], v[164:167], v[180:183], v[30:33]
	v_mfma_f32_16x16x32_bf16 v[26:29], v[172:175], v[180:183], v[26:29]
	v_mfma_f32_16x16x32_bf16 v[14:17], v[164:167], v[188:191], v[14:17]
	v_mfma_f32_16x16x32_bf16 v[10:13], v[172:175], v[188:191], v[10:13]
	v_mfma_f32_16x16x32_bf16 v[58:61], v[164:167], v[196:199], v[58:61]
	v_mfma_f32_16x16x32_bf16 v[62:65], v[172:175], v[196:199], v[62:65]
	v_mfma_f32_16x16x32_bf16 v[42:45], v[164:167], v[204:207], v[42:45]
	v_mfma_f32_16x16x32_bf16 v[50:53], v[172:175], v[204:207], v[50:53]
	v_mfma_f32_16x16x32_bf16 v[30:33], v[168:171], v[184:187], v[30:33]
	v_mfma_f32_16x16x32_bf16 v[26:29], v[176:179], v[184:187], v[26:29]
	v_mfma_f32_16x16x32_bf16 v[14:17], v[168:171], v[192:195], v[14:17]
	v_mfma_f32_16x16x32_bf16 v[10:13], v[176:179], v[192:195], v[10:13]
	v_mfma_f32_16x16x32_bf16 v[58:61], v[168:171], v[200:203], v[58:61]
	v_mfma_f32_16x16x32_bf16 v[62:65], v[176:179], v[200:203], v[62:65]
	v_mfma_f32_16x16x32_bf16 v[42:45], v[168:171], v[208:211], v[42:45]
	v_mfma_f32_16x16x32_bf16 v[50:53], v[176:179], v[208:211], v[50:53]
	s_setprio 0
	s_barrier
	s_add_i32 s62, 0, 0x18000
	s_add_i32 s63, 0, 0x1c000
	v_add_u32_e32 v160, s62, v143
	v_add_u32_e32 v176, s63, v143
	ds_read_b128 v[148:151], v160
	ds_read_b128 v[152:155], v160 offset:1024
	ds_read_b128 v[156:159], v160 offset:2048
	ds_read_b128 v[160:163], v160 offset:3072
	ds_read_b128 v[164:167], v176
	ds_read_b128 v[168:171], v176 offset:1024
	ds_read_b128 v[172:175], v176 offset:2048
	ds_read_b128 v[176:179], v176 offset:3072
	s_add_u32 s40, s40, 0x80000
	s_addc_u32 s41, s41, 0
	s_mov_b32 m0, s49
	v_lshl_add_u64 v[220:221], s[40:41], 0, v[130:131]
	ds_read_b128 v[180:183], v147 offset:32768
	ds_read_b128 v[184:187], v147 offset:33792
	ds_read_b128 v[188:191], v147 offset:34816
	ds_read_b128 v[192:195], v147 offset:35840
	ds_read_b128 v[196:199], v147 offset:36864
	ds_read_b128 v[200:203], v147 offset:37888
	ds_read_b128 v[204:207], v147 offset:38912
	ds_read_b128 v[208:211], v147 offset:39936
	global_load_lds_dwordx4 v[220:221], off
	v_lshl_add_u64 v[220:221], s[40:41], 0, v[132:133]
	s_mov_b32 m0, s50
	s_nop 0
	global_load_lds_dwordx4 v[220:221], off
	s_waitcnt vmcnt(8)
	s_waitcnt lgkmcnt(0)
	s_setprio 1
	s_barrier
	v_mfma_f32_16x16x32_bf16 v[126:129], v[148:151], v[180:183], v[126:129]
	v_mfma_f32_16x16x32_bf16 v[122:125], v[156:159], v[180:183], v[122:125]
	v_mfma_f32_16x16x32_bf16 v[118:121], v[148:151], v[188:191], v[118:121]
	v_mfma_f32_16x16x32_bf16 v[114:117], v[156:159], v[188:191], v[114:117]
	v_mfma_f32_16x16x32_bf16 v[102:105], v[148:151], v[196:199], v[102:105]
	v_mfma_f32_16x16x32_bf16 v[98:101], v[156:159], v[196:199], v[98:101]
	v_mfma_f32_16x16x32_bf16 v[86:89], v[148:151], v[204:207], v[86:89]
	v_mfma_f32_16x16x32_bf16 v[82:85], v[156:159], v[204:207], v[82:85]
	v_mfma_f32_16x16x32_bf16 v[126:129], v[152:155], v[184:187], v[126:129]
	v_mfma_f32_16x16x32_bf16 v[122:125], v[160:163], v[184:187], v[122:125]
	v_mfma_f32_16x16x32_bf16 v[118:121], v[152:155], v[192:195], v[118:121]
	v_mfma_f32_16x16x32_bf16 v[114:117], v[160:163], v[192:195], v[114:117]
	v_mfma_f32_16x16x32_bf16 v[102:105], v[152:155], v[200:203], v[102:105]
	v_mfma_f32_16x16x32_bf16 v[98:101], v[160:163], v[200:203], v[98:101]
	v_mfma_f32_16x16x32_bf16 v[86:89], v[152:155], v[208:211], v[86:89]
	v_mfma_f32_16x16x32_bf16 v[82:85], v[160:163], v[208:211], v[82:85]
	s_setprio 0
	s_setprio 1
	v_mfma_f32_16x16x32_bf16 v[110:113], v[164:167], v[180:183], v[110:113]
	v_mfma_f32_16x16x32_bf16 v[106:109], v[172:175], v[180:183], v[106:109]
	v_mfma_f32_16x16x32_bf16 v[94:97], v[164:167], v[188:191], v[94:97]
	v_mfma_f32_16x16x32_bf16 v[90:93], v[172:175], v[188:191], v[90:93]
	v_mfma_f32_16x16x32_bf16 v[78:81], v[164:167], v[196:199], v[78:81]
	v_mfma_f32_16x16x32_bf16 v[74:77], v[172:175], v[196:199], v[74:77]
	v_mfma_f32_16x16x32_bf16 v[70:73], v[164:167], v[204:207], v[70:73]
	v_mfma_f32_16x16x32_bf16 v[66:69], v[172:175], v[204:207], v[66:69]
	v_mfma_f32_16x16x32_bf16 v[110:113], v[168:171], v[184:187], v[110:113]
	v_mfma_f32_16x16x32_bf16 v[106:109], v[176:179], v[184:187], v[106:109]
	v_mfma_f32_16x16x32_bf16 v[94:97], v[168:171], v[192:195], v[94:97]
	v_mfma_f32_16x16x32_bf16 v[90:93], v[176:179], v[192:195], v[90:93]
	v_mfma_f32_16x16x32_bf16 v[78:81], v[168:171], v[200:203], v[78:81]
	v_mfma_f32_16x16x32_bf16 v[74:77], v[176:179], v[200:203], v[74:77]
	v_mfma_f32_16x16x32_bf16 v[70:73], v[168:171], v[208:211], v[70:73]
	v_mfma_f32_16x16x32_bf16 v[66:69], v[176:179], v[208:211], v[66:69]
	s_setprio 0
	s_barrier
; #define PG8_STAGE(bufoff, gbase, VO) do { _Pragma("unroll") for (int _i = 0; _i < 2; ++_i) \
;         __builtin_amdgcn_global_load_lds((const unsigned*)((const char*)(gbase) + VO[_i]), (LAS unsigned*)(lds + (bufoff) + ldsw + _i * 8192), 16, 0, 0); } while (0)
; #define PG8_LDA(dst, b, h) do { _Pragma("unroll") for (int m = 0; m < 4; ++m) _Pragma("unroll") for (int k = 0; k < 2; ++k) dst[m][k] = *(const LAS bf16x8*)(lds + PG8_SA(b, h) + aoff + m * 2048 + k * 1024); } while (0)
; #define PG8_MMA(ai, bj, At, Bt) do { __builtin_amdgcn_s_setprio(1); _Pragma("unroll") for (int m = 0; m < 4; ++m) _Pragma("unroll") for (int n = 0; n < 2; ++n) _Pragma("unroll") for (int k = 0; k < 2; ++k) \
;         acc[ai][bj][m][n] = __builtin_amdgcn_mfma_f32_16x16x32_bf16(Bt[n][k], At[m][k], acc[ai][bj][m][n], 0, 0, 0); __builtin_amdgcn_s_setprio(0); } while (0)
; #define PG8_WAIT_V(n) asm volatile("s_waitcnt vmcnt(" #n ")" ::: "memory")
; #define PG8_WAIT_L(n) asm volatile("s_waitcnt lgkmcnt(" #n ")" ::: "memory")
; #define PG8_BAR __builtin_amdgcn_s_barrier()
; #define PG8_SCHED __builtin_amdgcn_sched_barrier(0)
; template <int NSEG, class Epi, bool ALIGN_EPI = PG8_ALIGN, bool SP2 = PG8_SP2>
; DI void gemm_phase(LAS unsigned char* lds, const Gemm g, const StaticOrder& S, const Epi& E) {
;     ...
;             PG8_LDA(At, 1, 1); PG8_STAGE(PG8_SB(1, 0), b3, v2); PG8_STAGE(PG8_SB(1, 1), b3 + h2, v2); PG8_STAGE(PG8_SA(1, 0), a3, v2);
;             PG8_WAIT_V(8); PG8_WAIT_L(0); PG8_BAR; PG8_MMA(1, 0, At, B0); PG8_MMA(1, 1, At, B1); PG8_BAR; PG8_SCHED;
	s_add_i32 s40, s62, s47
	v_lshl_add_u64 v[212:213], v[212:213], 0, s[12:13]
	s_mov_b32 m0, s40
	ds_read_b128 v[180:183], v147 offset:49152
	ds_read_b128 v[184:187], v147 offset:50176
	ds_read_b128 v[188:191], v147 offset:51200
	ds_read_b128 v[192:195], v147 offset:52224
	ds_read_b128 v[196:199], v147 offset:53248
	ds_read_b128 v[200:203], v147 offset:54272
	ds_read_b128 v[204:207], v147 offset:55296
	ds_read_b128 v[208:211], v147 offset:56320
	global_load_lds_dwordx4 v[212:213], off
	s_add_i32 m0, s40, 0x2000
	s_add_u32 s38, s38, 0x80080
	v_lshl_add_u64 v[212:213], v[214:215], 0, s[12:13]
	s_addc_u32 s39, s39, 0
	s_add_i32 s40, s63, s47
	global_load_lds_dwordx4 v[212:213], off
	v_lshl_add_u64 v[212:213], s[38:39], 0, v[130:131]
	s_mov_b32 m0, s40
	s_nop 0
	global_load_lds_dwordx4 v[212:213], off
	v_lshl_add_u64 v[212:213], s[38:39], 0, v[132:133]
	s_add_i32 m0, s40, 0x2000
	s_nop 0
	global_load_lds_dwordx4 v[212:213], off
	v_lshl_add_u64 v[212:213], v[216:217], 0, s[12:13]
	s_mov_b32 m0, s53
	s_nop 0
	global_load_lds_dwordx4 v[212:213], off
	v_lshl_add_u64 v[212:213], v[218:219], 0, s[12:13]
	s_mov_b32 m0, s54
	s_nop 0
	global_load_lds_dwordx4 v[212:213], off
	s_waitcnt vmcnt(8)
	s_waitcnt lgkmcnt(0)
	s_setprio 1
	s_barrier
	v_mfma_f32_16x16x32_bf16 v[54:57], v[148:151], v[180:183], v[54:57]
	v_mfma_f32_16x16x32_bf16 v[46:49], v[156:159], v[180:183], v[46:49]
	v_mfma_f32_16x16x32_bf16 v[38:41], v[148:151], v[188:191], v[38:41]
	v_mfma_f32_16x16x32_bf16 v[34:37], v[156:159], v[188:191], v[34:37]
	v_mfma_f32_16x16x32_bf16 v[22:25], v[148:151], v[196:199], v[22:25]
	v_mfma_f32_16x16x32_bf16 v[18:21], v[156:159], v[196:199], v[18:21]
	v_mfma_f32_16x16x32_bf16 v[6:9], v[148:151], v[204:207], v[6:9]
	v_mfma_f32_16x16x32_bf16 v[2:5], v[156:159], v[204:207], v[2:5]
	v_mfma_f32_16x16x32_bf16 v[54:57], v[152:155], v[184:187], v[54:57]
	v_mfma_f32_16x16x32_bf16 v[46:49], v[160:163], v[184:187], v[46:49]
	v_mfma_f32_16x16x32_bf16 v[38:41], v[152:155], v[192:195], v[38:41]
	v_mfma_f32_16x16x32_bf16 v[34:37], v[160:163], v[192:195], v[34:37]
	v_mfma_f32_16x16x32_bf16 v[22:25], v[152:155], v[200:203], v[22:25]
	v_mfma_f32_16x16x32_bf16 v[18:21], v[160:163], v[200:203], v[18:21]
	v_mfma_f32_16x16x32_bf16 v[6:9], v[152:155], v[208:211], v[6:9]
	v_mfma_f32_16x16x32_bf16 v[2:5], v[160:163], v[208:211], v[2:5]
	s_setprio 0
	s_setprio 1
	v_mfma_f32_16x16x32_bf16 v[30:33], v[164:167], v[180:183], v[30:33]
	v_mfma_f32_16x16x32_bf16 v[26:29], v[172:175], v[180:183], v[26:29]
	v_mfma_f32_16x16x32_bf16 v[14:17], v[164:167], v[188:191], v[14:17]
	v_mfma_f32_16x16x32_bf16 v[10:13], v[172:175], v[188:191], v[10:13]
	v_mfma_f32_16x16x32_bf16 v[58:61], v[164:167], v[196:199], v[58:61]
	v_mfma_f32_16x16x32_bf16 v[62:65], v[172:175], v[196:199], v[62:65]
	v_mfma_f32_16x16x32_bf16 v[42:45], v[164:167], v[204:207], v[42:45]
	v_mfma_f32_16x16x32_bf16 v[50:53], v[172:175], v[204:207], v[50:53]
	v_mfma_f32_16x16x32_bf16 v[30:33], v[168:171], v[184:187], v[30:33]
	v_mfma_f32_16x16x32_bf16 v[26:29], v[176:179], v[184:187], v[26:29]
	v_mfma_f32_16x16x32_bf16 v[14:17], v[168:171], v[192:195], v[14:17]
	v_mfma_f32_16x16x32_bf16 v[10:13], v[176:179], v[192:195], v[10:13]
	v_mfma_f32_16x16x32_bf16 v[58:61], v[168:171], v[200:203], v[58:61]
	v_mfma_f32_16x16x32_bf16 v[62:65], v[176:179], v[200:203], v[62:65]
	v_mfma_f32_16x16x32_bf16 v[42:45], v[168:171], v[208:211], v[42:45]
	v_mfma_f32_16x16x32_bf16 v[50:53], v[176:179], v[208:211], v[50:53]
	s_setprio 0
	s_barrier
	s_add_i32 s61, s61, 2
	s_add_u32 s36, s36, 0x100
	s_addc_u32 s37, s37, 0
	s_add_u32 s25, s25, 0x100
	s_addc_u32 s27, s27, 0
	s_cmp_gt_u32 s61, 29
	s_cbranch_scc0 .LBB0_427
	s_and_b64 vcc, exec, s[14:15]
	s_cbranch_vccz .LBB0_430
	s_barrier

; #define PG8_STAGE(bufoff, gbase, VO) do { _Pragma("unroll") for (int _i = 0; _i < 2; ++_i) \
;         __builtin_amdgcn_global_load_lds((const unsigned*)((const char*)(gbase) + VO[_i]), (LAS unsigned*)(lds + (bufoff) + ldsw + _i * 8192), 16, 0, 0); } while (0)
; #define PG8_LDA(dst, b, h) do { _Pragma("unroll") for (int m = 0; m < 4; ++m) _Pragma("unroll") for (int k = 0; k < 2; ++k) dst[m][k] = *(const LAS bf16x8*)(lds + PG8_SA(b, h) + aoff + m * 2048 + k * 1024); } while (0)
; #define PG8_LDB(dst, b, h) do { _Pragma("unroll") for (int n = 0; n < 2; ++n) _Pragma("unroll") for (int k = 0; k < 2; ++k) dst[n][k] = *(const LAS bf16x8*)(lds + PG8_SB(b, h) + boff + n * 2048 + k * 1024); } while (0)
; #define PG8_MMA(ai, bj, At, Bt) do { __builtin_amdgcn_s_setprio(1); _Pragma("unroll") for (int m = 0; m < 4; ++m) _Pragma("unroll") for (int n = 0; n < 2; ++n) _Pragma("unroll") for (int k = 0; k < 2; ++k) \
;         acc[ai][bj][m][n] = __builtin_amdgcn_mfma_f32_16x16x32_bf16(Bt[n][k], At[m][k], acc[ai][bj][m][n], 0, 0, 0); __builtin_amdgcn_s_setprio(0); } while (0)
; #define PG8_WAIT_V(n) asm volatile("s_waitcnt vmcnt(" #n ")" ::: "memory")
; #define PG8_WAIT_L(n) asm volatile("s_waitcnt lgkmcnt(" #n ")" ::: "memory")
; template <int NSEG, class Epi, bool ALIGN_EPI = PG8_ALIGN, bool SP2 = PG8_SP2>
; DI void gemm_phase(LAS unsigned char* lds, const Gemm g, const StaticOrder& S, const Epi& E) {
;     ...
;         for (int t = 0; t < nt; t += 2) {
;             const bool last = (t == nt - 2);
;             const char* a1 = cA + (size_t)(t + 1) * kstep;
;             const char* a2 = last ? nA : cA + (size_t)(t + 2) * kstep; const char* b2 = last ? nB : cB + (size_t)(t + 2) * kstep;
;             const char* a3 = a2 + kstep; const char* b3 = b2 + kstep;
;             unsigned v2[2]; v2[0] = (NSEG > 1 && last) ? voffN[0] : voffC[0]; v2[1] = (NSEG > 1 && last) ? voffN[1] : voffC[1];
;             const size_t h2 = (NSEG > 1 && last) ? hstepN : hstepC;
;             if constexpr (SP2) {
;             PG8_LDB(B0, 0, 0); PG8_LDB(B1, 0, 1); PG8_SCHED; PG8_LDA(At, 0, 0); PG8_STAGE(PG8_SA(1, 1), a1 + hstepC, voffC);
;             PG8_WAIT_V(8); PG8_WAIT_L(0); PG8_BAR; PG8_MMA(0, 0, At, B0); PG8_MMA(0, 1, At, B1); PG8_BAR; PG8_SCHED;
;             PG8_LDA(At, 0, 1); PG8_STAGE(PG8_SB(0, 0), b2, v2); PG8_STAGE(PG8_SB(0, 1), b2 + h2, v2); PG8_STAGE(PG8_SA(0, 0), a2, v2);
.LBB0_501:
	ds_read_b128 v[148:151], v145
	ds_read_b128 v[152:155], v145 offset:1024
	ds_read_b128 v[156:159], v145 offset:2048
	ds_read_b128 v[160:163], v145 offset:3072
	ds_read_b128 v[164:167], v146
	ds_read_b128 v[168:171], v146 offset:1024
	ds_read_b128 v[172:175], v146 offset:2048
	ds_read_b128 v[176:179], v146 offset:3072
	s_add_u32 s24, s22, 0xfff80080
	s_addc_u32 s25, s23, -1
	s_cmp_eq_u32 s52, 28
	s_cselect_b32 s27, s5, s25
	s_cselect_b32 s26, s4, s24
	s_cselect_b32 s25, s21, s19
	s_cselect_b32 s24, s20, s17
	v_lshl_add_u64 v[212:213], s[22:23], 0, v[134:135]
	s_add_i32 m0, s15, 0xc000
	ds_read_b128 v[180:183], v147
	ds_read_b128 v[184:187], v147 offset:1024
	ds_read_b128 v[188:191], v147 offset:2048
	ds_read_b128 v[192:195], v147 offset:3072
	ds_read_b128 v[196:199], v147 offset:4096
	ds_read_b128 v[200:203], v147 offset:5120
	ds_read_b128 v[204:207], v147 offset:6144
	ds_read_b128 v[208:211], v147 offset:7168
	global_load_lds_dwordx4 v[212:213], off
	v_lshl_add_u64 v[212:213], s[22:23], 0, v[136:137]
	s_add_i32 m0, s15, 0xe000
	s_nop 0
	global_load_lds_dwordx4 v[212:213], off
	s_waitcnt vmcnt(8)
	s_waitcnt lgkmcnt(0)
	s_setprio 1
	s_barrier
	v_mfma_f32_16x16x32_bf16 v[126:129], v[148:151], v[180:183], v[126:129]
	v_mfma_f32_16x16x32_bf16 v[122:125], v[156:159], v[180:183], v[122:125]
	v_mfma_f32_16x16x32_bf16 v[118:121], v[148:151], v[188:191], v[118:121]
	v_mfma_f32_16x16x32_bf16 v[114:117], v[156:159], v[188:191], v[114:117]
	v_mfma_f32_16x16x32_bf16 v[102:105], v[148:151], v[196:199], v[102:105]
	v_mfma_f32_16x16x32_bf16 v[98:101], v[156:159], v[196:199], v[98:101]
	v_mfma_f32_16x16x32_bf16 v[86:89], v[148:151], v[204:207], v[86:89]
	v_mfma_f32_16x16x32_bf16 v[82:85], v[156:159], v[204:207], v[82:85]
	v_mfma_f32_16x16x32_bf16 v[126:129], v[152:155], v[184:187], v[126:129]
	v_mfma_f32_16x16x32_bf16 v[122:125], v[160:163], v[184:187], v[122:125]
	v_mfma_f32_16x16x32_bf16 v[118:121], v[152:155], v[192:195], v[118:121]
	v_mfma_f32_16x16x32_bf16 v[114:117], v[160:163], v[192:195], v[114:117]
	v_mfma_f32_16x16x32_bf16 v[102:105], v[152:155], v[200:203], v[102:105]
	v_mfma_f32_16x16x32_bf16 v[98:101], v[160:163], v[200:203], v[98:101]
	v_mfma_f32_16x16x32_bf16 v[86:89], v[152:155], v[208:211], v[86:89]
	v_mfma_f32_16x16x32_bf16 v[82:85], v[160:163], v[208:211], v[82:85]
	s_setprio 0
	s_setprio 1
	v_mfma_f32_16x16x32_bf16 v[110:113], v[164:167], v[180:183], v[110:113]
	v_mfma_f32_16x16x32_bf16 v[106:109], v[172:175], v[180:183], v[106:109]
	v_mfma_f32_16x16x32_bf16 v[94:97], v[164:167], v[188:191], v[94:97]
	v_mfma_f32_16x16x32_bf16 v[90:93], v[172:175], v[188:191], v[90:93]
	v_mfma_f32_16x16x32_bf16 v[78:81], v[164:167], v[196:199], v[78:81]
	v_mfma_f32_16x16x32_bf16 v[74:77], v[172:175], v[196:199], v[74:77]
	v_mfma_f32_16x16x32_bf16 v[70:73], v[164:167], v[204:207], v[70:73]
	v_mfma_f32_16x16x32_bf16 v[58:61], v[172:175], v[204:207], v[58:61]
	v_mfma_f32_16x16x32_bf16 v[110:113], v[168:171], v[184:187], v[110:113]
	v_mfma_f32_16x16x32_bf16 v[106:109], v[176:179], v[184:187], v[106:109]
	v_mfma_f32_16x16x32_bf16 v[94:97], v[168:171], v[192:195], v[94:97]
	v_mfma_f32_16x16x32_bf16 v[90:93], v[176:179], v[192:195], v[90:93]
	v_mfma_f32_16x16x32_bf16 v[78:81], v[168:171], v[200:203], v[78:81]
	v_mfma_f32_16x16x32_bf16 v[74:77], v[176:179], v[200:203], v[74:77]
	v_mfma_f32_16x16x32_bf16 v[70:73], v[168:171], v[208:211], v[70:73]
	v_mfma_f32_16x16x32_bf16 v[58:61], v[176:179], v[208:211], v[58:61]
	s_setprio 0
	s_barrier
	s_add_i32 s53, s48, s38
	v_lshl_add_u64 v[212:213], s[24:25], 0, v[130:131]
	s_mov_b32 m0, s53
	ds_read_b128 v[180:183], v147 offset:16384
	ds_read_b128 v[184:187], v147 offset:17408
	ds_read_b128 v[188:191], v147 offset:18432
	ds_read_b128 v[192:195], v147 offset:19456
	ds_read_b128 v[196:199], v147 offset:20480
	ds_read_b128 v[200:203], v147 offset:21504
	ds_read_b128 v[204:207], v147 offset:22528
	ds_read_b128 v[208:211], v147 offset:23552
	global_load_lds_dwordx4 v[212:213], off
	s_add_i32 m0, s53, 0x2000
	s_add_u32 s54, s24, 0x80000
	v_lshl_add_u64 v[214:215], s[24:25], 0, v[132:133]
	s_addc_u32 s55, s25, 0
	s_add_i32 s53, s49, s38
	global_load_lds_dwordx4 v[214:215], off
	v_lshl_add_u64 v[216:217], s[54:55], 0, v[130:131]
	s_mov_b32 m0, s53
	v_lshl_add_u64 v[218:219], s[26:27], 0, v[132:133]
	global_load_lds_dwordx4 v[216:217], off
	v_lshl_add_u64 v[216:217], s[54:55], 0, v[132:133]
	s_add_i32 m0, s53, 0x2000
	s_nop 0
	global_load_lds_dwordx4 v[216:217], off
	v_lshl_add_u64 v[216:217], s[26:27], 0, v[130:131]
	s_mov_b32 m0, s15
	s_nop 0
	global_load_lds_dwordx4 v[216:217], off
	s_mov_b32 m0, s41
	s_nop 0
	global_load_lds_dwordx4 v[218:219], off
	s_waitcnt vmcnt(8)
	s_waitcnt lgkmcnt(0)
	s_setprio 1
	s_barrier
; #define PG8_STAGE(bufoff, gbase, VO) do { _Pragma("unroll") for (int _i = 0; _i < 2; ++_i) \
;         __builtin_amdgcn_global_load_lds((const unsigned*)((const char*)(gbase) + VO[_i]), (LAS unsigned*)(lds + (bufoff) + ldsw + _i * 8192), 16, 0, 0); } while (0)
; #define PG8_LDA(dst, b, h) do { _Pragma("unroll") for (int m = 0; m < 4; ++m) _Pragma("unroll") for (int k = 0; k < 2; ++k) dst[m][k] = *(const LAS bf16x8*)(lds + PG8_SA(b, h) + aoff + m * 2048 + k * 1024); } while (0)
; #define PG8_LDB(dst, b, h) do { _Pragma("unroll") for (int n = 0; n < 2; ++n) _Pragma("unroll") for (int k = 0; k < 2; ++k) dst[n][k] = *(const LAS bf16x8*)(lds + PG8_SB(b, h) + boff + n * 2048 + k * 1024); } while (0)
; #define PG8_MMA(ai, bj, At, Bt) do { __builtin_amdgcn_s_setprio(1); _Pragma("unroll") for (int m = 0; m < 4; ++m) _Pragma("unroll") for (int n = 0; n < 2; ++n) _Pragma("unroll") for (int k = 0; k < 2; ++k) \
;         acc[ai][bj][m][n] = __builtin_amdgcn_mfma_f32_16x16x32_bf16(Bt[n][k], At[m][k], acc[ai][bj][m][n], 0, 0, 0); __builtin_amdgcn_s_setprio(0); } while (0)
; #define PG8_WAIT_V(n) asm volatile("s_waitcnt vmcnt(" #n ")" ::: "memory")
; #define PG8_WAIT_L(n) asm volatile("s_waitcnt lgkmcnt(" #n ")" ::: "memory")
; #define PG8_BAR __builtin_amdgcn_s_barrier()
; #define PG8_SCHED __builtin_amdgcn_sched_barrier(0)
; template <int NSEG, class Epi, bool ALIGN_EPI = PG8_ALIGN, bool SP2 = PG8_SP2>
; DI void gemm_phase(LAS unsigned char* lds, const Gemm g, const StaticOrder& S, const Epi& E) {
;     ...
;             PG8_LDA(At, 0, 1); PG8_STAGE(PG8_SB(0, 0), b2, v2); PG8_STAGE(PG8_SB(0, 1), b2 + h2, v2); PG8_STAGE(PG8_SA(0, 0), a2, v2);
;             PG8_WAIT_V(8); PG8_WAIT_L(0); PG8_BAR; PG8_MMA(1, 0, At, B0); PG8_MMA(1, 1, At, B1); PG8_BAR; PG8_SCHED;
;             PG8_LDB(B0, 1, 0); PG8_LDB(B1, 1, 1); PG8_SCHED; PG8_LDA(At, 1, 0); PG8_STAGE(PG8_SA(0, 1), a2 + h2, v2);
;             PG8_WAIT_V(8); PG8_WAIT_L(0); PG8_BAR; PG8_MMA(0, 0, At, B0); PG8_MMA(0, 1, At, B1); PG8_BAR; PG8_SCHED;
	v_mfma_f32_16x16x32_bf16 v[46:49], v[148:151], v[180:183], v[46:49]
	v_mfma_f32_16x16x32_bf16 v[42:45], v[156:159], v[180:183], v[42:45]
	v_mfma_f32_16x16x32_bf16 v[38:41], v[148:151], v[188:191], v[38:41]
	v_mfma_f32_16x16x32_bf16 v[34:37], v[156:159], v[188:191], v[34:37]
	v_mfma_f32_16x16x32_bf16 v[22:25], v[148:151], v[196:199], v[22:25]
	v_mfma_f32_16x16x32_bf16 v[18:21], v[156:159], v[196:199], v[18:21]
	v_mfma_f32_16x16x32_bf16 v[6:9], v[148:151], v[204:207], v[6:9]
	v_mfma_f32_16x16x32_bf16 v[2:5], v[156:159], v[204:207], v[2:5]
	v_mfma_f32_16x16x32_bf16 v[46:49], v[152:155], v[184:187], v[46:49]
	v_mfma_f32_16x16x32_bf16 v[42:45], v[160:163], v[184:187], v[42:45]
	v_mfma_f32_16x16x32_bf16 v[38:41], v[152:155], v[192:195], v[38:41]
	v_mfma_f32_16x16x32_bf16 v[34:37], v[160:163], v[192:195], v[34:37]
	v_mfma_f32_16x16x32_bf16 v[22:25], v[152:155], v[200:203], v[22:25]
	v_mfma_f32_16x16x32_bf16 v[18:21], v[160:163], v[200:203], v[18:21]
	v_mfma_f32_16x16x32_bf16 v[6:9], v[152:155], v[208:211], v[6:9]
	v_mfma_f32_16x16x32_bf16 v[2:5], v[160:163], v[208:211], v[2:5]
	s_setprio 0
	s_setprio 1
	v_mfma_f32_16x16x32_bf16 v[30:33], v[164:167], v[180:183], v[30:33]
	v_mfma_f32_16x16x32_bf16 v[26:29], v[172:175], v[180:183], v[26:29]
	v_mfma_f32_16x16x32_bf16 v[14:17], v[164:167], v[188:191], v[14:17]
	v_mfma_f32_16x16x32_bf16 v[10:13], v[172:175], v[188:191], v[10:13]
	v_mfma_f32_16x16x32_bf16 v[62:65], v[164:167], v[196:199], v[62:65]
	v_mfma_f32_16x16x32_bf16 v[66:69], v[172:175], v[196:199], v[66:69]
	v_mfma_f32_16x16x32_bf16 v[50:53], v[164:167], v[204:207], v[50:53]
	v_mfma_f32_16x16x32_bf16 v[54:57], v[172:175], v[204:207], v[54:57]
	v_mfma_f32_16x16x32_bf16 v[30:33], v[168:171], v[184:187], v[30:33]
	v_mfma_f32_16x16x32_bf16 v[26:29], v[176:179], v[184:187], v[26:29]
	v_mfma_f32_16x16x32_bf16 v[14:17], v[168:171], v[192:195], v[14:17]
	v_mfma_f32_16x16x32_bf16 v[10:13], v[176:179], v[192:195], v[10:13]
	v_mfma_f32_16x16x32_bf16 v[62:65], v[168:171], v[200:203], v[62:65]
	v_mfma_f32_16x16x32_bf16 v[66:69], v[176:179], v[200:203], v[66:69]
	v_mfma_f32_16x16x32_bf16 v[50:53], v[168:171], v[208:211], v[50:53]
	v_mfma_f32_16x16x32_bf16 v[54:57], v[176:179], v[208:211], v[54:57]
	s_setprio 0
	s_barrier
	s_add_i32 s53, 0, 0x18000
	s_add_i32 s54, 0, 0x1c000
	v_add_u32_e32 v160, s53, v143
	v_add_u32_e32 v176, s54, v143
	ds_read_b128 v[148:151], v160
	ds_read_b128 v[152:155], v160 offset:1024
	ds_read_b128 v[156:159], v160 offset:2048
	ds_read_b128 v[160:163], v160 offset:3072
	ds_read_b128 v[164:167], v176
	ds_read_b128 v[168:171], v176 offset:1024
	ds_read_b128 v[172:175], v176 offset:2048
	ds_read_b128 v[176:179], v176 offset:3072
	s_add_u32 s26, s26, 0x80000
	s_addc_u32 s27, s27, 0
	s_mov_b32 m0, s42
	v_lshl_add_u64 v[220:221], s[26:27], 0, v[130:131]
	ds_read_b128 v[180:183], v147 offset:32768
	ds_read_b128 v[184:187], v147 offset:33792
	ds_read_b128 v[188:191], v147 offset:34816
	ds_read_b128 v[192:195], v147 offset:35840
	ds_read_b128 v[196:199], v147 offset:36864
	ds_read_b128 v[200:203], v147 offset:37888
	ds_read_b128 v[204:207], v147 offset:38912
	ds_read_b128 v[208:211], v147 offset:39936
	global_load_lds_dwordx4 v[220:221], off
	v_lshl_add_u64 v[220:221], s[26:27], 0, v[132:133]
	s_mov_b32 m0, s43
	s_nop 0
	global_load_lds_dwordx4 v[220:221], off
	s_waitcnt vmcnt(8)
	s_waitcnt lgkmcnt(0)
	s_setprio 1
	s_barrier
	v_mfma_f32_16x16x32_bf16 v[126:129], v[148:151], v[180:183], v[126:129]
	v_mfma_f32_16x16x32_bf16 v[122:125], v[156:159], v[180:183], v[122:125]
	v_mfma_f32_16x16x32_bf16 v[118:121], v[148:151], v[188:191], v[118:121]
	v_mfma_f32_16x16x32_bf16 v[114:117], v[156:159], v[188:191], v[114:117]
	v_mfma_f32_16x16x32_bf16 v[102:105], v[148:151], v[196:199], v[102:105]
	v_mfma_f32_16x16x32_bf16 v[98:101], v[156:159], v[196:199], v[98:101]
	v_mfma_f32_16x16x32_bf16 v[86:89], v[148:151], v[204:207], v[86:89]
	v_mfma_f32_16x16x32_bf16 v[82:85], v[156:159], v[204:207], v[82:85]
	v_mfma_f32_16x16x32_bf16 v[126:129], v[152:155], v[184:187], v[126:129]
	v_mfma_f32_16x16x32_bf16 v[122:125], v[160:163], v[184:187], v[122:125]
	v_mfma_f32_16x16x32_bf16 v[118:121], v[152:155], v[192:195], v[118:121]
	v_mfma_f32_16x16x32_bf16 v[114:117], v[160:163], v[192:195], v[114:117]
	v_mfma_f32_16x16x32_bf16 v[102:105], v[152:155], v[200:203], v[102:105]
	v_mfma_f32_16x16x32_bf16 v[98:101], v[160:163], v[200:203], v[98:101]
	v_mfma_f32_16x16x32_bf16 v[86:89], v[152:155], v[208:211], v[86:89]
	v_mfma_f32_16x16x32_bf16 v[82:85], v[160:163], v[208:211], v[82:85]
	s_setprio 0
	s_setprio 1
	v_mfma_f32_16x16x32_bf16 v[110:113], v[164:167], v[180:183], v[110:113]
	v_mfma_f32_16x16x32_bf16 v[106:109], v[172:175], v[180:183], v[106:109]
	v_mfma_f32_16x16x32_bf16 v[94:97], v[164:167], v[188:191], v[94:97]
	v_mfma_f32_16x16x32_bf16 v[90:93], v[172:175], v[188:191], v[90:93]
	v_mfma_f32_16x16x32_bf16 v[78:81], v[164:167], v[196:199], v[78:81]
	v_mfma_f32_16x16x32_bf16 v[74:77], v[172:175], v[196:199], v[74:77]
	v_mfma_f32_16x16x32_bf16 v[70:73], v[164:167], v[204:207], v[70:73]
	v_mfma_f32_16x16x32_bf16 v[58:61], v[172:175], v[204:207], v[58:61]
	v_mfma_f32_16x16x32_bf16 v[110:113], v[168:171], v[184:187], v[110:113]
	v_mfma_f32_16x16x32_bf16 v[106:109], v[176:179], v[184:187], v[106:109]
	v_mfma_f32_16x16x32_bf16 v[94:97], v[168:171], v[192:195], v[94:97]
	v_mfma_f32_16x16x32_bf16 v[90:93], v[176:179], v[192:195], v[90:93]
	v_mfma_f32_16x16x32_bf16 v[78:81], v[168:171], v[200:203], v[78:81]
	v_mfma_f32_16x16x32_bf16 v[74:77], v[176:179], v[200:203], v[74:77]
	v_mfma_f32_16x16x32_bf16 v[70:73], v[168:171], v[208:211], v[70:73]
	v_mfma_f32_16x16x32_bf16 v[58:61], v[176:179], v[208:211], v[58:61]
	s_setprio 0
	s_barrier
; #define PG8_STAGE(bufoff, gbase, VO) do { _Pragma("unroll") for (int _i = 0; _i < 2; ++_i) \
;         __builtin_amdgcn_global_load_lds((const unsigned*)((const char*)(gbase) + VO[_i]), (LAS unsigned*)(lds + (bufoff) + ldsw + _i * 8192), 16, 0, 0); } while (0)
; #define PG8_LDA(dst, b, h) do { _Pragma("unroll") for (int m = 0; m < 4; ++m) _Pragma("unroll") for (int k = 0; k < 2; ++k) dst[m][k] = *(const LAS bf16x8*)(lds + PG8_SA(b, h) + aoff + m * 2048 + k * 1024); } while (0)
; #define PG8_MMA(ai, bj, At, Bt) do { __builtin_amdgcn_s_setprio(1); _Pragma("unroll") for (int m = 0; m < 4; ++m) _Pragma("unroll") for (int n = 0; n < 2; ++n) _Pragma("unroll") for (int k = 0; k < 2; ++k) \
;         acc[ai][bj][m][n] = __builtin_amdgcn_mfma_f32_16x16x32_bf16(Bt[n][k], At[m][k], acc[ai][bj][m][n], 0, 0, 0); __builtin_amdgcn_s_setprio(0); } while (0)
; #define PG8_WAIT_V(n) asm volatile("s_waitcnt vmcnt(" #n ")" ::: "memory")
; #define PG8_WAIT_L(n) asm volatile("s_waitcnt lgkmcnt(" #n ")" ::: "memory")
; #define PG8_BAR __builtin_amdgcn_s_barrier()
; #define PG8_SCHED __builtin_amdgcn_sched_barrier(0)
; template <int NSEG, class Epi, bool ALIGN_EPI = PG8_ALIGN, bool SP2 = PG8_SP2>
; DI void gemm_phase(LAS unsigned char* lds, const Gemm g, const StaticOrder& S, const Epi& E) {
;     ...
;             PG8_LDA(At, 1, 1); PG8_STAGE(PG8_SB(1, 0), b3, v2); PG8_STAGE(PG8_SB(1, 1), b3 + h2, v2); PG8_STAGE(PG8_SA(1, 0), a3, v2);
;             PG8_WAIT_V(8); PG8_WAIT_L(0); PG8_BAR; PG8_MMA(1, 0, At, B0); PG8_MMA(1, 1, At, B1); PG8_BAR; PG8_SCHED;
	s_add_i32 s26, s53, s38
	v_lshl_add_u64 v[212:213], v[212:213], 0, s[10:11]
	s_mov_b32 m0, s26
	ds_read_b128 v[180:183], v147 offset:49152
	ds_read_b128 v[184:187], v147 offset:50176
	ds_read_b128 v[188:191], v147 offset:51200
	ds_read_b128 v[192:195], v147 offset:52224
	ds_read_b128 v[196:199], v147 offset:53248
	ds_read_b128 v[200:203], v147 offset:54272
	ds_read_b128 v[204:207], v147 offset:55296
	ds_read_b128 v[208:211], v147 offset:56320
	global_load_lds_dwordx4 v[212:213], off
	s_add_i32 m0, s26, 0x2000
	s_add_u32 s24, s24, 0x80080
	v_lshl_add_u64 v[212:213], v[214:215], 0, s[10:11]
	s_addc_u32 s25, s25, 0
	s_add_i32 s26, s54, s38
	global_load_lds_dwordx4 v[212:213], off
	v_lshl_add_u64 v[212:213], s[24:25], 0, v[130:131]
	s_mov_b32 m0, s26
	s_nop 0
	global_load_lds_dwordx4 v[212:213], off
	v_lshl_add_u64 v[212:213], s[24:25], 0, v[132:133]
	s_add_i32 m0, s26, 0x2000
	s_nop 0
	global_load_lds_dwordx4 v[212:213], off
	v_lshl_add_u64 v[212:213], v[216:217], 0, s[10:11]
	s_mov_b32 m0, s46
	s_nop 0
	global_load_lds_dwordx4 v[212:213], off
	v_lshl_add_u64 v[212:213], v[218:219], 0, s[10:11]
	s_mov_b32 m0, s47
	s_nop 0
	global_load_lds_dwordx4 v[212:213], off
	s_waitcnt vmcnt(8)
	s_waitcnt lgkmcnt(0)
	s_setprio 1
	s_barrier
	v_mfma_f32_16x16x32_bf16 v[46:49], v[148:151], v[180:183], v[46:49]
	v_mfma_f32_16x16x32_bf16 v[42:45], v[156:159], v[180:183], v[42:45]
	v_mfma_f32_16x16x32_bf16 v[38:41], v[148:151], v[188:191], v[38:41]
	v_mfma_f32_16x16x32_bf16 v[34:37], v[156:159], v[188:191], v[34:37]
	v_mfma_f32_16x16x32_bf16 v[22:25], v[148:151], v[196:199], v[22:25]
	v_mfma_f32_16x16x32_bf16 v[18:21], v[156:159], v[196:199], v[18:21]
	v_mfma_f32_16x16x32_bf16 v[6:9], v[148:151], v[204:207], v[6:9]
	v_mfma_f32_16x16x32_bf16 v[2:5], v[156:159], v[204:207], v[2:5]
	v_mfma_f32_16x16x32_bf16 v[46:49], v[152:155], v[184:187], v[46:49]
	v_mfma_f32_16x16x32_bf16 v[42:45], v[160:163], v[184:187], v[42:45]
	v_mfma_f32_16x16x32_bf16 v[38:41], v[152:155], v[192:195], v[38:41]
	v_mfma_f32_16x16x32_bf16 v[34:37], v[160:163], v[192:195], v[34:37]
	v_mfma_f32_16x16x32_bf16 v[22:25], v[152:155], v[200:203], v[22:25]
	v_mfma_f32_16x16x32_bf16 v[18:21], v[160:163], v[200:203], v[18:21]
	v_mfma_f32_16x16x32_bf16 v[6:9], v[152:155], v[208:211], v[6:9]
	v_mfma_f32_16x16x32_bf16 v[2:5], v[160:163], v[208:211], v[2:5]
	s_setprio 0
	s_setprio 1
	v_mfma_f32_16x16x32_bf16 v[30:33], v[164:167], v[180:183], v[30:33]
	v_mfma_f32_16x16x32_bf16 v[26:29], v[172:175], v[180:183], v[26:29]
	v_mfma_f32_16x16x32_bf16 v[14:17], v[164:167], v[188:191], v[14:17]
	v_mfma_f32_16x16x32_bf16 v[10:13], v[172:175], v[188:191], v[10:13]
	v_mfma_f32_16x16x32_bf16 v[62:65], v[164:167], v[196:199], v[62:65]
	v_mfma_f32_16x16x32_bf16 v[66:69], v[172:175], v[196:199], v[66:69]
	v_mfma_f32_16x16x32_bf16 v[50:53], v[164:167], v[204:207], v[50:53]
	v_mfma_f32_16x16x32_bf16 v[54:57], v[172:175], v[204:207], v[54:57]
	v_mfma_f32_16x16x32_bf16 v[30:33], v[168:171], v[184:187], v[30:33]
	v_mfma_f32_16x16x32_bf16 v[26:29], v[176:179], v[184:187], v[26:29]
	v_mfma_f32_16x16x32_bf16 v[14:17], v[168:171], v[192:195], v[14:17]
	v_mfma_f32_16x16x32_bf16 v[10:13], v[176:179], v[192:195], v[10:13]
	v_mfma_f32_16x16x32_bf16 v[62:65], v[168:171], v[200:203], v[62:65]
	v_mfma_f32_16x16x32_bf16 v[66:69], v[176:179], v[200:203], v[66:69]
	v_mfma_f32_16x16x32_bf16 v[50:53], v[168:171], v[208:211], v[50:53]
	v_mfma_f32_16x16x32_bf16 v[54:57], v[176:179], v[208:211], v[54:57]
	s_setprio 0
	s_barrier
	s_add_i32 s52, s52, 2
	s_add_u32 s22, s22, 0x100
	s_addc_u32 s23, s23, 0
	s_add_u32 s17, s17, 0x100
	s_addc_u32 s19, s19, 0
	s_cmp_gt_u32 s52, 29
	s_cbranch_scc0 .LBB0_501
	s_and_b64 vcc, exec, s[12:13]
	s_cbranch_vccz .LBB0_504
	s_barrier

; #define PG8_STAGE(bufoff, gbase, VO) do { _Pragma("unroll") for (int _i = 0; _i < 2; ++_i) \
;         __builtin_amdgcn_global_load_lds((const unsigned*)((const char*)(gbase) + VO[_i]), (LAS unsigned*)(lds + (bufoff) + ldsw + _i * 8192), 16, 0, 0); } while (0)
; #define PG8_LDA(dst, b, h) do { _Pragma("unroll") for (int m = 0; m < 4; ++m) _Pragma("unroll") for (int k = 0; k < 2; ++k) dst[m][k] = *(const LAS bf16x8*)(lds + PG8_SA(b, h) + aoff + m * 2048 + k * 1024); } while (0)
; #define PG8_LDB(dst, b, h) do { _Pragma("unroll") for (int n = 0; n < 2; ++n) _Pragma("unroll") for (int k = 0; k < 2; ++k) dst[n][k] = *(const LAS bf16x8*)(lds + PG8_SB(b, h) + boff + n * 2048 + k * 1024); } while (0)
; #define PG8_MMA(ai, bj, At, Bt) do { __builtin_amdgcn_s_setprio(1); _Pragma("unroll") for (int m = 0; m < 4; ++m) _Pragma("unroll") for (int n = 0; n < 2; ++n) _Pragma("unroll") for (int k = 0; k < 2; ++k) \
;         acc[ai][bj][m][n] = __builtin_amdgcn_mfma_f32_16x16x32_bf16(Bt[n][k], At[m][k], acc[ai][bj][m][n], 0, 0, 0); __builtin_amdgcn_s_setprio(0); } while (0)
; #define PG8_WAIT_V(n) asm volatile("s_waitcnt vmcnt(" #n ")" ::: "memory")
; #define PG8_WAIT_L(n) asm volatile("s_waitcnt lgkmcnt(" #n ")" ::: "memory")
; template <int NSEG, class Epi, bool ALIGN_EPI = PG8_ALIGN, bool SP2 = PG8_SP2>
; DI void gemm_phase(LAS unsigned char* lds, const Gemm g, const StaticOrder& S, const Epi& E) {
;     ...
;         for (int t = 0; t < nt; t += 2) {
;             const bool last = (t == nt - 2);
;             const char* a1 = cA + (size_t)(t + 1) * kstep;
;             const char* a2 = last ? nA : cA + (size_t)(t + 2) * kstep; const char* b2 = last ? nB : cB + (size_t)(t + 2) * kstep;
;             const char* a3 = a2 + kstep; const char* b3 = b2 + kstep;
;             unsigned v2[2]; v2[0] = (NSEG > 1 && last) ? voffN[0] : voffC[0]; v2[1] = (NSEG > 1 && last) ? voffN[1] : voffC[1];
;             const size_t h2 = (NSEG > 1 && last) ? hstepN : hstepC;
;             if constexpr (SP2) {
;             PG8_LDB(B0, 0, 0); PG8_LDB(B1, 0, 1); PG8_SCHED; PG8_LDA(At, 0, 0); PG8_STAGE(PG8_SA(1, 1), a1 + hstepC, voffC);
;             PG8_WAIT_V(8); PG8_WAIT_L(0); PG8_BAR; PG8_MMA(0, 0, At, B0); PG8_MMA(0, 1, At, B1); PG8_BAR; PG8_SCHED;
;             PG8_LDA(At, 0, 1); PG8_STAGE(PG8_SB(0, 0), b2, v2); PG8_STAGE(PG8_SB(0, 1), b2 + h2, v2); PG8_STAGE(PG8_SA(0, 0), a2, v2);
.LBB0_545:
	ds_read_b128 v[102:105], v207
	ds_read_b128 v[106:109], v207 offset:1024
	ds_read_b128 v[110:113], v207 offset:2048
	ds_read_b128 v[114:117], v207 offset:3072
	ds_read_b128 v[118:121], v208
	ds_read_b128 v[122:125], v208 offset:1024
	ds_read_b128 v[126:129], v208 offset:2048
	ds_read_b128 v[130:133], v208 offset:3072
	s_add_u32 s34, s4, 0xfff80080
	s_addc_u32 s35, s5, -1
	s_cmp_eq_u32 s67, 28
	s_cselect_b32 s39, s1, s35
	s_cselect_b32 s38, s25, s34
	s_cselect_b32 s35, s27, s66
	s_cselect_b32 s34, s64, s65
	v_lshl_add_u64 v[204:205], s[4:5], 0, v[178:179]
	s_add_i32 m0, s3, 0xc000
	ds_read_b128 v[162:165], v209
	ds_read_b128 v[166:169], v209 offset:1024
	ds_read_b128 v[170:173], v209 offset:2048
	ds_read_b128 v[188:191], v209 offset:3072
	ds_read_b128 v[192:195], v209 offset:4096
	ds_read_b128 v[196:199], v209 offset:5120
	ds_read_b128 v[200:203], v209 offset:6144
	ds_read_b128 v[212:215], v209 offset:7168
	global_load_lds_dwordx4 v[204:205], off
	v_lshl_add_u64 v[204:205], s[4:5], 0, v[180:181]
	s_add_i32 m0, s3, 0xe000
	s_nop 0
	global_load_lds_dwordx4 v[204:205], off
	s_waitcnt vmcnt(8)
	s_waitcnt lgkmcnt(0)
	s_setprio 1
	s_barrier
	v_mfma_f32_16x16x32_bf16 v[158:161], v[102:105], v[162:165], v[158:161]
	v_mfma_f32_16x16x32_bf16 v[154:157], v[110:113], v[162:165], v[154:157]
	v_mfma_f32_16x16x32_bf16 v[150:153], v[102:105], v[170:173], v[150:153]
	v_mfma_f32_16x16x32_bf16 v[146:149], v[110:113], v[170:173], v[146:149]
	v_mfma_f32_16x16x32_bf16 v[142:145], v[102:105], v[192:195], v[142:145]
	v_mfma_f32_16x16x32_bf16 v[138:141], v[110:113], v[192:195], v[138:141]
	v_mfma_f32_16x16x32_bf16 v[134:137], v[102:105], v[200:203], v[134:137]
	v_mfma_f32_16x16x32_bf16 v[98:101], v[110:113], v[200:203], v[98:101]
	v_mfma_f32_16x16x32_bf16 v[158:161], v[106:109], v[166:169], v[158:161]
	v_mfma_f32_16x16x32_bf16 v[154:157], v[114:117], v[166:169], v[154:157]
	v_mfma_f32_16x16x32_bf16 v[150:153], v[106:109], v[188:191], v[150:153]
	v_mfma_f32_16x16x32_bf16 v[146:149], v[114:117], v[188:191], v[146:149]
	v_mfma_f32_16x16x32_bf16 v[142:145], v[106:109], v[196:199], v[142:145]
	v_mfma_f32_16x16x32_bf16 v[138:141], v[114:117], v[196:199], v[138:141]
	v_mfma_f32_16x16x32_bf16 v[134:137], v[106:109], v[212:215], v[134:137]
	v_mfma_f32_16x16x32_bf16 v[98:101], v[114:117], v[212:215], v[98:101]
	s_setprio 0
	s_setprio 1
	v_mfma_f32_16x16x32_bf16 v[62:65], v[118:121], v[162:165], v[62:65]
	v_mfma_f32_16x16x32_bf16 v[58:61], v[126:129], v[162:165], v[58:61]
	v_mfma_f32_16x16x32_bf16 v[54:57], v[118:121], v[170:173], v[54:57]
	v_mfma_f32_16x16x32_bf16 v[50:53], v[126:129], v[170:173], v[50:53]
	v_mfma_f32_16x16x32_bf16 v[46:49], v[118:121], v[192:195], v[46:49]
	v_mfma_f32_16x16x32_bf16 v[42:45], v[126:129], v[192:195], v[42:45]
	v_mfma_f32_16x16x32_bf16 v[38:41], v[118:121], v[200:203], v[38:41]
	v_mfma_f32_16x16x32_bf16 v[34:37], v[126:129], v[200:203], v[34:37]
	v_mfma_f32_16x16x32_bf16 v[62:65], v[122:125], v[166:169], v[62:65]
	v_mfma_f32_16x16x32_bf16 v[58:61], v[130:133], v[166:169], v[58:61]
	v_mfma_f32_16x16x32_bf16 v[54:57], v[122:125], v[188:191], v[54:57]
	v_mfma_f32_16x16x32_bf16 v[50:53], v[130:133], v[188:191], v[50:53]
	v_mfma_f32_16x16x32_bf16 v[46:49], v[122:125], v[196:199], v[46:49]
	v_mfma_f32_16x16x32_bf16 v[42:45], v[130:133], v[196:199], v[42:45]
	v_mfma_f32_16x16x32_bf16 v[38:41], v[122:125], v[212:215], v[38:41]
	v_mfma_f32_16x16x32_bf16 v[34:37], v[130:133], v[212:215], v[34:37]
	s_setprio 0
	s_barrier
	s_add_i32 s68, s58, s50
	v_lshl_add_u64 v[204:205], s[34:35], 0, v[174:175]
	s_mov_b32 m0, s68
	ds_read_b128 v[162:165], v209 offset:16384
	ds_read_b128 v[166:169], v209 offset:17408
	ds_read_b128 v[170:173], v209 offset:18432
	ds_read_b128 v[188:191], v209 offset:19456
	ds_read_b128 v[192:195], v209 offset:20480
	ds_read_b128 v[196:199], v209 offset:21504
	ds_read_b128 v[200:203], v209 offset:22528
	ds_read_b128 v[212:215], v209 offset:23552
	global_load_lds_dwordx4 v[204:205], off
	s_add_i32 m0, s68, 0x2000
	s_add_u32 s68, s34, 0x80000
	v_lshl_add_u64 v[216:217], s[34:35], 0, v[176:177]
	s_addc_u32 s69, s35, 0
	s_add_i32 s70, s59, s50
	global_load_lds_dwordx4 v[216:217], off
	v_lshl_add_u64 v[218:219], s[68:69], 0, v[174:175]
	s_mov_b32 m0, s70
	v_lshl_add_u64 v[220:221], s[38:39], 0, v[176:177]
	global_load_lds_dwordx4 v[218:219], off
	v_lshl_add_u64 v[218:219], s[68:69], 0, v[176:177]
	s_add_i32 m0, s70, 0x2000
	s_nop 0
	global_load_lds_dwordx4 v[218:219], off
	v_lshl_add_u64 v[218:219], s[38:39], 0, v[174:175]
	s_mov_b32 m0, s3
	s_nop 0
	global_load_lds_dwordx4 v[218:219], off
	s_mov_b32 m0, s52
	s_nop 0
	global_load_lds_dwordx4 v[220:221], off
	s_waitcnt vmcnt(8)
	s_waitcnt lgkmcnt(0)
	s_setprio 1
	s_barrier
; #define PG8_STAGE(bufoff, gbase, VO) do { _Pragma("unroll") for (int _i = 0; _i < 2; ++_i) \
;         __builtin_amdgcn_global_load_lds((const unsigned*)((const char*)(gbase) + VO[_i]), (LAS unsigned*)(lds + (bufoff) + ldsw + _i * 8192), 16, 0, 0); } while (0)
; #define PG8_LDA(dst, b, h) do { _Pragma("unroll") for (int m = 0; m < 4; ++m) _Pragma("unroll") for (int k = 0; k < 2; ++k) dst[m][k] = *(const LAS bf16x8*)(lds + PG8_SA(b, h) + aoff + m * 2048 + k * 1024); } while (0)
; #define PG8_LDB(dst, b, h) do { _Pragma("unroll") for (int n = 0; n < 2; ++n) _Pragma("unroll") for (int k = 0; k < 2; ++k) dst[n][k] = *(const LAS bf16x8*)(lds + PG8_SB(b, h) + boff + n * 2048 + k * 1024); } while (0)
; #define PG8_MMA(ai, bj, At, Bt) do { __builtin_amdgcn_s_setprio(1); _Pragma("unroll") for (int m = 0; m < 4; ++m) _Pragma("unroll") for (int n = 0; n < 2; ++n) _Pragma("unroll") for (int k = 0; k < 2; ++k) \
;         acc[ai][bj][m][n] = __builtin_amdgcn_mfma_f32_16x16x32_bf16(Bt[n][k], At[m][k], acc[ai][bj][m][n], 0, 0, 0); __builtin_amdgcn_s_setprio(0); } while (0)
; #define PG8_WAIT_V(n) asm volatile("s_waitcnt vmcnt(" #n ")" ::: "memory")
; #define PG8_WAIT_L(n) asm volatile("s_waitcnt lgkmcnt(" #n ")" ::: "memory")
; #define PG8_BAR __builtin_amdgcn_s_barrier()
; #define PG8_SCHED __builtin_amdgcn_sched_barrier(0)
; template <int NSEG, class Epi, bool ALIGN_EPI = PG8_ALIGN, bool SP2 = PG8_SP2>
; DI void gemm_phase(LAS unsigned char* lds, const Gemm g, const StaticOrder& S, const Epi& E) {
;     ...
;             PG8_LDA(At, 0, 1); PG8_STAGE(PG8_SB(0, 0), b2, v2); PG8_STAGE(PG8_SB(0, 1), b2 + h2, v2); PG8_STAGE(PG8_SA(0, 0), a2, v2);
;             PG8_WAIT_V(8); PG8_WAIT_L(0); PG8_BAR; PG8_MMA(1, 0, At, B0); PG8_MMA(1, 1, At, B1); PG8_BAR; PG8_SCHED;
;             PG8_LDB(B0, 1, 0); PG8_LDB(B1, 1, 1); PG8_SCHED; PG8_LDA(At, 1, 0); PG8_STAGE(PG8_SA(0, 1), a2 + h2, v2);
;             PG8_WAIT_V(8); PG8_WAIT_L(0); PG8_BAR; PG8_MMA(0, 0, At, B0); PG8_MMA(0, 1, At, B1); PG8_BAR; PG8_SCHED;
	v_mfma_f32_16x16x32_bf16 v[94:97], v[102:105], v[162:165], v[94:97]
	v_mfma_f32_16x16x32_bf16 v[90:93], v[110:113], v[162:165], v[90:93]
	v_mfma_f32_16x16x32_bf16 v[86:89], v[102:105], v[170:173], v[86:89]
	v_mfma_f32_16x16x32_bf16 v[82:85], v[110:113], v[170:173], v[82:85]
	v_mfma_f32_16x16x32_bf16 v[78:81], v[102:105], v[192:195], v[78:81]
	v_mfma_f32_16x16x32_bf16 v[74:77], v[110:113], v[192:195], v[74:77]
	v_mfma_f32_16x16x32_bf16 v[70:73], v[102:105], v[200:203], v[70:73]
	v_mfma_f32_16x16x32_bf16 v[66:69], v[110:113], v[200:203], v[66:69]
	v_mfma_f32_16x16x32_bf16 v[94:97], v[106:109], v[166:169], v[94:97]
	v_mfma_f32_16x16x32_bf16 v[90:93], v[114:117], v[166:169], v[90:93]
	v_mfma_f32_16x16x32_bf16 v[86:89], v[106:109], v[188:191], v[86:89]
	v_mfma_f32_16x16x32_bf16 v[82:85], v[114:117], v[188:191], v[82:85]
	v_mfma_f32_16x16x32_bf16 v[78:81], v[106:109], v[196:199], v[78:81]
	v_mfma_f32_16x16x32_bf16 v[74:77], v[114:117], v[196:199], v[74:77]
	v_mfma_f32_16x16x32_bf16 v[70:73], v[106:109], v[212:215], v[70:73]
	v_mfma_f32_16x16x32_bf16 v[66:69], v[114:117], v[212:215], v[66:69]
	s_setprio 0
	s_setprio 1
	v_mfma_f32_16x16x32_bf16 v[30:33], v[118:121], v[162:165], v[30:33]
	v_mfma_f32_16x16x32_bf16 v[26:29], v[126:129], v[162:165], v[26:29]
	v_mfma_f32_16x16x32_bf16 v[22:25], v[118:121], v[170:173], v[22:25]
	v_mfma_f32_16x16x32_bf16 v[14:17], v[126:129], v[170:173], v[14:17]
	v_mfma_f32_16x16x32_bf16 v[18:21], v[118:121], v[192:195], v[18:21]
	v_mfma_f32_16x16x32_bf16 v[10:13], v[126:129], v[192:195], v[10:13]
	v_mfma_f32_16x16x32_bf16 v[6:9], v[118:121], v[200:203], v[6:9]
	v_mfma_f32_16x16x32_bf16 v[2:5], v[126:129], v[200:203], v[2:5]
	v_mfma_f32_16x16x32_bf16 v[30:33], v[122:125], v[166:169], v[30:33]
	v_mfma_f32_16x16x32_bf16 v[26:29], v[130:133], v[166:169], v[26:29]
	v_mfma_f32_16x16x32_bf16 v[22:25], v[122:125], v[188:191], v[22:25]
	v_mfma_f32_16x16x32_bf16 v[14:17], v[130:133], v[188:191], v[14:17]
	v_mfma_f32_16x16x32_bf16 v[18:21], v[122:125], v[196:199], v[18:21]
	v_mfma_f32_16x16x32_bf16 v[10:13], v[130:133], v[196:199], v[10:13]
	v_mfma_f32_16x16x32_bf16 v[6:9], v[122:125], v[212:215], v[6:9]
	v_mfma_f32_16x16x32_bf16 v[2:5], v[130:133], v[212:215], v[2:5]
	s_setprio 0
	s_barrier
	s_add_i32 s68, 0, 0x18000
	s_add_i32 s69, 0, 0x1c000
	v_add_u32_e32 v114, s68, v187
	v_add_u32_e32 v130, s69, v187
	ds_read_b128 v[102:105], v114
	ds_read_b128 v[106:109], v114 offset:1024
	ds_read_b128 v[110:113], v114 offset:2048
	ds_read_b128 v[114:117], v114 offset:3072
	ds_read_b128 v[118:121], v130
	ds_read_b128 v[122:125], v130 offset:1024
	ds_read_b128 v[126:129], v130 offset:2048
	ds_read_b128 v[130:133], v130 offset:3072
	s_add_u32 s38, s38, 0x80000
	s_addc_u32 s39, s39, 0
	s_mov_b32 m0, s53
	v_lshl_add_u64 v[222:223], s[38:39], 0, v[174:175]
	ds_read_b128 v[162:165], v209 offset:32768
	ds_read_b128 v[166:169], v209 offset:33792
	ds_read_b128 v[170:173], v209 offset:34816
	ds_read_b128 v[188:191], v209 offset:35840
	ds_read_b128 v[192:195], v209 offset:36864
	ds_read_b128 v[196:199], v209 offset:37888
	ds_read_b128 v[200:203], v209 offset:38912
	ds_read_b128 v[212:215], v209 offset:39936
	global_load_lds_dwordx4 v[222:223], off
	v_lshl_add_u64 v[222:223], s[38:39], 0, v[176:177]
	s_mov_b32 m0, s54
	s_nop 0
	global_load_lds_dwordx4 v[222:223], off
	s_waitcnt vmcnt(8)
	s_waitcnt lgkmcnt(0)
	s_setprio 1
	s_barrier
	v_mfma_f32_16x16x32_bf16 v[158:161], v[102:105], v[162:165], v[158:161]
	v_mfma_f32_16x16x32_bf16 v[154:157], v[110:113], v[162:165], v[154:157]
	v_mfma_f32_16x16x32_bf16 v[150:153], v[102:105], v[170:173], v[150:153]
	v_mfma_f32_16x16x32_bf16 v[146:149], v[110:113], v[170:173], v[146:149]
	v_mfma_f32_16x16x32_bf16 v[142:145], v[102:105], v[192:195], v[142:145]
	v_mfma_f32_16x16x32_bf16 v[138:141], v[110:113], v[192:195], v[138:141]
	v_mfma_f32_16x16x32_bf16 v[134:137], v[102:105], v[200:203], v[134:137]
	v_mfma_f32_16x16x32_bf16 v[98:101], v[110:113], v[200:203], v[98:101]
	v_mfma_f32_16x16x32_bf16 v[158:161], v[106:109], v[166:169], v[158:161]
	v_mfma_f32_16x16x32_bf16 v[154:157], v[114:117], v[166:169], v[154:157]
	v_mfma_f32_16x16x32_bf16 v[150:153], v[106:109], v[188:191], v[150:153]
	v_mfma_f32_16x16x32_bf16 v[146:149], v[114:117], v[188:191], v[146:149]
	v_mfma_f32_16x16x32_bf16 v[142:145], v[106:109], v[196:199], v[142:145]
	v_mfma_f32_16x16x32_bf16 v[138:141], v[114:117], v[196:199], v[138:141]
	v_mfma_f32_16x16x32_bf16 v[134:137], v[106:109], v[212:215], v[134:137]
	v_mfma_f32_16x16x32_bf16 v[98:101], v[114:117], v[212:215], v[98:101]
	s_setprio 0
	s_setprio 1
	v_mfma_f32_16x16x32_bf16 v[62:65], v[118:121], v[162:165], v[62:65]
	v_mfma_f32_16x16x32_bf16 v[58:61], v[126:129], v[162:165], v[58:61]
	v_mfma_f32_16x16x32_bf16 v[54:57], v[118:121], v[170:173], v[54:57]
	v_mfma_f32_16x16x32_bf16 v[50:53], v[126:129], v[170:173], v[50:53]
	v_mfma_f32_16x16x32_bf16 v[46:49], v[118:121], v[192:195], v[46:49]
	v_mfma_f32_16x16x32_bf16 v[42:45], v[126:129], v[192:195], v[42:45]
	v_mfma_f32_16x16x32_bf16 v[38:41], v[118:121], v[200:203], v[38:41]
	v_mfma_f32_16x16x32_bf16 v[34:37], v[126:129], v[200:203], v[34:37]
	v_mfma_f32_16x16x32_bf16 v[62:65], v[122:125], v[166:169], v[62:65]
	v_mfma_f32_16x16x32_bf16 v[58:61], v[130:133], v[166:169], v[58:61]
	v_mfma_f32_16x16x32_bf16 v[54:57], v[122:125], v[188:191], v[54:57]
	v_mfma_f32_16x16x32_bf16 v[50:53], v[130:133], v[188:191], v[50:53]
	v_mfma_f32_16x16x32_bf16 v[46:49], v[122:125], v[196:199], v[46:49]
	v_mfma_f32_16x16x32_bf16 v[42:45], v[130:133], v[196:199], v[42:45]
	v_mfma_f32_16x16x32_bf16 v[38:41], v[122:125], v[212:215], v[38:41]
	v_mfma_f32_16x16x32_bf16 v[34:37], v[130:133], v[212:215], v[34:37]
	s_setprio 0
	s_barrier
; #define PG8_STAGE(bufoff, gbase, VO) do { _Pragma("unroll") for (int _i = 0; _i < 2; ++_i) \
;         __builtin_amdgcn_global_load_lds((const unsigned*)((const char*)(gbase) + VO[_i]), (LAS unsigned*)(lds + (bufoff) + ldsw + _i * 8192), 16, 0, 0); } while (0)
; #define PG8_LDA(dst, b, h) do { _Pragma("unroll") for (int m = 0; m < 4; ++m) _Pragma("unroll") for (int k = 0; k < 2; ++k) dst[m][k] = *(const LAS bf16x8*)(lds + PG8_SA(b, h) + aoff + m * 2048 + k * 1024); } while (0)
; #define PG8_MMA(ai, bj, At, Bt) do { __builtin_amdgcn_s_setprio(1); _Pragma("unroll") for (int m = 0; m < 4; ++m) _Pragma("unroll") for (int n = 0; n < 2; ++n) _Pragma("unroll") for (int k = 0; k < 2; ++k) \
;         acc[ai][bj][m][n] = __builtin_amdgcn_mfma_f32_16x16x32_bf16(Bt[n][k], At[m][k], acc[ai][bj][m][n], 0, 0, 0); __builtin_amdgcn_s_setprio(0); } while (0)
; #define PG8_WAIT_V(n) asm volatile("s_waitcnt vmcnt(" #n ")" ::: "memory")
; #define PG8_WAIT_L(n) asm volatile("s_waitcnt lgkmcnt(" #n ")" ::: "memory")
; #define PG8_BAR __builtin_amdgcn_s_barrier()
; #define PG8_SCHED __builtin_amdgcn_sched_barrier(0)
; template <int NSEG, class Epi, bool ALIGN_EPI = PG8_ALIGN, bool SP2 = PG8_SP2>
; DI void gemm_phase(LAS unsigned char* lds, const Gemm g, const StaticOrder& S, const Epi& E) {
;     ...
;             PG8_LDA(At, 1, 1); PG8_STAGE(PG8_SB(1, 0), b3, v2); PG8_STAGE(PG8_SB(1, 1), b3 + h2, v2); PG8_STAGE(PG8_SA(1, 0), a3, v2);
;             PG8_WAIT_V(8); PG8_WAIT_L(0); PG8_BAR; PG8_MMA(1, 0, At, B0); PG8_MMA(1, 1, At, B1); PG8_BAR; PG8_SCHED;
	s_add_i32 s38, s68, s50
	v_lshl_add_u64 v[204:205], v[204:205], 0, s[16:17]
	s_mov_b32 m0, s38
	ds_read_b128 v[162:165], v209 offset:49152
	ds_read_b128 v[166:169], v209 offset:50176
	ds_read_b128 v[170:173], v209 offset:51200
	ds_read_b128 v[188:191], v209 offset:52224
	ds_read_b128 v[192:195], v209 offset:53248
	ds_read_b128 v[196:199], v209 offset:54272
	ds_read_b128 v[200:203], v209 offset:55296
	ds_read_b128 v[212:215], v209 offset:56320
	global_load_lds_dwordx4 v[204:205], off
	s_add_i32 m0, s38, 0x2000
	s_add_u32 s34, s34, 0x80080
	v_lshl_add_u64 v[204:205], v[216:217], 0, s[16:17]
	s_addc_u32 s35, s35, 0
	s_add_i32 s38, s69, s50
	global_load_lds_dwordx4 v[204:205], off
	v_lshl_add_u64 v[204:205], s[34:35], 0, v[174:175]
	s_mov_b32 m0, s38
	s_nop 0
	global_load_lds_dwordx4 v[204:205], off
	v_lshl_add_u64 v[204:205], s[34:35], 0, v[176:177]
	s_add_i32 m0, s38, 0x2000
	s_nop 0
	global_load_lds_dwordx4 v[204:205], off
	v_lshl_add_u64 v[204:205], v[218:219], 0, s[16:17]
	s_mov_b32 m0, s55
	s_nop 0
	global_load_lds_dwordx4 v[204:205], off
	v_lshl_add_u64 v[204:205], v[220:221], 0, s[16:17]
	s_mov_b32 m0, s56
	s_nop 0
	global_load_lds_dwordx4 v[204:205], off
	s_waitcnt vmcnt(8)
	s_waitcnt lgkmcnt(0)
	s_setprio 1
	s_barrier
	v_mfma_f32_16x16x32_bf16 v[94:97], v[102:105], v[162:165], v[94:97]
	v_mfma_f32_16x16x32_bf16 v[90:93], v[110:113], v[162:165], v[90:93]
	v_mfma_f32_16x16x32_bf16 v[86:89], v[102:105], v[170:173], v[86:89]
	v_mfma_f32_16x16x32_bf16 v[82:85], v[110:113], v[170:173], v[82:85]
	v_mfma_f32_16x16x32_bf16 v[78:81], v[102:105], v[192:195], v[78:81]
	v_mfma_f32_16x16x32_bf16 v[74:77], v[110:113], v[192:195], v[74:77]
	v_mfma_f32_16x16x32_bf16 v[70:73], v[102:105], v[200:203], v[70:73]
	v_mfma_f32_16x16x32_bf16 v[66:69], v[110:113], v[200:203], v[66:69]
	v_mfma_f32_16x16x32_bf16 v[94:97], v[106:109], v[166:169], v[94:97]
	v_mfma_f32_16x16x32_bf16 v[90:93], v[114:117], v[166:169], v[90:93]
	v_mfma_f32_16x16x32_bf16 v[86:89], v[106:109], v[188:191], v[86:89]
	v_mfma_f32_16x16x32_bf16 v[82:85], v[114:117], v[188:191], v[82:85]
	v_mfma_f32_16x16x32_bf16 v[78:81], v[106:109], v[196:199], v[78:81]
	v_mfma_f32_16x16x32_bf16 v[74:77], v[114:117], v[196:199], v[74:77]
	v_mfma_f32_16x16x32_bf16 v[70:73], v[106:109], v[212:215], v[70:73]
	v_mfma_f32_16x16x32_bf16 v[66:69], v[114:117], v[212:215], v[66:69]
	s_setprio 0
	s_setprio 1
	v_mfma_f32_16x16x32_bf16 v[30:33], v[118:121], v[162:165], v[30:33]
	v_mfma_f32_16x16x32_bf16 v[26:29], v[126:129], v[162:165], v[26:29]
	v_mfma_f32_16x16x32_bf16 v[22:25], v[118:121], v[170:173], v[22:25]
	v_mfma_f32_16x16x32_bf16 v[14:17], v[126:129], v[170:173], v[14:17]
	v_mfma_f32_16x16x32_bf16 v[18:21], v[118:121], v[192:195], v[18:21]
	v_mfma_f32_16x16x32_bf16 v[10:13], v[126:129], v[192:195], v[10:13]
	v_mfma_f32_16x16x32_bf16 v[6:9], v[118:121], v[200:203], v[6:9]
	v_mfma_f32_16x16x32_bf16 v[2:5], v[126:129], v[200:203], v[2:5]
	v_mfma_f32_16x16x32_bf16 v[30:33], v[122:125], v[166:169], v[30:33]
	v_mfma_f32_16x16x32_bf16 v[26:29], v[130:133], v[166:169], v[26:29]
	v_mfma_f32_16x16x32_bf16 v[22:25], v[122:125], v[188:191], v[22:25]
	v_mfma_f32_16x16x32_bf16 v[14:17], v[130:133], v[188:191], v[14:17]
	v_mfma_f32_16x16x32_bf16 v[18:21], v[122:125], v[196:199], v[18:21]
	v_mfma_f32_16x16x32_bf16 v[10:13], v[130:133], v[196:199], v[10:13]
	v_mfma_f32_16x16x32_bf16 v[6:9], v[122:125], v[212:215], v[6:9]
	v_mfma_f32_16x16x32_bf16 v[2:5], v[130:133], v[212:215], v[2:5]
	s_setprio 0
	s_barrier
	s_add_i32 s67, s67, 2
	s_add_u32 s4, s4, 0x100
	s_addc_u32 s5, s5, 0
	s_add_u32 s65, s65, 0x100
	s_addc_u32 s66, s66, 0
	s_cmp_gt_u32 s67, 29
	s_cbranch_scc0 .LBB0_545
	s_and_b64 vcc, exec, s[18:19]
	s_cbranch_vccz .LBB0_548
	s_barrier

; #define PG8_STAGE(bufoff, gbase, VO) do { _Pragma("unroll") for (int _i = 0; _i < 2; ++_i) \
;         __builtin_amdgcn_global_load_lds((const unsigned*)((const char*)(gbase) + VO[_i]), (LAS unsigned*)(lds + (bufoff) + ldsw + _i * 8192), 16, 0, 0); } while (0)
; #define PG8_LDA(dst, b, h) do { _Pragma("unroll") for (int m = 0; m < 4; ++m) _Pragma("unroll") for (int k = 0; k < 2; ++k) dst[m][k] = *(const LAS bf16x8*)(lds + PG8_SA(b, h) + aoff + m * 2048 + k * 1024); } while (0)
; #define PG8_LDB(dst, b, h) do { _Pragma("unroll") for (int n = 0; n < 2; ++n) _Pragma("unroll") for (int k = 0; k < 2; ++k) dst[n][k] = *(const LAS bf16x8*)(lds + PG8_SB(b, h) + boff + n * 2048 + k * 1024); } while (0)
; #define PG8_MMA(ai, bj, At, Bt) do { __builtin_amdgcn_s_setprio(1); _Pragma("unroll") for (int m = 0; m < 4; ++m) _Pragma("unroll") for (int n = 0; n < 2; ++n) _Pragma("unroll") for (int k = 0; k < 2; ++k) \
;         acc[ai][bj][m][n] = __builtin_amdgcn_mfma_f32_16x16x32_bf16(Bt[n][k], At[m][k], acc[ai][bj][m][n], 0, 0, 0); __builtin_amdgcn_s_setprio(0); } while (0)
; #define PG8_WAIT_V(n) asm volatile("s_waitcnt vmcnt(" #n ")" ::: "memory")
; #define PG8_WAIT_L(n) asm volatile("s_waitcnt lgkmcnt(" #n ")" ::: "memory")
; template <int NSEG, class Epi, bool ALIGN_EPI = PG8_ALIGN, bool SP2 = PG8_SP2>
; DI void gemm_phase(LAS unsigned char* lds, const Gemm g, const StaticOrder& S, const Epi& E) {
;     ...
;         for (int t = 0; t < nt; t += 2) {
;             const bool last = (t == nt - 2);
;             const char* a1 = cA + (size_t)(t + 1) * kstep;
;             const char* a2 = last ? nA : cA + (size_t)(t + 2) * kstep; const char* b2 = last ? nB : cB + (size_t)(t + 2) * kstep;
;             const char* a3 = a2 + kstep; const char* b3 = b2 + kstep;
;             unsigned v2[2]; v2[0] = (NSEG > 1 && last) ? voffN[0] : voffC[0]; v2[1] = (NSEG > 1 && last) ? voffN[1] : voffC[1];
;             const size_t h2 = (NSEG > 1 && last) ? hstepN : hstepC;
;             if constexpr (SP2) {
;             PG8_LDB(B0, 0, 0); PG8_LDB(B1, 0, 1); PG8_SCHED; PG8_LDA(At, 0, 0); PG8_STAGE(PG8_SA(1, 1), a1 + hstepC, voffC);
;             PG8_WAIT_V(8); PG8_WAIT_L(0); PG8_BAR; PG8_MMA(0, 0, At, B0); PG8_MMA(0, 1, At, B1); PG8_BAR; PG8_SCHED;
;             PG8_LDA(At, 0, 1); PG8_STAGE(PG8_SB(0, 0), b2, v2); PG8_STAGE(PG8_SB(0, 1), b2 + h2, v2); PG8_STAGE(PG8_SA(0, 0), a2, v2);
.LBB0_599:
	ds_read_b128 v[146:149], v143
	ds_read_b128 v[150:153], v143 offset:1024
	ds_read_b128 v[154:157], v143 offset:2048
	ds_read_b128 v[158:161], v143 offset:3072
	ds_read_b128 v[162:165], v144
	ds_read_b128 v[166:169], v144 offset:1024
	ds_read_b128 v[170:173], v144 offset:2048
	ds_read_b128 v[174:177], v144 offset:3072
	s_add_u32 s34, s26, 0xffea0080
	s_addc_u32 s35, s27, -1
	s_cmpk_eq_i32 s64, 0x54
	s_cselect_b32 s37, s23, s35
	s_cselect_b32 s36, s22, s34
	s_cselect_b32 s35, s25, s63
	s_cselect_b32 s34, s24, s62
	v_lshl_add_u64 v[210:211], s[26:27], 0, v[134:135]
	s_add_i32 m0, s45, 0xc000
	ds_read_b128 v[178:181], v145
	ds_read_b128 v[182:185], v145 offset:1024
	ds_read_b128 v[186:189], v145 offset:2048
	ds_read_b128 v[190:193], v145 offset:3072
	ds_read_b128 v[194:197], v145 offset:4096
	ds_read_b128 v[198:201], v145 offset:5120
	ds_read_b128 v[202:205], v145 offset:6144
	ds_read_b128 v[206:209], v145 offset:7168
	global_load_lds_dwordx4 v[210:211], off
	v_lshl_add_u64 v[210:211], s[26:27], 0, v[136:137]
	s_add_i32 m0, s45, 0xe000
	s_nop 0
	global_load_lds_dwordx4 v[210:211], off
	s_waitcnt vmcnt(8)
	s_waitcnt lgkmcnt(0)
	s_setprio 1
	s_barrier
	v_mfma_f32_16x16x32_bf16 v[126:129], v[146:149], v[178:181], v[126:129]
	v_mfma_f32_16x16x32_bf16 v[122:125], v[154:157], v[178:181], v[122:125]
	v_mfma_f32_16x16x32_bf16 v[118:121], v[146:149], v[186:189], v[118:121]
	v_mfma_f32_16x16x32_bf16 v[114:117], v[154:157], v[186:189], v[114:117]
	v_mfma_f32_16x16x32_bf16 v[102:105], v[146:149], v[194:197], v[102:105]
	v_mfma_f32_16x16x32_bf16 v[98:101], v[154:157], v[194:197], v[98:101]
	v_mfma_f32_16x16x32_bf16 v[86:89], v[146:149], v[202:205], v[86:89]
	v_mfma_f32_16x16x32_bf16 v[82:85], v[154:157], v[202:205], v[82:85]
	v_mfma_f32_16x16x32_bf16 v[126:129], v[150:153], v[182:185], v[126:129]
	v_mfma_f32_16x16x32_bf16 v[122:125], v[158:161], v[182:185], v[122:125]
	v_mfma_f32_16x16x32_bf16 v[118:121], v[150:153], v[190:193], v[118:121]
	v_mfma_f32_16x16x32_bf16 v[114:117], v[158:161], v[190:193], v[114:117]
	v_mfma_f32_16x16x32_bf16 v[102:105], v[150:153], v[198:201], v[102:105]
	v_mfma_f32_16x16x32_bf16 v[98:101], v[158:161], v[198:201], v[98:101]
	v_mfma_f32_16x16x32_bf16 v[86:89], v[150:153], v[206:209], v[86:89]
	v_mfma_f32_16x16x32_bf16 v[82:85], v[158:161], v[206:209], v[82:85]
	s_setprio 0
	s_setprio 1
	v_mfma_f32_16x16x32_bf16 v[110:113], v[162:165], v[178:181], v[110:113]
	v_mfma_f32_16x16x32_bf16 v[106:109], v[170:173], v[178:181], v[106:109]
	v_mfma_f32_16x16x32_bf16 v[94:97], v[162:165], v[186:189], v[94:97]
	v_mfma_f32_16x16x32_bf16 v[90:93], v[170:173], v[186:189], v[90:93]
	v_mfma_f32_16x16x32_bf16 v[78:81], v[162:165], v[194:197], v[78:81]
	v_mfma_f32_16x16x32_bf16 v[74:77], v[170:173], v[194:197], v[74:77]
	v_mfma_f32_16x16x32_bf16 v[70:73], v[162:165], v[202:205], v[70:73]
	v_mfma_f32_16x16x32_bf16 v[66:69], v[170:173], v[202:205], v[66:69]
	v_mfma_f32_16x16x32_bf16 v[110:113], v[166:169], v[182:185], v[110:113]
	v_mfma_f32_16x16x32_bf16 v[106:109], v[174:177], v[182:185], v[106:109]
	v_mfma_f32_16x16x32_bf16 v[94:97], v[166:169], v[190:193], v[94:97]
	v_mfma_f32_16x16x32_bf16 v[90:93], v[174:177], v[190:193], v[90:93]
	v_mfma_f32_16x16x32_bf16 v[78:81], v[166:169], v[198:201], v[78:81]
	v_mfma_f32_16x16x32_bf16 v[74:77], v[174:177], v[198:201], v[74:77]
	v_mfma_f32_16x16x32_bf16 v[70:73], v[166:169], v[206:209], v[70:73]
	v_mfma_f32_16x16x32_bf16 v[66:69], v[174:177], v[206:209], v[66:69]
	s_setprio 0
	s_barrier
	s_add_i32 s65, s52, s44
	v_lshl_add_u64 v[210:211], s[34:35], 0, v[130:131]
	s_mov_b32 m0, s65
	ds_read_b128 v[178:181], v145 offset:16384
	ds_read_b128 v[182:185], v145 offset:17408
	ds_read_b128 v[186:189], v145 offset:18432
	ds_read_b128 v[190:193], v145 offset:19456
	ds_read_b128 v[194:197], v145 offset:20480
	ds_read_b128 v[198:201], v145 offset:21504
	ds_read_b128 v[202:205], v145 offset:22528
	ds_read_b128 v[206:209], v145 offset:23552
	global_load_lds_dwordx4 v[210:211], off
	s_add_i32 m0, s65, 0x2000
	s_add_u32 s66, s34, 0x160000
	v_lshl_add_u64 v[212:213], s[34:35], 0, v[132:133]
	s_addc_u32 s67, s35, 0
	s_add_i32 s65, s53, s44
	global_load_lds_dwordx4 v[212:213], off
	v_lshl_add_u64 v[214:215], s[66:67], 0, v[130:131]
	s_mov_b32 m0, s65
	v_lshl_add_u64 v[216:217], s[36:37], 0, v[132:133]
	global_load_lds_dwordx4 v[214:215], off
	v_lshl_add_u64 v[214:215], s[66:67], 0, v[132:133]
	s_add_i32 m0, s65, 0x2000
	s_nop 0
	global_load_lds_dwordx4 v[214:215], off
	v_lshl_add_u64 v[214:215], s[36:37], 0, v[130:131]
	s_mov_b32 m0, s45
	s_nop 0
	global_load_lds_dwordx4 v[214:215], off
	s_mov_b32 m0, s46
	s_nop 0
	global_load_lds_dwordx4 v[216:217], off
	s_waitcnt vmcnt(8)
	s_waitcnt lgkmcnt(0)
	s_setprio 1
	s_barrier
; #define PG8_STAGE(bufoff, gbase, VO) do { _Pragma("unroll") for (int _i = 0; _i < 2; ++_i) \
;         __builtin_amdgcn_global_load_lds((const unsigned*)((const char*)(gbase) + VO[_i]), (LAS unsigned*)(lds + (bufoff) + ldsw + _i * 8192), 16, 0, 0); } while (0)
; #define PG8_LDA(dst, b, h) do { _Pragma("unroll") for (int m = 0; m < 4; ++m) _Pragma("unroll") for (int k = 0; k < 2; ++k) dst[m][k] = *(const LAS bf16x8*)(lds + PG8_SA(b, h) + aoff + m * 2048 + k * 1024); } while (0)
; #define PG8_LDB(dst, b, h) do { _Pragma("unroll") for (int n = 0; n < 2; ++n) _Pragma("unroll") for (int k = 0; k < 2; ++k) dst[n][k] = *(const LAS bf16x8*)(lds + PG8_SB(b, h) + boff + n * 2048 + k * 1024); } while (0)
; #define PG8_MMA(ai, bj, At, Bt) do { __builtin_amdgcn_s_setprio(1); _Pragma("unroll") for (int m = 0; m < 4; ++m) _Pragma("unroll") for (int n = 0; n < 2; ++n) _Pragma("unroll") for (int k = 0; k < 2; ++k) \
;         acc[ai][bj][m][n] = __builtin_amdgcn_mfma_f32_16x16x32_bf16(Bt[n][k], At[m][k], acc[ai][bj][m][n], 0, 0, 0); __builtin_amdgcn_s_setprio(0); } while (0)
; #define PG8_WAIT_V(n) asm volatile("s_waitcnt vmcnt(" #n ")" ::: "memory")
; #define PG8_WAIT_L(n) asm volatile("s_waitcnt lgkmcnt(" #n ")" ::: "memory")
; #define PG8_BAR __builtin_amdgcn_s_barrier()
; #define PG8_SCHED __builtin_amdgcn_sched_barrier(0)
; template <int NSEG, class Epi, bool ALIGN_EPI = PG8_ALIGN, bool SP2 = PG8_SP2>
; DI void gemm_phase(LAS unsigned char* lds, const Gemm g, const StaticOrder& S, const Epi& E) {
;     ...
;             PG8_LDA(At, 0, 1); PG8_STAGE(PG8_SB(0, 0), b2, v2); PG8_STAGE(PG8_SB(0, 1), b2 + h2, v2); PG8_STAGE(PG8_SA(0, 0), a2, v2);
;             PG8_WAIT_V(8); PG8_WAIT_L(0); PG8_BAR; PG8_MMA(1, 0, At, B0); PG8_MMA(1, 1, At, B1); PG8_BAR; PG8_SCHED;
;             PG8_LDB(B0, 1, 0); PG8_LDB(B1, 1, 1); PG8_SCHED; PG8_LDA(At, 1, 0); PG8_STAGE(PG8_SA(0, 1), a2 + h2, v2);
;             PG8_WAIT_V(8); PG8_WAIT_L(0); PG8_BAR; PG8_MMA(0, 0, At, B0); PG8_MMA(0, 1, At, B1); PG8_BAR; PG8_SCHED;
	v_mfma_f32_16x16x32_bf16 v[54:57], v[146:149], v[178:181], v[54:57]
	v_mfma_f32_16x16x32_bf16 v[46:49], v[154:157], v[178:181], v[46:49]
	v_mfma_f32_16x16x32_bf16 v[38:41], v[146:149], v[186:189], v[38:41]
	v_mfma_f32_16x16x32_bf16 v[34:37], v[154:157], v[186:189], v[34:37]
	v_mfma_f32_16x16x32_bf16 v[22:25], v[146:149], v[194:197], v[22:25]
	v_mfma_f32_16x16x32_bf16 v[18:21], v[154:157], v[194:197], v[18:21]
	v_mfma_f32_16x16x32_bf16 v[6:9], v[146:149], v[202:205], v[6:9]
	v_mfma_f32_16x16x32_bf16 v[2:5], v[154:157], v[202:205], v[2:5]
	v_mfma_f32_16x16x32_bf16 v[54:57], v[150:153], v[182:185], v[54:57]
	v_mfma_f32_16x16x32_bf16 v[46:49], v[158:161], v[182:185], v[46:49]
	v_mfma_f32_16x16x32_bf16 v[38:41], v[150:153], v[190:193], v[38:41]
	v_mfma_f32_16x16x32_bf16 v[34:37], v[158:161], v[190:193], v[34:37]
	v_mfma_f32_16x16x32_bf16 v[22:25], v[150:153], v[198:201], v[22:25]
	v_mfma_f32_16x16x32_bf16 v[18:21], v[158:161], v[198:201], v[18:21]
	v_mfma_f32_16x16x32_bf16 v[6:9], v[150:153], v[206:209], v[6:9]
	v_mfma_f32_16x16x32_bf16 v[2:5], v[158:161], v[206:209], v[2:5]
	s_setprio 0
	s_setprio 1
	v_mfma_f32_16x16x32_bf16 v[30:33], v[162:165], v[178:181], v[30:33]
	v_mfma_f32_16x16x32_bf16 v[26:29], v[170:173], v[178:181], v[26:29]
	v_mfma_f32_16x16x32_bf16 v[14:17], v[162:165], v[186:189], v[14:17]
	v_mfma_f32_16x16x32_bf16 v[10:13], v[170:173], v[186:189], v[10:13]
	v_mfma_f32_16x16x32_bf16 v[58:61], v[162:165], v[194:197], v[58:61]
	v_mfma_f32_16x16x32_bf16 v[62:65], v[170:173], v[194:197], v[62:65]
	v_mfma_f32_16x16x32_bf16 v[42:45], v[162:165], v[202:205], v[42:45]
	v_mfma_f32_16x16x32_bf16 v[50:53], v[170:173], v[202:205], v[50:53]
	v_mfma_f32_16x16x32_bf16 v[30:33], v[166:169], v[182:185], v[30:33]
	v_mfma_f32_16x16x32_bf16 v[26:29], v[174:177], v[182:185], v[26:29]
	v_mfma_f32_16x16x32_bf16 v[14:17], v[166:169], v[190:193], v[14:17]
	v_mfma_f32_16x16x32_bf16 v[10:13], v[174:177], v[190:193], v[10:13]
	v_mfma_f32_16x16x32_bf16 v[58:61], v[166:169], v[198:201], v[58:61]
	v_mfma_f32_16x16x32_bf16 v[62:65], v[174:177], v[198:201], v[62:65]
	v_mfma_f32_16x16x32_bf16 v[42:45], v[166:169], v[206:209], v[42:45]
	v_mfma_f32_16x16x32_bf16 v[50:53], v[174:177], v[206:209], v[50:53]
	s_setprio 0
	s_barrier
	s_add_i32 s65, 0, 0x18000
	s_add_i32 s66, 0, 0x1c000
	v_add_u32_e32 v158, s65, v141
	v_add_u32_e32 v174, s66, v141
	ds_read_b128 v[146:149], v158
	ds_read_b128 v[150:153], v158 offset:1024
	ds_read_b128 v[154:157], v158 offset:2048
	ds_read_b128 v[158:161], v158 offset:3072
	ds_read_b128 v[162:165], v174
	ds_read_b128 v[166:169], v174 offset:1024
	ds_read_b128 v[170:173], v174 offset:2048
	ds_read_b128 v[174:177], v174 offset:3072
	s_add_u32 s36, s36, 0x160000
	s_addc_u32 s37, s37, 0
	s_mov_b32 m0, s47
	v_lshl_add_u64 v[218:219], s[36:37], 0, v[130:131]
	ds_read_b128 v[178:181], v145 offset:32768
	ds_read_b128 v[182:185], v145 offset:33792
	ds_read_b128 v[186:189], v145 offset:34816
	ds_read_b128 v[190:193], v145 offset:35840
	ds_read_b128 v[194:197], v145 offset:36864
	ds_read_b128 v[198:201], v145 offset:37888
	ds_read_b128 v[202:205], v145 offset:38912
	ds_read_b128 v[206:209], v145 offset:39936
	global_load_lds_dwordx4 v[218:219], off
	v_lshl_add_u64 v[218:219], s[36:37], 0, v[132:133]
	s_mov_b32 m0, s48
	s_nop 0
	global_load_lds_dwordx4 v[218:219], off
	s_waitcnt vmcnt(8)
	s_waitcnt lgkmcnt(0)
	s_setprio 1
	s_barrier
	v_mfma_f32_16x16x32_bf16 v[126:129], v[146:149], v[178:181], v[126:129]
	v_mfma_f32_16x16x32_bf16 v[122:125], v[154:157], v[178:181], v[122:125]
	v_mfma_f32_16x16x32_bf16 v[118:121], v[146:149], v[186:189], v[118:121]
	v_mfma_f32_16x16x32_bf16 v[114:117], v[154:157], v[186:189], v[114:117]
	v_mfma_f32_16x16x32_bf16 v[102:105], v[146:149], v[194:197], v[102:105]
	v_mfma_f32_16x16x32_bf16 v[98:101], v[154:157], v[194:197], v[98:101]
	v_mfma_f32_16x16x32_bf16 v[86:89], v[146:149], v[202:205], v[86:89]
	v_mfma_f32_16x16x32_bf16 v[82:85], v[154:157], v[202:205], v[82:85]
	v_mfma_f32_16x16x32_bf16 v[126:129], v[150:153], v[182:185], v[126:129]
	v_mfma_f32_16x16x32_bf16 v[122:125], v[158:161], v[182:185], v[122:125]
	v_mfma_f32_16x16x32_bf16 v[118:121], v[150:153], v[190:193], v[118:121]
	v_mfma_f32_16x16x32_bf16 v[114:117], v[158:161], v[190:193], v[114:117]
	v_mfma_f32_16x16x32_bf16 v[102:105], v[150:153], v[198:201], v[102:105]
	v_mfma_f32_16x16x32_bf16 v[98:101], v[158:161], v[198:201], v[98:101]
	v_mfma_f32_16x16x32_bf16 v[86:89], v[150:153], v[206:209], v[86:89]
	v_mfma_f32_16x16x32_bf16 v[82:85], v[158:161], v[206:209], v[82:85]
	s_setprio 0
	s_setprio 1
	v_mfma_f32_16x16x32_bf16 v[110:113], v[162:165], v[178:181], v[110:113]
	v_mfma_f32_16x16x32_bf16 v[106:109], v[170:173], v[178:181], v[106:109]
	v_mfma_f32_16x16x32_bf16 v[94:97], v[162:165], v[186:189], v[94:97]
	v_mfma_f32_16x16x32_bf16 v[90:93], v[170:173], v[186:189], v[90:93]
	v_mfma_f32_16x16x32_bf16 v[78:81], v[162:165], v[194:197], v[78:81]
	v_mfma_f32_16x16x32_bf16 v[74:77], v[170:173], v[194:197], v[74:77]
	v_mfma_f32_16x16x32_bf16 v[70:73], v[162:165], v[202:205], v[70:73]
	v_mfma_f32_16x16x32_bf16 v[66:69], v[170:173], v[202:205], v[66:69]
	v_mfma_f32_16x16x32_bf16 v[110:113], v[166:169], v[182:185], v[110:113]
	v_mfma_f32_16x16x32_bf16 v[106:109], v[174:177], v[182:185], v[106:109]
	v_mfma_f32_16x16x32_bf16 v[94:97], v[166:169], v[190:193], v[94:97]
	v_mfma_f32_16x16x32_bf16 v[90:93], v[174:177], v[190:193], v[90:93]
	v_mfma_f32_16x16x32_bf16 v[78:81], v[166:169], v[198:201], v[78:81]
	v_mfma_f32_16x16x32_bf16 v[74:77], v[174:177], v[198:201], v[74:77]
	v_mfma_f32_16x16x32_bf16 v[70:73], v[166:169], v[206:209], v[70:73]
	v_mfma_f32_16x16x32_bf16 v[66:69], v[174:177], v[206:209], v[66:69]
	s_setprio 0
	s_barrier
; #define PG8_STAGE(bufoff, gbase, VO) do { _Pragma("unroll") for (int _i = 0; _i < 2; ++_i) \
;         __builtin_amdgcn_global_load_lds((const unsigned*)((const char*)(gbase) + VO[_i]), (LAS unsigned*)(lds + (bufoff) + ldsw + _i * 8192), 16, 0, 0); } while (0)
; #define PG8_LDA(dst, b, h) do { _Pragma("unroll") for (int m = 0; m < 4; ++m) _Pragma("unroll") for (int k = 0; k < 2; ++k) dst[m][k] = *(const LAS bf16x8*)(lds + PG8_SA(b, h) + aoff + m * 2048 + k * 1024); } while (0)
; #define PG8_MMA(ai, bj, At, Bt) do { __builtin_amdgcn_s_setprio(1); _Pragma("unroll") for (int m = 0; m < 4; ++m) _Pragma("unroll") for (int n = 0; n < 2; ++n) _Pragma("unroll") for (int k = 0; k < 2; ++k) \
;         acc[ai][bj][m][n] = __builtin_amdgcn_mfma_f32_16x16x32_bf16(Bt[n][k], At[m][k], acc[ai][bj][m][n], 0, 0, 0); __builtin_amdgcn_s_setprio(0); } while (0)
; #define PG8_WAIT_V(n) asm volatile("s_waitcnt vmcnt(" #n ")" ::: "memory")
; #define PG8_WAIT_L(n) asm volatile("s_waitcnt lgkmcnt(" #n ")" ::: "memory")
; #define PG8_BAR __builtin_amdgcn_s_barrier()
; #define PG8_SCHED __builtin_amdgcn_sched_barrier(0)
; template <int NSEG, class Epi, bool ALIGN_EPI = PG8_ALIGN, bool SP2 = PG8_SP2>
; DI void gemm_phase(LAS unsigned char* lds, const Gemm g, const StaticOrder& S, const Epi& E) {
;     ...
;             PG8_LDA(At, 1, 1); PG8_STAGE(PG8_SB(1, 0), b3, v2); PG8_STAGE(PG8_SB(1, 1), b3 + h2, v2); PG8_STAGE(PG8_SA(1, 0), a3, v2);
;             PG8_WAIT_V(8); PG8_WAIT_L(0); PG8_BAR; PG8_MMA(1, 0, At, B0); PG8_MMA(1, 1, At, B1); PG8_BAR; PG8_SCHED;
	s_add_i32 s36, s65, s44
	v_lshl_add_u64 v[210:211], v[210:211], 0, s[10:11]
	s_mov_b32 m0, s36
	ds_read_b128 v[178:181], v145 offset:49152
	ds_read_b128 v[182:185], v145 offset:50176
	ds_read_b128 v[186:189], v145 offset:51200
	ds_read_b128 v[190:193], v145 offset:52224
	ds_read_b128 v[194:197], v145 offset:53248
	ds_read_b128 v[198:201], v145 offset:54272
	ds_read_b128 v[202:205], v145 offset:55296
	ds_read_b128 v[206:209], v145 offset:56320
	global_load_lds_dwordx4 v[210:211], off
	s_add_i32 m0, s36, 0x2000
	s_add_u32 s34, s34, 0x160080
	v_lshl_add_u64 v[210:211], v[212:213], 0, s[10:11]
	s_addc_u32 s35, s35, 0
	s_add_i32 s36, s66, s44
	global_load_lds_dwordx4 v[210:211], off
	v_lshl_add_u64 v[210:211], s[34:35], 0, v[130:131]
	s_mov_b32 m0, s36
	s_nop 0
	global_load_lds_dwordx4 v[210:211], off
	v_lshl_add_u64 v[210:211], s[34:35], 0, v[132:133]
	s_add_i32 m0, s36, 0x2000
	s_nop 0
	global_load_lds_dwordx4 v[210:211], off
	v_lshl_add_u64 v[210:211], v[214:215], 0, s[10:11]
	s_mov_b32 m0, s49
	s_nop 0
	global_load_lds_dwordx4 v[210:211], off
	v_lshl_add_u64 v[210:211], v[216:217], 0, s[10:11]
	s_mov_b32 m0, s50
	s_nop 0
	global_load_lds_dwordx4 v[210:211], off
	s_waitcnt vmcnt(8)
	s_waitcnt lgkmcnt(0)
	s_setprio 1
	s_barrier
	v_mfma_f32_16x16x32_bf16 v[54:57], v[146:149], v[178:181], v[54:57]
	v_mfma_f32_16x16x32_bf16 v[46:49], v[154:157], v[178:181], v[46:49]
	v_mfma_f32_16x16x32_bf16 v[38:41], v[146:149], v[186:189], v[38:41]
	v_mfma_f32_16x16x32_bf16 v[34:37], v[154:157], v[186:189], v[34:37]
	v_mfma_f32_16x16x32_bf16 v[22:25], v[146:149], v[194:197], v[22:25]
	v_mfma_f32_16x16x32_bf16 v[18:21], v[154:157], v[194:197], v[18:21]
	v_mfma_f32_16x16x32_bf16 v[6:9], v[146:149], v[202:205], v[6:9]
	v_mfma_f32_16x16x32_bf16 v[2:5], v[154:157], v[202:205], v[2:5]
	v_mfma_f32_16x16x32_bf16 v[54:57], v[150:153], v[182:185], v[54:57]
	v_mfma_f32_16x16x32_bf16 v[46:49], v[158:161], v[182:185], v[46:49]
	v_mfma_f32_16x16x32_bf16 v[38:41], v[150:153], v[190:193], v[38:41]
	v_mfma_f32_16x16x32_bf16 v[34:37], v[158:161], v[190:193], v[34:37]
	v_mfma_f32_16x16x32_bf16 v[22:25], v[150:153], v[198:201], v[22:25]
	v_mfma_f32_16x16x32_bf16 v[18:21], v[158:161], v[198:201], v[18:21]
	v_mfma_f32_16x16x32_bf16 v[6:9], v[150:153], v[206:209], v[6:9]
	v_mfma_f32_16x16x32_bf16 v[2:5], v[158:161], v[206:209], v[2:5]
	s_setprio 0
	s_setprio 1
	v_mfma_f32_16x16x32_bf16 v[30:33], v[162:165], v[178:181], v[30:33]
	v_mfma_f32_16x16x32_bf16 v[26:29], v[170:173], v[178:181], v[26:29]
	v_mfma_f32_16x16x32_bf16 v[14:17], v[162:165], v[186:189], v[14:17]
	v_mfma_f32_16x16x32_bf16 v[10:13], v[170:173], v[186:189], v[10:13]
	v_mfma_f32_16x16x32_bf16 v[58:61], v[162:165], v[194:197], v[58:61]
	v_mfma_f32_16x16x32_bf16 v[62:65], v[170:173], v[194:197], v[62:65]
	v_mfma_f32_16x16x32_bf16 v[42:45], v[162:165], v[202:205], v[42:45]
	v_mfma_f32_16x16x32_bf16 v[50:53], v[170:173], v[202:205], v[50:53]
	v_mfma_f32_16x16x32_bf16 v[30:33], v[166:169], v[182:185], v[30:33]
	v_mfma_f32_16x16x32_bf16 v[26:29], v[174:177], v[182:185], v[26:29]
	v_mfma_f32_16x16x32_bf16 v[14:17], v[166:169], v[190:193], v[14:17]
	v_mfma_f32_16x16x32_bf16 v[10:13], v[174:177], v[190:193], v[10:13]
	v_mfma_f32_16x16x32_bf16 v[58:61], v[166:169], v[198:201], v[58:61]
	v_mfma_f32_16x16x32_bf16 v[62:65], v[174:177], v[198:201], v[62:65]
	v_mfma_f32_16x16x32_bf16 v[42:45], v[166:169], v[206:209], v[42:45]
	v_mfma_f32_16x16x32_bf16 v[50:53], v[174:177], v[206:209], v[50:53]
	s_setprio 0
	s_barrier
	s_add_i32 s64, s64, 2
	s_add_u32 s26, s26, 0x100
	s_addc_u32 s27, s27, 0
	s_add_u32 s62, s62, 0x100
	s_addc_u32 s63, s63, 0
	s_cmpk_gt_u32 s64, 0x55
	s_cbranch_scc0 .LBB0_599
	s_and_b64 vcc, exec, s[12:13]
	s_cbranch_vccz .LBB0_602
	s_barrier
